# mixer: rpb table once per phase, first-pass Q fragment loads issued before the ctx staging, ctx pooling runs dealt one per workgroup
# speedup vs baseline: 1.0351x; 1.0081x over previous
; #define LAS __attribute__((address_space(3)))
; __device__ __forceinline__ int kswz(int key) { return ((key >> 1) & 1) | (((key >> 3) & 3) << 1); }
; __device__ __forceinline__ void phase_mixer(const Params& p, LAS unsigned char* lds, int l, bool with_ctx, int G, int tid, int wave, int lane, int rep_attn, int rep_pool) {
;     ...
;         const int x = I & 7, t = I >> 3, j = t & 31, rho = t >> 5, pr = rho * 8 + x, b = pr >> 3, h = pr & 7;
;         const int r0 = 2 * j, rs0 = min(max(r0 - 4, 0), 56);
;         const int r = r0 + (wave >> 2), n = wave & 3, rs = min(max(r - 4, 0), 56), kc0 = min(max(16 * n - 8, 0), 32);
;         const int qc = 16 * n + qi, qs = min(max(qc - 8, 0), 48);
;         const int sel = (j - 2 * rho) & 31;
;         const int npass = (with_ctx && sel < 2) ? 2 : 1;
;         {
;             u32x4 kreg[4], vreg[4];
;             const bf16_t* ksrc = PB + (size_t)(ML + b * CT + (tid >> 3)) * PBW + 1024 + h * 64 + (tid & 7) * 8;
;             const bf16_t* vsrc = VT + (size_t)(h * 64 + (tid >> 5)) * VTP + ML + b * CT + (tid & 31) * 8;
; #pragma unroll
;             for (int ps = 0; ps < 4; ++ps) { kreg[ps] = *(const u32x4*)(ksrc + (size_t)(ps * 64) * PBW); vreg[ps] = *(const u32x4*)(vsrc + (size_t)(ps * 16) * VTP); }
;             __builtin_amdgcn_sched_barrier(0);
; #pragma unroll
;             for (int ps = 0; ps < 4; ++ps) { const int key = ps * 64 + (tid >> 3), d = ps * 16 + (tid >> 5);
;                 *(LAS u32x4*)(lds + AT_KC + key * 128 + ((((tid & 7) ^ kswz(key))) << 4)) = kreg[ps];
;                 *(LAS u32x4*)(lds + AT_VC + d * 512 + ((((tid & 31) ^ (d & 15))) << 4)) = vreg[ps]; }
;         }
;         __syncthreads();
;         float mxA = -INFINITY, lA = 0.f; f32x4 oA[4]; bf16x8 qA0, qA1;
;         {
;             const int kl = kap, ka0 = AT_KC + kl * 128 + ((g ^ kswz(kl)) << 4), ka1 = AT_KC + kl * 128 + (((g + 4) ^ kswz(kl)) << 4);
;             const int vrow = AT_VC + qi * 512;
; #pragma unroll 1
;             for (int ps = 2 - npass; ps < 2; ++ps) {
;                 const int qtok = (ps == 1) ? (b * SEQ + r * 64 + 16 * n + qi) : (ML + b * CT + 16 * (sel * 8 + wave) + qi);
;                 const bf16_t* qp = PB + (size_t)qtok * PBW + 512 + h * 64 + 8 * g;
;                 qA0 = *(const bf16x8*)qp; qA1 = *(const bf16x8*)(qp + 32);
.LBB0_297:
	s_ashr_i32 s62, s61, 8
	s_lshr_b32 s63, s61, 2
	s_lshr_b32 s30, s61, 3
	s_and_b32 s71, s63, 62
	s_lshl_b32 s68, s62, 1
	s_add_i32 s63, s71, s24
	s_sub_i32 s30, s30, s68
	s_and_b32 s65, s61, 7
	s_max_i32 s64, s63, 4
	s_and_b32 s80, s30, 31
	s_cmp_lt_u32 s80, 2
	s_cselect_b64 s[68:69], -1, 0
	s_and_b32 s74, s61, 0xffffff00
	s_add_i32 s81, s74, 0x8000
	v_add_u32_e32 v2, s81, v109
	v_mov_b64_e32 v[0:1], s[0:1]
	v_mad_i64_i32 v[0:1], s[76:77], v2, s58, v[0:1]
	s_lshl_b32 s30, s65, 7
	s_lshl_b32 s70, s65, 6
	v_lshl_add_u64 v[0:1], v[0:1], 0, s[30:31]
	v_lshl_add_u64 v[24:25], v[0:1], 0, v[156:157]
	v_add_u32_e32 v2, s70, v110
	v_mov_b64_e32 v[0:1], s[28:29]
	s_mov_b32 s75, 0x11100
	v_mad_i64_i32 v[0:1], s[76:77], v2, s75, v[0:1]
	s_ashr_i32 s75, s74, 31
	v_lshl_add_u64 v[0:1], s[74:75], 1, v[0:1]
	v_mov_b32_e32 v97, v157
	v_lshl_add_u64 v[26:27], v[0:1], 0, v[96:97]
	s_mov_b32 s74, 0x10000
	v_add_co_u32_e32 v4, vcc, s74, v26
	s_mov_b32 s74, 0x30000
	s_nop 0
	v_addc_co_u32_e32 v5, vcc, 0, v27, vcc
	v_add_co_u32_e32 v8, vcc, s74, v24
	s_mov_b32 s74, 0x121000
	s_nop 0
	v_addc_co_u32_e32 v9, vcc, 0, v25, vcc
	v_add_co_u32_e32 v12, vcc, s74, v26
	s_mov_b32 s74, 0x60000
	s_nop 0
	v_addc_co_u32_e32 v13, vcc, 0, v27, vcc
	v_add_co_u32_e32 v16, vcc, s74, v24
	s_mov_b32 s74, 0x232000
	s_nop 0
	v_addc_co_u32_e32 v17, vcc, 0, v25, vcc
	v_add_co_u32_e32 v20, vcc, s74, v26
	s_mov_b32 s74, 0x90000
	s_nop 0
	v_addc_co_u32_e32 v21, vcc, 0, v27, vcc
	global_load_dwordx4 v[0:3], v[24:25], off offset:2048
	s_nop 0
	global_load_dwordx4 v[4:7], v[4:5], off
	v_add_co_u32_e32 v24, vcc, s74, v24
	s_mov_b32 s74, 0x343000
	s_nop 0
	v_addc_co_u32_e32 v25, vcc, 0, v25, vcc
	v_add_co_u32_e32 v28, vcc, s74, v26
	global_load_dwordx4 v[8:11], v[8:9], off offset:2048
	s_nop 0
	global_load_dwordx4 v[12:15], v[12:13], off
	v_addc_co_u32_e32 v29, vcc, 0, v27, vcc
	global_load_dwordx4 v[16:19], v[16:17], off offset:2048
	s_nop 0
	global_load_dwordx4 v[20:23], v[20:21], off
	s_nop 0
	global_load_dwordx4 v[24:27], v[24:25], off offset:2048
	s_nop 0
	global_load_dwordx4 v[28:31], v[28:29], off
	s_lshl_b32 s76, s62, 12
	s_lshl_b32 s62, s63, 6
	s_and_b64 s[74:75], s[36:37], s[68:69]
	s_lshl_b32 s68, s80, 7
	s_add_i32 s77, s81, s25
	s_add_i32 s62, s62, s76
	s_add_i32 s77, s77, s68
	s_or_b32 s80, s62, s33
	v_lshl_add_u64 v[100:101], v[92:93], 0, s[30:31]
	v_lshl_add_u64 v[102:103], v[94:95], 0, s[30:31]
	s_and_b64 s[68:69], s[74:75], exec
	s_cselect_b32 s32, s77, s80
	v_or_b32_e32 v235, s32, v107
	v_mad_i64_i32 v[236:237], s[68:69], v235, s58, v[100:101]
	global_load_dwordx4 v[240:243], v[236:237], off offset:1024
	s_nop 0
	global_load_dwordx4 v[236:239], v[236:237], off offset:1088
	s_waitcnt vmcnt(9)
	ds_write_b128 v111, v[0:3]
	s_waitcnt vmcnt(8)
	ds_write_b128 v131, v[4:7] offset:32768
	s_waitcnt vmcnt(7)
	ds_write_b128 v111, v[8:11] offset:8192
	s_waitcnt vmcnt(6)
	ds_write_b128 v131, v[12:15] offset:40960
	s_waitcnt vmcnt(5)
	ds_write_b128 v111, v[16:19] offset:16384
	s_waitcnt vmcnt(4)
	ds_write_b128 v131, v[20:23] offset:49152
	s_waitcnt vmcnt(3)
	ds_write_b128 v111, v[24:27] offset:24576
	s_waitcnt vmcnt(2)
	ds_write_b128 v131, v[28:31] offset:57344
	s_waitcnt lgkmcnt(0)
	s_barrier
	s_and_b64 s[68:69], s[74:75], exec
	s_cselect_b32 s30, s77, s80
	v_or_b32_e32 v104, s30, v107
	s_waitcnt vmcnt(0)
	v_mov_b32_e32 v4, v240
	v_mov_b32_e32 v5, v241
	v_mov_b32_e32 v6, v242
	v_mov_b32_e32 v7, v243
	v_mov_b32_e32 v0, v236
	v_mov_b32_e32 v1, v237
	v_mov_b32_e32 v2, v238
	v_mov_b32_e32 v3, v239
	s_branch .Lqjoin_299

; #define AH_LDK(c, bufi) do { kf[bufi][0] = *(const LAS bf16x8*)(lds + kaddr0 + (c) * kcs); kf[bufi][1] = *(const LAS bf16x8*)(lds + kaddr1 + (c) * kcs); \
;         kf[bufi][2] = *(const LAS bf16x8*)(lds + kaddr0 + (c) * kcs + 512); kf[bufi][3] = *(const LAS bf16x8*)(lds + kaddr1 + (c) * kcs + 512); } while (0)
; template <bool LOC> ...
;     ...
;     AH_LDK(0, 0);
; #pragma unroll
;     for (int c = 0; c < 8; ++c) {
;         if (c < 7) AH_LDK(c + 1, (c + 1) & 1);
;         __builtin_amdgcn_sched_barrier(0);
;         f32x4 t0 = (f32x4){0.f, 0.f, 0.f, 0.f}, t1 = (f32x4){0.f, 0.f, 0.f, 0.f};
;         t0 = __builtin_amdgcn_mfma_f32_16x16x32_bf16(kf[c & 1][0], q0, t0, 0, 0, 0); t1 = __builtin_amdgcn_mfma_f32_16x16x32_bf16(kf[c & 1][2], q0, t1, 0, 0, 0);
;         t0 = __builtin_amdgcn_mfma_f32_16x16x32_bf16(kf[c & 1][1], q1, t0, 0, 0, 0); t1 = __builtin_amdgcn_mfma_f32_16x16x32_bf16(kf[c & 1][3], q1, t1, 0, 0, 0);
; #pragma unroll
;         for (int e = 0; e < 8; ++e) { const float a = (e < 4) ? t0[e] : t1[e - 4];
;             if (LOC) { const float bv = bp[c * RPB_PITCH + e]; const bool ok = (e >= elo) && (e < elo + 16); s[c][e] = ok ? (a * SC + bv) : -INFINITY; }
;             else s[c][e] = a * SC; }
;         __builtin_amdgcn_sched_barrier(0);
;     }
.Lqjoin_299:
	ds_read_b128 v[8:11], v132
	ds_read_b128 v[12:15], v132 offset:512
	ds_read_b128 v[16:19], v133
	ds_read_b128 v[20:23], v133 offset:512
	ds_read_b128 v[24:27], v132 offset:4096
	ds_read_b128 v[28:31], v132 offset:4608
	ds_read_b128 v[32:35], v133 offset:4096
	ds_read_b128 v[36:39], v133 offset:4608
	s_waitcnt vmcnt(1) lgkmcnt(7)
	v_mfma_f32_16x16x32_bf16 v[8:11], v[8:11], v[4:7], 0
	s_waitcnt vmcnt(0) lgkmcnt(5)
	v_mfma_f32_16x16x32_bf16 v[68:71], v[16:19], v[0:3], v[8:11]
	v_mfma_f32_16x16x32_bf16 v[8:11], v[12:15], v[4:7], 0
	s_waitcnt lgkmcnt(4)
	v_mfma_f32_16x16x32_bf16 v[64:67], v[20:23], v[0:3], v[8:11]
	s_nop 4
	v_mul_f32_e32 v97, 0x3e38aa3b, v68
	v_mul_f32_e32 v99, 0x3e38aa3b, v69
	v_mul_f32_e32 v105, 0x3e38aa3b, v70
	v_mul_f32_e32 v151, 0x3e38aa3b, v71
	v_mul_f32_e32 v160, 0x3e38aa3b, v64
	v_mul_f32_e32 v161, 0x3e38aa3b, v65
	v_mul_f32_e32 v167, 0x3e38aa3b, v66
	v_mul_f32_e32 v186, 0x3e38aa3b, v67
	ds_read_b128 v[8:11], v132 offset:8192
	ds_read_b128 v[12:15], v132 offset:8704
	ds_read_b128 v[16:19], v133 offset:8192
	ds_read_b128 v[20:23], v133 offset:8704
	s_waitcnt lgkmcnt(7)
	v_mfma_f32_16x16x32_bf16 v[24:27], v[24:27], v[4:7], 0
	s_waitcnt lgkmcnt(5)
	v_mfma_f32_16x16x32_bf16 v[60:63], v[32:35], v[0:3], v[24:27]
	v_mfma_f32_16x16x32_bf16 v[24:27], v[28:31], v[4:7], 0
	s_waitcnt lgkmcnt(4)
	v_mfma_f32_16x16x32_bf16 v[56:59], v[36:39], v[0:3], v[24:27]
	s_nop 4
	v_mul_f32_e32 v187, 0x3e38aa3b, v60
	v_mul_f32_e32 v188, 0x3e38aa3b, v61
	v_mul_f32_e32 v189, 0x3e38aa3b, v62
	v_mul_f32_e32 v190, 0x3e38aa3b, v63
	v_mul_f32_e32 v191, 0x3e38aa3b, v56
	v_mul_f32_e32 v192, 0x3e38aa3b, v57
	v_mul_f32_e32 v193, 0x3e38aa3b, v58
	v_mul_f32_e32 v194, 0x3e38aa3b, v59
	ds_read_b128 v[24:27], v132 offset:12288
	ds_read_b128 v[28:31], v132 offset:12800
	ds_read_b128 v[32:35], v133 offset:12288
	ds_read_b128 v[36:39], v133 offset:12800
	s_waitcnt lgkmcnt(7)
	v_mfma_f32_16x16x32_bf16 v[8:11], v[8:11], v[4:7], 0
	s_waitcnt lgkmcnt(5)
	v_mfma_f32_16x16x32_bf16 v[52:55], v[16:19], v[0:3], v[8:11]
	v_mfma_f32_16x16x32_bf16 v[8:11], v[12:15], v[4:7], 0
	s_waitcnt lgkmcnt(4)
	v_mfma_f32_16x16x32_bf16 v[48:51], v[20:23], v[0:3], v[8:11]
	s_nop 4
	v_mul_f32_e32 v195, 0x3e38aa3b, v52
	v_mul_f32_e32 v196, 0x3e38aa3b, v53
	v_mul_f32_e32 v197, 0x3e38aa3b, v54
	v_mul_f32_e32 v198, 0x3e38aa3b, v55
	v_mul_f32_e32 v199, 0x3e38aa3b, v48
	v_mul_f32_e32 v200, 0x3e38aa3b, v49
	v_mul_f32_e32 v201, 0x3e38aa3b, v50
	v_mul_f32_e32 v202, 0x3e38aa3b, v51
	ds_read_b128 v[8:11], v132 offset:16384
	ds_read_b128 v[12:15], v132 offset:16896
	ds_read_b128 v[16:19], v133 offset:16384
	ds_read_b128 v[20:23], v133 offset:16896
	s_waitcnt lgkmcnt(7)
	v_mfma_f32_16x16x32_bf16 v[24:27], v[24:27], v[4:7], 0
	s_waitcnt lgkmcnt(5)
	v_mfma_f32_16x16x32_bf16 v[44:47], v[32:35], v[0:3], v[24:27]
	v_mfma_f32_16x16x32_bf16 v[24:27], v[28:31], v[4:7], 0
	s_waitcnt lgkmcnt(4)
	v_mfma_f32_16x16x32_bf16 v[40:43], v[36:39], v[0:3], v[24:27]
	s_nop 4
	v_mul_f32_e32 v203, 0x3e38aa3b, v44
	v_mul_f32_e32 v204, 0x3e38aa3b, v45
	v_mul_f32_e32 v205, 0x3e38aa3b, v46
	v_mul_f32_e32 v206, 0x3e38aa3b, v47
	v_mul_f32_e32 v207, 0x3e38aa3b, v40
	v_mul_f32_e32 v208, 0x3e38aa3b, v41
	v_mul_f32_e32 v209, 0x3e38aa3b, v42
	v_mul_f32_e32 v210, 0x3e38aa3b, v43
	ds_read_b128 v[24:27], v132 offset:20480
	ds_read_b128 v[152:155], v132 offset:20992
	ds_read_b128 v[28:31], v133 offset:20480
	ds_read_b128 v[170:173], v133 offset:20992
	s_waitcnt lgkmcnt(7)
	v_mfma_f32_16x16x32_bf16 v[8:11], v[8:11], v[4:7], 0
	s_waitcnt lgkmcnt(5)
	v_mfma_f32_16x16x32_bf16 v[36:39], v[16:19], v[0:3], v[8:11]
	v_mfma_f32_16x16x32_bf16 v[8:11], v[12:15], v[4:7], 0
	s_waitcnt lgkmcnt(4)
	v_mfma_f32_16x16x32_bf16 v[32:35], v[20:23], v[0:3], v[8:11]
	s_nop 4
	v_mul_f32_e32 v211, 0x3e38aa3b, v36
	v_mul_f32_e32 v212, 0x3e38aa3b, v37
	v_mul_f32_e32 v213, 0x3e38aa3b, v38
	v_mul_f32_e32 v214, 0x3e38aa3b, v39
	v_mul_f32_e32 v215, 0x3e38aa3b, v32
	v_mul_f32_e32 v216, 0x3e38aa3b, v33
	v_mul_f32_e32 v217, 0x3e38aa3b, v34
	v_mul_f32_e32 v218, 0x3e38aa3b, v35
	ds_read_b128 v[8:11], v132 offset:24576
	ds_read_b128 v[12:15], v132 offset:25088
	ds_read_b128 v[16:19], v133 offset:24576
	ds_read_b128 v[174:177], v133 offset:25088
	s_waitcnt lgkmcnt(7)
	v_mfma_f32_16x16x32_bf16 v[20:23], v[24:27], v[4:7], 0
	s_waitcnt lgkmcnt(5)
	v_mfma_f32_16x16x32_bf16 v[28:31], v[28:31], v[0:3], v[20:23]
	v_mfma_f32_16x16x32_bf16 v[20:23], v[152:155], v[4:7], 0
	s_waitcnt lgkmcnt(4)
	v_mfma_f32_16x16x32_bf16 v[24:27], v[170:173], v[0:3], v[20:23]
	s_nop 4
	v_mul_f32_e32 v219, 0x3e38aa3b, v28
	v_mul_f32_e32 v224, 0x3e38aa3b, v29
	v_mul_f32_e32 v225, 0x3e38aa3b, v30
	v_mul_f32_e32 v226, 0x3e38aa3b, v31
	v_mul_f32_e32 v227, 0x3e38aa3b, v24
	v_mul_f32_e32 v228, 0x3e38aa3b, v25
	v_mul_f32_e32 v229, 0x3e38aa3b, v26
	v_mul_f32_e32 v230, 0x3e38aa3b, v27
	ds_read_b128 v[152:155], v132 offset:28672
	ds_read_b128 v[170:173], v132 offset:29184
	ds_read_b128 v[178:181], v133 offset:28672
	ds_read_b128 v[182:185], v133 offset:29184
	s_waitcnt lgkmcnt(7)
	v_mfma_f32_16x16x32_bf16 v[8:11], v[8:11], v[4:7], 0
	s_waitcnt lgkmcnt(5)
	v_mfma_f32_16x16x32_bf16 v[20:23], v[16:19], v[0:3], v[8:11]
	v_mfma_f32_16x16x32_bf16 v[8:11], v[12:15], v[4:7], 0
	s_waitcnt lgkmcnt(4)
	v_mfma_f32_16x16x32_bf16 v[16:19], v[174:177], v[0:3], v[8:11]
	s_nop 4
	v_mul_f32_e32 v231, 0x3e38aa3b, v20
	v_mul_f32_e32 v232, 0x3e38aa3b, v21
	v_mul_f32_e32 v233, 0x3e38aa3b, v22
	v_mul_f32_e32 v234, 0x3e38aa3b, v23
	v_mul_f32_e32 v174, 0x3e38aa3b, v16
	v_mul_f32_e32 v175, 0x3e38aa3b, v17
	v_mul_f32_e32 v176, 0x3e38aa3b, v18
	v_mul_f32_e32 v177, 0x3e38aa3b, v19
	s_waitcnt lgkmcnt(3)
; __device__ __forceinline__ unsigned cvt_pk_bf16(float lo, float hi) { const f32x2 v = (f32x2){lo, hi}; return __builtin_bit_cast(unsigned, __builtin_convertvector(v, bf16v2)); }
; #define AH_LDV(c, bufi) do { const int vaddr = vrow + (((vchunk0 + (c) * vcs + g) ^ qi) << 4); _Pragma("unroll") for (int dt = 0; dt < 4; ++dt) vf[bufi][dt] = *(const LAS bf16x8*)(lds + vaddr + dt * vpitch_dt); } while (0)
; template <bool LOC> ...
;     ...
;         for (int e = 0; e < 8; ++e) { const float a = (e < 4) ? t0[e] : t1[e - 4];
;             if (LOC) { const float bv = bp[c * RPB_PITCH + e]; const bool ok = (e >= elo) && (e < elo + 16); s[c][e] = ok ? (a * SC + bv) : -INFINITY; }
;             else s[c][e] = a * SC; }
;         __builtin_amdgcn_sched_barrier(0);
;     }
;     ...
;     float m2 = mx;
; #pragma unroll
;     for (int c = 0; c < 8; ++c)
; #pragma unroll
;         for (int e = 0; e < 8; ++e) m2 = fmaxf(m2, s[c][e]);
;     m2 = fmaxf(m2, __shfl_xor(m2, 16)); m2 = fmaxf(m2, __shfl_xor(m2, 32));
;     const float alpha = __builtin_amdgcn_exp2f(mx - m2);
;     mx = m2; lsum *= alpha;
; #pragma unroll
;     for (int dt = 0; dt < 4; ++dt) o[dt] = o[dt] * alpha;
;     bf16x8 vf[2][4];
;     ...
;     AH_LDV(0, 0);
; #pragma unroll
;     for (int c = 0; c < 8; ++c) {
;         if (c < 7) AH_LDV(c + 1, (c + 1) & 1);
;         __builtin_amdgcn_sched_barrier(0);
;         float pe[8];
; #pragma unroll
;         for (int e = 0; e < 8; ++e) { pe[e] = __builtin_amdgcn_exp2f(s[c][e] - mx); lsum += pe[e]; }
;         u32x4 pw; pw.x = cvt_pk_bf16(pe[0], pe[1]); pw.y = cvt_pk_bf16(pe[2], pe[3]); pw.z = cvt_pk_bf16(pe[4], pe[5]); pw.w = cvt_pk_bf16(pe[6], pe[7]);
;         const bf16x8 pb = __builtin_bit_cast(bf16x8, pw);
; #pragma unroll
;         for (int dt = 0; dt < 4; ++dt) o[dt] = __builtin_amdgcn_mfma_f32_16x16x32_bf16(vf[c & 1][dt], pb, o[dt], 0, 0, 0);
	v_mfma_f32_16x16x32_bf16 v[8:11], v[152:155], v[4:7], 0
	s_waitcnt lgkmcnt(1)
	v_mfma_f32_16x16x32_bf16 v[12:15], v[178:181], v[0:3], v[8:11]
	v_mfma_f32_16x16x32_bf16 v[8:11], v[170:173], v[4:7], 0
	s_waitcnt lgkmcnt(0)
	v_mfma_f32_16x16x32_bf16 v[8:11], v[182:185], v[0:3], v[8:11]
	s_nop 4
	v_mul_f32_e32 v152, 0x3e38aa3b, v12
	v_mul_f32_e32 v153, 0x3e38aa3b, v13
	v_mul_f32_e32 v154, 0x3e38aa3b, v14
	v_mul_f32_e32 v155, 0x3e38aa3b, v15
	v_mul_f32_e32 v170, 0x3e38aa3b, v8
	v_mul_f32_e32 v171, 0x3e38aa3b, v9
	v_mul_f32_e32 v172, 0x3e38aa3b, v10
	v_mul_f32_e32 v173, 0x3e38aa3b, v11
	s_mov_b32 s30, 0xff800000
	v_max3_f32 v97, v97, s30, v99
	v_max3_f32 v97, v97, v105, v151
	v_max3_f32 v97, v97, v160, v161
	v_max3_f32 v97, v97, v167, v186
	v_max3_f32 v97, v97, v187, v188
	v_max3_f32 v97, v97, v189, v190
	v_max3_f32 v97, v97, v191, v192
	v_max3_f32 v97, v97, v193, v194
	v_max3_f32 v97, v97, v195, v196
	v_max3_f32 v97, v97, v197, v198
	v_max3_f32 v97, v97, v199, v200
	v_max3_f32 v97, v97, v201, v202
	v_max3_f32 v97, v97, v203, v204
	v_max3_f32 v97, v97, v205, v206
	v_max3_f32 v97, v97, v207, v208
	v_max3_f32 v97, v97, v209, v210
	v_max3_f32 v97, v97, v211, v212
	v_max3_f32 v97, v97, v213, v214
	v_max3_f32 v97, v97, v215, v216
	v_max3_f32 v97, v97, v217, v218
	v_max3_f32 v97, v97, v219, v224
	v_max3_f32 v97, v97, v225, v226
	v_max3_f32 v97, v97, v227, v228
	v_max3_f32 v97, v97, v229, v230
	v_max3_f32 v97, v97, v231, v232
	v_max3_f32 v97, v97, v233, v234
	v_max3_f32 v97, v97, v174, v175
	v_max3_f32 v97, v97, v176, v177
	v_max3_f32 v97, v97, v152, v153
	v_max3_f32 v97, v97, v154, v155
	v_max3_f32 v97, v97, v170, v171
	v_max3_f32 v97, v97, v172, v173
	ds_bpermute_b32 v99, v114, v97
	ds_read_b128 v[152:155], v134 offset:32768
	ds_read_b128 v[170:173], v134 offset:40960
	ds_read_b128 v[174:177], v134 offset:49152
	ds_read_b128 v[178:181], v134 offset:57344
	ds_read_b128 v[182:185], v135 offset:32768
	ds_read_b128 v[186:189], v135 offset:40960
	ds_read_b128 v[190:193], v135 offset:49152
	ds_read_b128 v[194:197], v135 offset:57344
	s_waitcnt lgkmcnt(8)
	v_max_f32_e32 v99, v99, v99
	v_max_f32_e32 v97, v97, v99
	ds_bpermute_b32 v99, v115, v97
	s_waitcnt lgkmcnt(0)
	v_max_f32_e32 v99, v99, v99
	v_max_f32_e32 v97, v97, v99
	v_sub_f32_e32 v99, 0xff800000, v97
	v_exp_f32_e32 v99, v99
	s_nop 0
	v_mul_f32_e32 v198, 0, v99
	v_mov_b32_e32 v199, v198
	v_mov_b32_e32 v200, v198
	v_mov_b32_e32 v201, v198
	v_fma_f32 v68, v68, s67, -v97
	v_exp_f32_e32 v68, v68
	v_fma_f32 v69, v69, s67, -v97
	v_exp_f32_e32 v69, v69
	v_fma_f32 v70, v70, s67, -v97
	v_exp_f32_e32 v70, v70
	v_fma_f32 v71, v71, s67, -v97
	v_exp_f32_e32 v71, v71
	v_fma_f32 v64, v64, s67, -v97
	v_fma_f32 v99, 0, v99, v68
	v_exp_f32_e32 v105, v64
	v_add_f32_e32 v99, v69, v99
	v_add_f32_e32 v99, v70, v99
	v_add_f32_e32 v99, v71, v99
	v_fma_f32 v65, v65, s67, -v97
	v_add_f32_e32 v64, v105, v99
	v_exp_f32_e32 v99, v65
	v_fma_f32 v65, v66, s67, -v97
	v_exp_f32_e32 v151, v65
	v_fma_f32 v65, v67, s67, -v97
	v_exp_f32_e32 v67, v65
	v_add_f32_e32 v64, v99, v64
	v_add_f32_e32 v64, v151, v64
	v_cvt_pk_bf16_f32 v65, v70, v71
	v_add_f32_e32 v160, v67, v64
	v_cvt_pk_bf16_f32 v64, v68, v69
	v_cvt_pk_bf16_f32 v66, v105, v99
	v_cvt_pk_bf16_f32 v67, v151, v67
	s_nop 1
	v_mfma_f32_16x16x32_bf16 v[68:71], v[152:155], v[64:67], v[198:201]
	v_mfma_f32_16x16x32_bf16 v[152:155], v[170:173], v[64:67], v[198:201]
	v_mfma_f32_16x16x32_bf16 v[170:173], v[174:177], v[64:67], v[198:201]
	v_mfma_f32_16x16x32_bf16 v[64:67], v[178:181], v[64:67], v[198:201]
	ds_read_b128 v[174:177], v136 offset:32768
	ds_read_b128 v[178:181], v136 offset:40960
	s_nop 0
	ds_read_b128 v[198:201], v136 offset:49152
	ds_read_b128 v[202:205], v136 offset:57344
	v_fma_f32 v60, v60, s67, -v97
	v_exp_f32_e32 v60, v60
	v_fma_f32 v61, v61, s67, -v97
	v_exp_f32_e32 v61, v61
	v_fma_f32 v62, v62, s67, -v97
	v_exp_f32_e32 v62, v62
	v_fma_f32 v63, v63, s67, -v97
	v_exp_f32_e32 v63, v63
	v_fma_f32 v56, v56, s67, -v97
	v_add_f32_e32 v99, v60, v160
	v_exp_f32_e32 v105, v56
	v_add_f32_e32 v99, v61, v99
	v_add_f32_e32 v99, v62, v99
	v_add_f32_e32 v99, v63, v99
	v_fma_f32 v57, v57, s67, -v97
	v_add_f32_e32 v56, v105, v99
	v_exp_f32_e32 v99, v57
	v_fma_f32 v57, v58, s67, -v97
	v_exp_f32_e32 v151, v57
	v_fma_f32 v57, v59, s67, -v97
	v_exp_f32_e32 v59, v57
	v_add_f32_e32 v56, v99, v56
	v_add_f32_e32 v56, v151, v56
	v_cvt_pk_bf16_f32 v57, v62, v63
	v_add_f32_e32 v160, v59, v56
	v_cvt_pk_bf16_f32 v56, v60, v61
	v_cvt_pk_bf16_f32 v58, v105, v99
	v_cvt_pk_bf16_f32 v59, v151, v59
	s_nop 1
	v_mfma_f32_16x16x32_bf16 v[60:63], v[182:185], v[56:59], v[68:71]
	v_mfma_f32_16x16x32_bf16 v[68:71], v[186:189], v[56:59], v[152:155]
	v_mfma_f32_16x16x32_bf16 v[152:155], v[190:193], v[56:59], v[170:173]
	v_mfma_f32_16x16x32_bf16 v[56:59], v[194:197], v[56:59], v[64:67]
	s_nop 2
	ds_read_b128 v[64:67], v137 offset:32768
	ds_read_b128 v[170:173], v137 offset:40960
	ds_read_b128 v[182:185], v137 offset:49152
	ds_read_b128 v[186:189], v137 offset:57344
	v_fma_f32 v52, v52, s67, -v97
	v_exp_f32_e32 v52, v52
	v_fma_f32 v53, v53, s67, -v97
	v_exp_f32_e32 v53, v53
	v_fma_f32 v54, v54, s67, -v97
	v_exp_f32_e32 v54, v54
	v_fma_f32 v55, v55, s67, -v97
	v_exp_f32_e32 v55, v55
	v_fma_f32 v48, v48, s67, -v97
	v_add_f32_e32 v99, v52, v160
	v_exp_f32_e32 v105, v48
	v_add_f32_e32 v99, v53, v99
	v_add_f32_e32 v99, v54, v99
	v_add_f32_e32 v99, v55, v99
	v_fma_f32 v49, v49, s67, -v97
	v_add_f32_e32 v48, v105, v99
	v_exp_f32_e32 v99, v49
	v_fma_f32 v49, v50, s67, -v97
	v_exp_f32_e32 v151, v49
	v_fma_f32 v49, v51, s67, -v97
	v_exp_f32_e32 v51, v49
	v_add_f32_e32 v48, v99, v48
	v_add_f32_e32 v48, v151, v48
	v_cvt_pk_bf16_f32 v49, v54, v55
	v_add_f32_e32 v160, v51, v48
	v_cvt_pk_bf16_f32 v48, v52, v53
	v_cvt_pk_bf16_f32 v50, v105, v99
	v_cvt_pk_bf16_f32 v51, v151, v51
	s_waitcnt lgkmcnt(7)
; __device__ __forceinline__ unsigned cvt_pk_bf16(float lo, float hi) { const f32x2 v = (f32x2){lo, hi}; return __builtin_bit_cast(unsigned, __builtin_convertvector(v, bf16v2)); }
; #define AH_LDV(c, bufi) do { const int vaddr = vrow + (((vchunk0 + (c) * vcs + g) ^ qi) << 4); _Pragma("unroll") for (int dt = 0; dt < 4; ++dt) vf[bufi][dt] = *(const LAS bf16x8*)(lds + vaddr + dt * vpitch_dt); } while (0)
; template <bool LOC> ...
;     ...
;     for (int c = 0; c < 8; ++c) {
;         if (c < 7) AH_LDV(c + 1, (c + 1) & 1);
;         __builtin_amdgcn_sched_barrier(0);
;         float pe[8];
; #pragma unroll
;         for (int e = 0; e < 8; ++e) { pe[e] = __builtin_amdgcn_exp2f(s[c][e] - mx); lsum += pe[e]; }
;         u32x4 pw; pw.x = cvt_pk_bf16(pe[0], pe[1]); pw.y = cvt_pk_bf16(pe[2], pe[3]); pw.z = cvt_pk_bf16(pe[4], pe[5]); pw.w = cvt_pk_bf16(pe[6], pe[7]);
;         const bf16x8 pb = __builtin_bit_cast(bf16x8, pw);
; #pragma unroll
;         for (int dt = 0; dt < 4; ++dt) o[dt] = __builtin_amdgcn_mfma_f32_16x16x32_bf16(vf[c & 1][dt], pb, o[dt], 0, 0, 0);
;         __builtin_amdgcn_sched_barrier(0);
;     }
	s_nop 0
	v_mfma_f32_16x16x32_bf16 v[52:55], v[174:177], v[48:51], v[60:63]
	s_waitcnt lgkmcnt(6)
	v_mfma_f32_16x16x32_bf16 v[60:63], v[178:181], v[48:51], v[68:71]
	s_waitcnt lgkmcnt(5)
	v_mfma_f32_16x16x32_bf16 v[68:71], v[198:201], v[48:51], v[152:155]
	s_waitcnt lgkmcnt(4)
	v_mfma_f32_16x16x32_bf16 v[48:51], v[202:205], v[48:51], v[56:59]
	s_nop 2
	ds_read_b128 v[56:59], v138 offset:32768
	ds_read_b128 v[152:155], v138 offset:40960
	ds_read_b128 v[174:177], v138 offset:49152
	ds_read_b128 v[178:181], v138 offset:57344
	v_fma_f32 v44, v44, s67, -v97
	v_exp_f32_e32 v44, v44
	v_fma_f32 v45, v45, s67, -v97
	v_exp_f32_e32 v45, v45
	v_fma_f32 v46, v46, s67, -v97
	v_exp_f32_e32 v46, v46
	v_fma_f32 v47, v47, s67, -v97
	v_exp_f32_e32 v47, v47
	v_fma_f32 v40, v40, s67, -v97
	v_add_f32_e32 v99, v44, v160
	v_exp_f32_e32 v105, v40
	v_add_f32_e32 v99, v45, v99
	v_add_f32_e32 v99, v46, v99
	v_add_f32_e32 v99, v47, v99
	v_fma_f32 v41, v41, s67, -v97
	v_add_f32_e32 v40, v105, v99
	v_exp_f32_e32 v99, v41
	v_fma_f32 v41, v42, s67, -v97
	v_exp_f32_e32 v151, v41
	v_fma_f32 v41, v43, s67, -v97
	v_exp_f32_e32 v43, v41
	v_add_f32_e32 v40, v99, v40
	v_add_f32_e32 v40, v151, v40
	v_cvt_pk_bf16_f32 v41, v46, v47
	v_add_f32_e32 v160, v43, v40
	v_cvt_pk_bf16_f32 v40, v44, v45
	v_cvt_pk_bf16_f32 v42, v105, v99
	v_cvt_pk_bf16_f32 v43, v151, v43
	s_waitcnt lgkmcnt(7)
	s_nop 0
	v_mfma_f32_16x16x32_bf16 v[44:47], v[64:67], v[40:43], v[52:55]
	s_waitcnt lgkmcnt(6)
	v_mfma_f32_16x16x32_bf16 v[52:55], v[170:173], v[40:43], v[60:63]
	s_waitcnt lgkmcnt(5)
	v_mfma_f32_16x16x32_bf16 v[60:63], v[182:185], v[40:43], v[68:71]
	s_waitcnt lgkmcnt(4)
	v_mfma_f32_16x16x32_bf16 v[40:43], v[186:189], v[40:43], v[48:51]
	s_nop 2
	ds_read_b128 v[48:51], v139 offset:32768
	ds_read_b128 v[64:67], v139 offset:40960
	ds_read_b128 v[68:71], v139 offset:49152
	ds_read_b128 v[170:173], v139 offset:57344
	v_fma_f32 v36, v36, s67, -v97
	v_exp_f32_e32 v36, v36
	v_fma_f32 v37, v37, s67, -v97
	v_exp_f32_e32 v37, v37
	v_fma_f32 v38, v38, s67, -v97
	v_exp_f32_e32 v38, v38
	v_fma_f32 v39, v39, s67, -v97
	v_exp_f32_e32 v39, v39
	v_fma_f32 v32, v32, s67, -v97
	v_add_f32_e32 v99, v36, v160
	v_exp_f32_e32 v105, v32
	v_add_f32_e32 v99, v37, v99
	v_add_f32_e32 v99, v38, v99
	v_add_f32_e32 v99, v39, v99
	v_fma_f32 v33, v33, s67, -v97
	v_add_f32_e32 v32, v105, v99
	v_exp_f32_e32 v99, v33
	v_fma_f32 v33, v34, s67, -v97
	v_exp_f32_e32 v151, v33
	v_fma_f32 v33, v35, s67, -v97
	v_exp_f32_e32 v35, v33
	v_add_f32_e32 v32, v99, v32
	v_add_f32_e32 v32, v151, v32
	v_cvt_pk_bf16_f32 v33, v38, v39
	v_add_f32_e32 v160, v35, v32
	v_cvt_pk_bf16_f32 v32, v36, v37
	v_cvt_pk_bf16_f32 v34, v105, v99
	v_cvt_pk_bf16_f32 v35, v151, v35
	s_waitcnt lgkmcnt(7)
	s_nop 0
	v_mfma_f32_16x16x32_bf16 v[36:39], v[56:59], v[32:35], v[44:47]
	s_waitcnt lgkmcnt(6)
	v_mfma_f32_16x16x32_bf16 v[44:47], v[152:155], v[32:35], v[52:55]
	s_waitcnt lgkmcnt(5)
	v_mfma_f32_16x16x32_bf16 v[52:55], v[174:177], v[32:35], v[60:63]
	s_waitcnt lgkmcnt(4)
	v_mfma_f32_16x16x32_bf16 v[32:35], v[178:181], v[32:35], v[40:43]
	s_nop 2
	ds_read_b128 v[40:43], v140 offset:32768
	ds_read_b128 v[56:59], v140 offset:40960
	ds_read_b128 v[60:63], v140 offset:49152
	ds_read_b128 v[152:155], v140 offset:57344
	v_fma_f32 v28, v28, s67, -v97
	v_exp_f32_e32 v28, v28
	v_fma_f32 v29, v29, s67, -v97
	v_exp_f32_e32 v29, v29
	v_fma_f32 v30, v30, s67, -v97
	v_exp_f32_e32 v30, v30
	v_fma_f32 v31, v31, s67, -v97
	v_exp_f32_e32 v31, v31
	v_fma_f32 v24, v24, s67, -v97
	v_add_f32_e32 v99, v28, v160
	v_exp_f32_e32 v105, v24
	v_add_f32_e32 v99, v29, v99
	v_add_f32_e32 v99, v30, v99
	v_add_f32_e32 v99, v31, v99
	v_fma_f32 v25, v25, s67, -v97
	v_add_f32_e32 v24, v105, v99
	v_exp_f32_e32 v99, v25
	v_fma_f32 v25, v26, s67, -v97
	v_exp_f32_e32 v151, v25
	v_fma_f32 v25, v27, s67, -v97
	v_exp_f32_e32 v27, v25
	v_add_f32_e32 v24, v99, v24
	v_add_f32_e32 v24, v151, v24
	v_cvt_pk_bf16_f32 v25, v30, v31
	v_add_f32_e32 v160, v27, v24
	v_cvt_pk_bf16_f32 v24, v28, v29
	v_cvt_pk_bf16_f32 v26, v105, v99
	v_cvt_pk_bf16_f32 v27, v151, v27
	s_waitcnt lgkmcnt(7)
	s_nop 0
	v_mfma_f32_16x16x32_bf16 v[28:31], v[48:51], v[24:27], v[36:39]
	s_waitcnt lgkmcnt(6)
	v_mfma_f32_16x16x32_bf16 v[36:39], v[64:67], v[24:27], v[44:47]
	s_waitcnt lgkmcnt(5)
	v_mfma_f32_16x16x32_bf16 v[44:47], v[68:71], v[24:27], v[52:55]
	s_waitcnt lgkmcnt(4)
	v_mfma_f32_16x16x32_bf16 v[24:27], v[170:173], v[24:27], v[32:35]
	s_nop 2
	ds_read_b128 v[32:35], v141 offset:32768
	ds_read_b128 v[48:51], v141 offset:40960
	ds_read_b128 v[52:55], v141 offset:49152
	ds_read_b128 v[64:67], v141 offset:57344
	v_fma_f32 v20, v20, s67, -v97
	v_exp_f32_e32 v20, v20
	v_fma_f32 v21, v21, s67, -v97
	v_exp_f32_e32 v21, v21
	v_fma_f32 v22, v22, s67, -v97
	v_exp_f32_e32 v22, v22
	v_fma_f32 v23, v23, s67, -v97
	v_exp_f32_e32 v23, v23
	v_fma_f32 v16, v16, s67, -v97
	v_add_f32_e32 v68, v20, v160
	v_exp_f32_e32 v69, v16
	v_add_f32_e32 v68, v21, v68
	v_add_f32_e32 v68, v22, v68
	v_add_f32_e32 v68, v23, v68
	v_fma_f32 v17, v17, s67, -v97
	v_add_f32_e32 v16, v69, v68
	v_exp_f32_e32 v68, v17
	v_fma_f32 v17, v18, s67, -v97
	v_exp_f32_e32 v70, v17
	v_fma_f32 v17, v19, s67, -v97
	v_exp_f32_e32 v19, v17
	v_add_f32_e32 v16, v68, v16
	v_add_f32_e32 v16, v70, v16
	v_cvt_pk_bf16_f32 v17, v22, v23
	v_add_f32_e32 v71, v19, v16
	v_cvt_pk_bf16_f32 v16, v20, v21
	v_cvt_pk_bf16_f32 v18, v69, v68
	v_cvt_pk_bf16_f32 v19, v70, v19
	s_waitcnt lgkmcnt(7)
	s_nop 0
	v_mfma_f32_16x16x32_bf16 v[20:23], v[40:43], v[16:19], v[28:31]
	s_waitcnt lgkmcnt(6)
	v_mfma_f32_16x16x32_bf16 v[36:39], v[56:59], v[16:19], v[36:39]
	s_waitcnt lgkmcnt(5)
	v_mfma_f32_16x16x32_bf16 v[40:43], v[60:63], v[16:19], v[44:47]
	s_waitcnt lgkmcnt(4)
	v_mfma_f32_16x16x32_bf16 v[24:27], v[152:155], v[16:19], v[24:27]
	v_fma_f32 v12, v12, s67, -v97
	v_exp_f32_e32 v12, v12
	v_fma_f32 v13, v13, s67, -v97
	v_exp_f32_e32 v13, v13
	v_fma_f32 v14, v14, s67, -v97
	v_exp_f32_e32 v14, v14
	v_fma_f32 v15, v15, s67, -v97
	v_exp_f32_e32 v15, v15
	v_fma_f32 v8, v8, s67, -v97
	v_add_f32_e32 v16, v12, v71
	v_exp_f32_e32 v8, v8
	v_fma_f32 v9, v9, s67, -v97
	v_add_f32_e32 v16, v13, v16
	v_exp_f32_e32 v9, v9
	v_fma_f32 v10, v10, s67, -v97
	v_fma_f32 v11, v11, s67, -v97
	v_add_f32_e32 v16, v14, v16
	v_exp_f32_e32 v10, v10
	v_exp_f32_e32 v11, v11
	v_add_f32_e32 v16, v15, v16
	v_add_f32_e32 v16, v8, v16
	v_add_f32_e32 v16, v9, v16
	v_add_f32_e32 v16, v10, v16
	v_cvt_pk_bf16_f32 v44, v12, v13
	v_cvt_pk_bf16_f32 v45, v14, v15
	v_cvt_pk_bf16_f32 v46, v8, v9
	v_cvt_pk_bf16_f32 v47, v10, v11
	v_add_f32_e32 v28, v11, v16
	s_waitcnt lgkmcnt(3)
	v_mfma_f32_16x16x32_bf16 v[8:11], v[32:35], v[44:47], v[20:23]
	s_waitcnt lgkmcnt(2)
	v_mfma_f32_16x16x32_bf16 v[12:15], v[48:51], v[44:47], v[36:39]
	s_waitcnt lgkmcnt(1)
	v_mfma_f32_16x16x32_bf16 v[16:19], v[52:55], v[44:47], v[40:43]
	s_waitcnt lgkmcnt(0)
	v_mfma_f32_16x16x32_bf16 v[20:23], v[64:67], v[44:47], v[24:27]
	s_andn2_b64 vcc, exec, s[74:75]
	s_mov_b64 s[68:69], -1
	s_cbranch_vccnz .LBB0_298
; __device__ __forceinline__ unsigned cvt_pk_bf16(float lo, float hi) { const f32x2 v = (f32x2){lo, hi}; return __builtin_bit_cast(unsigned, __builtin_convertvector(v, bf16v2)); }
; __device__ __forceinline__ void attn_store(bf16_t* MIX, int qtok, int h, int g, float lsum, const f32x4 (&o)[4]) {
;     lsum += __shfl_xor(lsum, 16); lsum += __shfl_xor(lsum, 32);
;     const float inv = 1.f / lsum;
;     bf16_t* op = MIX + (size_t)qtok * DM + 512 + h * 64 + 4 * g;
; #pragma unroll
;     for (int dt = 0; dt < 4; ++dt) { u32x2 w; w.x = cvt_pk_bf16(o[dt][0] * inv, o[dt][1] * inv); w.y = cvt_pk_bf16(o[dt][2] * inv, o[dt][3] * inv); *(u32x2*)(op + 16 * dt) = w; }
; }
	ds_bpermute_b32 v24, v114, v28
	v_ashrrev_i32_e32 v105, 31, v104
	s_waitcnt lgkmcnt(0)
	v_add_f32_e32 v24, v28, v24
	ds_bpermute_b32 v25, v115, v24
	s_waitcnt lgkmcnt(0)
	v_add_f32_e32 v24, v24, v25
	v_div_scale_f32 v25, s[68:69], v24, v24, 1.0
	v_rcp_f32_e32 v26, v25
	s_mov_b64 s[68:69], 0
	v_fma_f32 v27, -v25, v26, 1.0
	v_fmac_f32_e32 v26, v27, v26
	v_div_scale_f32 v27, vcc, 1.0, v24, 1.0
	v_mul_f32_e32 v29, v27, v26
	v_fma_f32 v30, -v25, v29, v27
	v_fmac_f32_e32 v29, v30, v26
	v_fma_f32 v25, -v25, v29, v27
	v_div_fmas_f32 v25, v25, v26, v29
	v_div_fixup_f32 v24, v25, v24, 1.0
	v_lshlrev_b64 v[26:27], 11, v[104:105]
	v_pk_mul_f32 v[30:31], v[8:9], v[24:25] op_sel_hi:[1,0]
	v_pk_mul_f32 v[32:33], v[10:11], v[24:25] op_sel_hi:[1,0]
	v_lshl_add_u64 v[26:27], v[102:103], 0, v[26:27]
	v_cvt_pk_bf16_f32 v30, v30, v31
	v_cvt_pk_bf16_f32 v31, v32, v33
	global_store_dwordx2 v[26:27], v[30:31], off offset:1024
	v_pk_mul_f32 v[30:31], v[12:13], v[24:25] op_sel_hi:[1,0]
	v_pk_mul_f32 v[32:33], v[14:15], v[24:25] op_sel_hi:[1,0]
	v_cvt_pk_bf16_f32 v30, v30, v31
	v_cvt_pk_bf16_f32 v31, v32, v33
	global_store_dwordx2 v[26:27], v[30:31], off offset:1056
	v_pk_mul_f32 v[30:31], v[16:17], v[24:25] op_sel_hi:[1,0]
	v_pk_mul_f32 v[32:33], v[18:19], v[24:25] op_sel_hi:[1,0]
	v_cvt_pk_bf16_f32 v30, v30, v31
	v_cvt_pk_bf16_f32 v31, v32, v33
	global_store_dwordx2 v[26:27], v[30:31], off offset:1088
	v_pk_mul_f32 v[30:31], v[20:21], v[24:25] op_sel_hi:[1,0]
	v_pk_mul_f32 v[24:25], v[22:23], v[24:25] op_sel_hi:[1,0]
	v_cvt_pk_bf16_f32 v30, v30, v31
	v_cvt_pk_bf16_f32 v31, v24, v25
	global_store_dwordx2 v[26:27], v[30:31], off offset:1120
	s_branch .LBB0_298

; __device__ __forceinline__ void phase_mixer(const Params& p, LAS unsigned char* lds, int l, bool with_ctx, int G, int tid, int wave, int lane, int rep_attn, int rep_pool) {
;     ...
;     for (int run = gw; run < nrun; run += NGW) {
;         const int tok0 = run * 16; const bool isl = tok0 < ML;
;         const int base = isl ? (tok0 & ~(SEQ - 1)) : (ML + ((tok0 - ML) & ~(CT - 1))), len = isl ? SEQ : CT, t0 = tok0 - base;
;         u32x4 w[31];
; #pragma unroll
;         for (int i = 0; i < 31; ++i) { const int tt = min(max(t0 - 8 + i, 0), len - 1); w[i] = *(const u32x4*)(PB + (size_t)(base + tt) * PBW + 8 * lane); }
; #pragma unroll
;         for (int o = 0; o < 16; ++o) {
;             const int t = t0 + o, st = max(t - lo, 0), en = min(t + hi + 1, len);
;             float acc[8];
; #pragma unroll
;             for (int e = 0; e < 8; ++e) acc[e] = 0.f;
; #pragma unroll
;             for (int i = 0; i < 16; ++i) { const int tt = t + i - 8; const float wt = (tt >= st && tt < en) ? 1.f : 0.f; const u32x4 ww = w[o + i];
.LBB0_308:
	s_lshl_b32 s4, s6, 4
	s_cmpk_lt_i32 s6, 0x800
	s_movk_i32 s0, 0x1000
	s_cselect_b32 s9, s0, 0x100
	s_movk_i32 s0, 0xf000
	s_cselect_b32 s0, s0, 0x7fffff00
	s_and_b32 s1, s0, s4
	s_sub_i32 s8, s4, s1
	s_add_i32 s0, s8, -8
	s_add_i32 s5, s9, -1
	s_max_i32 s10, s0, 0
	s_min_u32 s10, s10, s5
	s_add_i32 s10, s10, s1
	s_waitcnt vmcnt(0)
	v_mad_i64_i32 v[0:1], s[10:11], s10, v223, v[124:125]
	s_add_i32 s33, s8, -7
	s_max_i32 s10, s33, 0
	s_min_u32 s10, s10, s5
	s_add_i32 s10, s10, s1
	global_load_dwordx4 v[84:87], v[0:1], off
	v_mad_i64_i32 v[0:1], s[10:11], s10, v223, v[124:125]
	s_add_i32 s25, s8, -6
	s_max_i32 s10, s25, 0
	s_min_u32 s10, s10, s5
	s_add_i32 s10, s10, s1
	global_load_dwordx4 v[88:91], v[0:1], off
	v_mad_i64_i32 v[0:1], s[10:11], s10, v223, v[124:125]
	s_add_i32 s24, s8, -5
	s_max_i32 s10, s24, 0
	s_min_u32 s10, s10, s5
	s_add_i32 s10, s10, s1
	global_load_dwordx4 v[92:95], v[0:1], off
	v_mad_i64_i32 v[0:1], s[10:11], s10, v223, v[124:125]
	s_add_i32 s30, s8, -4
	s_max_i32 s10, s30, 0
	s_min_u32 s10, s10, s5
	s_add_i32 s10, s10, s1
	global_load_dwordx4 v[96:99], v[0:1], off
	v_mad_i64_i32 v[0:1], s[10:11], s10, v223, v[124:125]
	s_add_i32 s29, s8, -3
	s_max_i32 s10, s29, 0
	s_min_u32 s10, s10, s5
	s_add_i32 s10, s10, s1
	global_load_dwordx4 v[100:103], v[0:1], off
	v_mad_i64_i32 v[0:1], s[10:11], s10, v223, v[124:125]
	s_add_i32 s28, s8, -2
	s_max_i32 s10, s28, 0
	s_min_u32 s10, s10, s5
	s_add_i32 s10, s10, s1
	global_load_dwordx4 v[104:107], v[0:1], off
	v_mad_i64_i32 v[0:1], s[10:11], s10, v223, v[124:125]
	s_add_i32 s27, s8, -1
	s_max_i32 s10, s27, 0
	s_min_u32 s10, s10, s5
	s_add_i32 s10, s10, s1
	global_load_dwordx4 v[108:111], v[0:1], off
	v_mad_i64_i32 v[0:1], s[10:11], s10, v223, v[124:125]
	s_max_i32 s10, s8, 0
	s_min_u32 s10, s10, s5
	s_add_i32 s10, s10, s1
	global_load_dwordx4 v[112:115], v[0:1], off
	v_mad_i64_i32 v[0:1], s[10:11], s10, v223, v[124:125]
	s_or_b32 s26, s8, 1
	s_max_i32 s10, s26, 0
	s_min_u32 s10, s10, s5
	s_add_i32 s10, s10, s1
	global_load_dwordx4 v[80:83], v[0:1], off
	v_mad_i64_i32 v[0:1], s[10:11], s10, v223, v[124:125]
	s_or_b32 s23, s8, 2
	s_max_i32 s10, s23, 0
	s_min_u32 s10, s10, s5
	s_add_i32 s10, s10, s1
	global_load_dwordx4 v[116:119], v[0:1], off
	v_mad_i64_i32 v[0:1], s[10:11], s10, v223, v[124:125]
	s_or_b32 s22, s8, 3
	s_max_i32 s10, s22, 0
	s_min_u32 s10, s10, s5
	s_add_i32 s10, s10, s1
	global_load_dwordx4 v[120:123], v[0:1], off
	v_mad_i64_i32 v[0:1], s[10:11], s10, v223, v[124:125]
	s_or_b32 s21, s8, 4
	s_max_i32 s10, s21, 0
	s_min_u32 s10, s10, s5
	s_add_i32 s10, s10, s1
	global_load_dwordx4 v[60:63], v[0:1], off
	v_mad_i64_i32 v[0:1], s[10:11], s10, v223, v[124:125]
	s_or_b32 s20, s8, 5
	s_max_i32 s10, s20, 0
	s_min_u32 s10, s10, s5
	s_add_i32 s10, s10, s1
	global_load_dwordx4 v[64:67], v[0:1], off
	v_mad_i64_i32 v[0:1], s[10:11], s10, v223, v[124:125]
	s_or_b32 s19, s8, 6
	s_max_i32 s10, s19, 0
	s_min_u32 s10, s10, s5
	s_add_i32 s10, s10, s1
	global_load_dwordx4 v[68:71], v[0:1], off
	v_mad_i64_i32 v[0:1], s[10:11], s10, v223, v[124:125]
	s_or_b32 s10, s8, 7
	s_max_i32 s11, s10, 0
	s_min_u32 s11, s11, s5
	s_add_i32 s11, s11, s1
	global_load_dwordx4 v[72:75], v[0:1], off
	v_mad_i64_i32 v[0:1], s[12:13], s11, v223, v[124:125]
	s_or_b32 s11, s8, 8
	s_max_i32 s12, s11, 0
	s_min_u32 s12, s12, s5
	s_add_i32 s12, s12, s1
	global_load_dwordx4 v[76:79], v[0:1], off
	v_mad_i64_i32 v[0:1], s[12:13], s12, v223, v[124:125]
	s_or_b32 s12, s8, 9
	s_max_i32 s13, s12, 0
	s_min_u32 s13, s13, s5
	s_add_i32 s13, s13, s1
	global_load_dwordx4 v[56:59], v[0:1], off
	v_mad_i64_i32 v[0:1], s[14:15], s13, v223, v[124:125]
	s_or_b32 s13, s8, 10
	s_max_i32 s14, s13, 0
	s_min_u32 s14, s14, s5
	s_add_i32 s14, s14, s1
	global_load_dwordx4 v[52:55], v[0:1], off
	v_mad_i64_i32 v[0:1], s[14:15], s14, v223, v[124:125]
	s_or_b32 s14, s8, 11
	s_max_i32 s15, s14, 0
	s_min_u32 s15, s15, s5
	s_add_i32 s15, s15, s1
	global_load_dwordx4 v[48:51], v[0:1], off
	v_mad_i64_i32 v[0:1], s[16:17], s15, v223, v[124:125]
	s_or_b32 s15, s8, 12
	s_max_i32 s16, s15, 0
	s_min_u32 s16, s16, s5
	s_add_i32 s16, s16, s1
	global_load_dwordx4 v[44:47], v[0:1], off
	v_mad_i64_i32 v[0:1], s[16:17], s16, v223, v[124:125]
	s_or_b32 s17, s8, 13
	s_max_i32 s16, s17, 0
	s_min_u32 s16, s16, s5
	s_add_i32 s16, s16, s1
	global_load_dwordx4 v[40:43], v[0:1], off
	v_mad_i64_i32 v[0:1], s[62:63], s16, v223, v[124:125]
	s_or_b32 s16, s8, 14
	s_max_i32 s18, s16, 0
	s_min_u32 s18, s18, s5
	s_add_i32 s18, s18, s1
	global_load_dwordx4 v[36:39], v[0:1], off
	v_mad_i64_i32 v[0:1], s[62:63], s18, v223, v[124:125]
	s_or_b32 s18, s8, 15
	s_max_i32 s53, s18, 0
	s_min_u32 s53, s53, s5
	s_add_i32 s53, s53, s1
	global_load_dwordx4 v[32:35], v[0:1], off
	v_mad_i64_i32 v[0:1], s[62:63], s53, v223, v[124:125]
	s_max_i32 s53, s8, -16
	s_add_i32 s53, s53, 16
	s_min_u32 s53, s53, s5
	s_add_i32 s53, s53, s1
	global_load_dwordx4 v[28:31], v[0:1], off
	v_mad_i64_i32 v[0:1], s[62:63], s53, v223, v[124:125]
	s_max_i32 s53, s8, 0xffffffef
	s_add_i32 s53, s53, 17
	s_min_u32 s53, s53, s5
	s_add_i32 s53, s53, s1
	global_load_dwordx4 v[24:27], v[0:1], off
	v_mad_i64_i32 v[0:1], s[62:63], s53, v223, v[124:125]
	s_max_i32 s53, s8, 0xffffffee
	s_add_i32 s53, s53, 18
	s_min_u32 s53, s53, s5
	s_add_i32 s53, s53, s1
	global_load_dwordx4 v[20:23], v[0:1], off
	v_mad_i64_i32 v[0:1], s[62:63], s53, v223, v[124:125]
	s_max_i32 s53, s8, 0xffffffed
	s_add_i32 s53, s53, 19
	s_min_u32 s53, s53, s5
	s_add_i32 s53, s53, s1
	global_load_dwordx4 v[16:19], v[0:1], off
	v_mad_i64_i32 v[0:1], s[62:63], s53, v223, v[124:125]
	s_max_i32 s53, s8, 0xffffffec
	s_add_i32 s53, s53, 20
	s_min_u32 s53, s53, s5
	s_add_i32 s53, s53, s1
	global_load_dwordx4 v[12:15], v[0:1], off
	v_mad_i64_i32 v[0:1], s[62:63], s53, v223, v[124:125]
	s_max_i32 s53, s8, 0xffffffeb
	s_add_i32 s53, s53, 21
	s_min_u32 s53, s53, s5
	s_add_i32 s53, s53, s1
	global_load_dwordx4 v[8:11], v[0:1], off
	v_mad_i64_i32 v[0:1], s[62:63], s53, v223, v[124:125]
	s_max_i32 s53, s8, 0xffffffea
	s_add_i32 s53, s53, 22
	v_sub_u32_e32 v128, s8, v167
	v_or_b32_e32 v129, s8, v167
	s_min_u32 s5, s53, s5
	v_max_i32_e32 v135, 0, v128
	v_min_i32_e32 v156, s9, v129
	s_add_i32 s5, s5, s1
	v_cmp_ge_i32_e32 vcc, s0, v135
	v_cmp_lt_i32_e64 s[0:1], s0, v156
	s_and_b64 s[0:1], vcc, s[0:1]
	v_cmp_ge_i32_e32 vcc, s33, v135
	v_cndmask_b32_e64 v128, 0, 1.0, s[0:1]
	v_cmp_lt_i32_e64 s[0:1], s33, v156
	s_and_b64 s[0:1], vcc, s[0:1]
	v_cmp_ge_i32_e32 vcc, s25, v135
	v_cndmask_b32_e64 v130, 0, 1.0, s[0:1]
	v_cmp_lt_i32_e64 s[0:1], s25, v156
	s_and_b64 s[0:1], vcc, s[0:1]
	v_cmp_ge_i32_e32 vcc, s24, v135
	v_cndmask_b32_e64 v132, 0, 1.0, s[0:1]
	v_cmp_lt_i32_e64 s[0:1], s24, v156
	s_and_b64 s[0:1], vcc, s[0:1]
	v_cmp_ge_i32_e32 vcc, s30, v135
	v_cndmask_b32_e64 v134, 0, 1.0, s[0:1]
	v_cmp_lt_i32_e64 s[0:1], s30, v156
	s_waitcnt vmcnt(28)
; __device__ __forceinline__ float bf_lo(unsigned w) { return __uint_as_float(w << 16); }
; __device__ __forceinline__ float bf_hi(unsigned w) { return __uint_as_float(w & 0xffff0000u); }
; __device__ __forceinline__ void phase_mixer(const Params& p, LAS unsigned char* lds, int l, bool with_ctx, int G, int tid, int wave, int lane, int rep_attn, int rep_pool) {
;     ...
;         for (int o = 0; o < 16; ++o) {
;             const int t = t0 + o, st = max(t - lo, 0), en = min(t + hi + 1, len);
;             float acc[8];
; #pragma unroll
;             for (int e = 0; e < 8; ++e) acc[e] = 0.f;
; #pragma unroll
;             for (int i = 0; i < 16; ++i) { const int tt = t + i - 8; const float wt = (tt >= st && tt < en) ? 1.f : 0.f; const u32x4 ww = w[o + i];
;                 acc[0] += wt * bf_lo(ww.x); acc[1] += wt * bf_hi(ww.x); acc[2] += wt * bf_lo(ww.y); acc[3] += wt * bf_hi(ww.y);
;                 acc[4] += wt * bf_lo(ww.z); acc[5] += wt * bf_hi(ww.z); acc[6] += wt * bf_lo(ww.w); acc[7] += wt * bf_hi(ww.w); }
	v_lshlrev_b32_e32 v136, 16, v84
	v_and_b32_e32 v137, 0xffff0000, v84
	s_and_b64 s[0:1], vcc, s[0:1]
	v_pk_fma_f32 v[136:137], v[128:129], v[136:137], 0 op_sel_hi:[0,1,0]
	s_waitcnt vmcnt(27)
	v_lshlrev_b32_e32 v204, 16, v88
	v_and_b32_e32 v205, 0xffff0000, v88
	v_cndmask_b32_e64 v140, 0, 1.0, s[0:1]
	v_cmp_ge_i32_e32 vcc, s29, v135
	v_cmp_lt_i32_e64 s[0:1], s29, v156
	v_pk_fma_f32 v[136:137], v[130:131], v[204:205], v[136:137] op_sel_hi:[0,1,1]
	s_waitcnt vmcnt(26)
	v_lshlrev_b32_e32 v196, 16, v92
	v_and_b32_e32 v197, 0xffff0000, v92
	v_lshlrev_b32_e32 v84, 16, v85
	v_and_b32_e32 v85, 0xffff0000, v85
	s_and_b64 s[0:1], vcc, s[0:1]
	v_pk_fma_f32 v[136:137], v[132:133], v[196:197], v[136:137] op_sel_hi:[0,1,1]
	s_waitcnt vmcnt(25)
	v_lshlrev_b32_e32 v190, 16, v96
	v_and_b32_e32 v191, 0xffff0000, v96
	v_pk_fma_f32 v[84:85], v[128:129], v[84:85], 0 op_sel_hi:[0,1,0]
	v_lshlrev_b32_e32 v206, 16, v89
	v_and_b32_e32 v207, 0xffff0000, v89
	v_cndmask_b32_e64 v142, 0, 1.0, s[0:1]
	v_cmp_ge_i32_e32 vcc, s28, v135
	v_cmp_lt_i32_e64 s[0:1], s28, v156
	v_pk_fma_f32 v[136:137], v[134:135], v[190:191], v[136:137] op_sel_hi:[0,1,1]
	s_waitcnt vmcnt(24)
	v_lshlrev_b32_e32 v182, 16, v100
	v_and_b32_e32 v183, 0xffff0000, v100
	v_pk_fma_f32 v[84:85], v[130:131], v[206:207], v[84:85] op_sel_hi:[0,1,1]
	v_lshlrev_b32_e32 v198, 16, v93
	v_and_b32_e32 v199, 0xffff0000, v93
	s_and_b64 s[0:1], vcc, s[0:1]
	v_pk_fma_f32 v[138:139], v[140:141], v[182:183], v[136:137] op_sel_hi:[0,1,1]
	s_waitcnt vmcnt(23)
	v_lshlrev_b32_e32 v136, 16, v104
	v_and_b32_e32 v137, 0xffff0000, v104
	v_pk_fma_f32 v[84:85], v[132:133], v[198:199], v[84:85] op_sel_hi:[0,1,1]
	v_lshlrev_b32_e32 v192, 16, v97
	v_and_b32_e32 v193, 0xffff0000, v97
	v_cndmask_b32_e64 v144, 0, 1.0, s[0:1]
	v_pk_fma_f32 v[138:139], v[142:143], v[136:137], v[138:139] op_sel_hi:[0,1,1]
	s_waitcnt vmcnt(22)
	v_lshlrev_b32_e32 v148, 16, v108
	v_and_b32_e32 v149, 0xffff0000, v108
	v_pk_fma_f32 v[84:85], v[134:135], v[192:193], v[84:85] op_sel_hi:[0,1,1]
	v_lshlrev_b32_e32 v184, 16, v101
	v_and_b32_e32 v185, 0xffff0000, v101
	v_pk_fma_f32 v[152:153], v[144:145], v[148:149], v[138:139] op_sel_hi:[0,1,1]
	v_pk_fma_f32 v[84:85], v[140:141], v[184:185], v[84:85] op_sel_hi:[0,1,1]
	v_lshlrev_b32_e32 v138, 16, v105
	v_and_b32_e32 v139, 0xffff0000, v105
	v_pk_fma_f32 v[84:85], v[142:143], v[138:139], v[84:85] op_sel_hi:[0,1,1]
	v_lshlrev_b32_e32 v150, 16, v109
	v_and_b32_e32 v151, 0xffff0000, v109
	v_pk_fma_f32 v[154:155], v[144:145], v[150:151], v[84:85] op_sel_hi:[0,1,1]
	v_lshlrev_b32_e32 v84, 16, v86
	v_and_b32_e32 v85, 0xffff0000, v86
	v_pk_fma_f32 v[84:85], v[128:129], v[84:85], 0 op_sel_hi:[0,1,0]
	v_lshlrev_b32_e32 v208, 16, v90
	v_and_b32_e32 v209, 0xffff0000, v90
	v_pk_fma_f32 v[84:85], v[130:131], v[208:209], v[84:85] op_sel_hi:[0,1,1]
	v_lshlrev_b32_e32 v200, 16, v94
	v_and_b32_e32 v201, 0xffff0000, v94
	v_pk_fma_f32 v[84:85], v[132:133], v[200:201], v[84:85] op_sel_hi:[0,1,1]
	v_lshlrev_b32_e32 v108, 16, v98
	v_and_b32_e32 v109, 0xffff0000, v98
	v_pk_fma_f32 v[84:85], v[134:135], v[108:109], v[84:85] op_sel_hi:[0,1,1]
	v_lshlrev_b32_e32 v186, 16, v102
	v_and_b32_e32 v187, 0xffff0000, v102
	v_pk_fma_f32 v[84:85], v[140:141], v[186:187], v[84:85] op_sel_hi:[0,1,1]
	v_lshlrev_b32_e32 v178, 16, v106
	v_and_b32_e32 v179, 0xffff0000, v106
	v_pk_fma_f32 v[84:85], v[142:143], v[178:179], v[84:85] op_sel_hi:[0,1,1]
	v_lshlrev_b32_e32 v174, 16, v110
	v_and_b32_e32 v175, 0xffff0000, v110
	v_pk_fma_f32 v[96:97], v[144:145], v[174:175], v[84:85] op_sel_hi:[0,1,1]
	v_lshlrev_b32_e32 v84, 16, v87
	v_and_b32_e32 v85, 0xffff0000, v87
	v_cmp_ge_i32_e32 vcc, s27, v135
	v_cmp_lt_i32_e64 s[0:1], s27, v156
	v_pk_fma_f32 v[84:85], v[128:129], v[84:85], 0 op_sel_hi:[0,1,0]
	v_lshlrev_b32_e32 v210, 16, v91
	v_and_b32_e32 v211, 0xffff0000, v91
	s_and_b64 s[0:1], vcc, s[0:1]
	v_pk_fma_f32 v[84:85], v[130:131], v[210:211], v[84:85] op_sel_hi:[0,1,1]
	v_lshlrev_b32_e32 v202, 16, v95
	v_and_b32_e32 v203, 0xffff0000, v95
	v_cndmask_b32_e64 v218, 0, 1.0, s[0:1]
	v_cmp_ge_i32_e32 vcc, s8, v135
	v_cmp_lt_i32_e64 s[0:1], s8, v156
	v_pk_fma_f32 v[84:85], v[132:133], v[202:203], v[84:85] op_sel_hi:[0,1,1]
	v_lshlrev_b32_e32 v194, 16, v99
	v_and_b32_e32 v195, 0xffff0000, v99
	s_and_b64 s[0:1], vcc, s[0:1]
	v_pk_fma_f32 v[84:85], v[134:135], v[194:195], v[84:85] op_sel_hi:[0,1,1]
	v_cndmask_b32_e64 v134, 0, 1.0, s[0:1]
	v_cmp_ge_i32_e32 vcc, s26, v135
	v_cmp_lt_i32_e64 s[0:1], s26, v156
	s_and_b64 s[0:1], vcc, s[0:1]
	v_cmp_ge_i32_e32 vcc, s23, v135
	v_cndmask_b32_e64 v214, 0, 1.0, s[0:1]
	v_cmp_lt_i32_e64 s[0:1], s23, v156
	s_and_b64 s[0:1], vcc, s[0:1]
	v_cmp_ge_i32_e32 vcc, s22, v135
	v_cndmask_b32_e64 v216, 0, 1.0, s[0:1]
	v_cmp_lt_i32_e64 s[0:1], s22, v156
	s_and_b64 s[0:1], vcc, s[0:1]
	v_lshlrev_b32_e32 v188, 16, v103
	v_and_b32_e32 v189, 0xffff0000, v103
	v_cndmask_b32_e64 v110, 0, 1.0, s[0:1]
	v_cmp_ge_i32_e32 vcc, s21, v135
	v_cmp_lt_i32_e64 s[0:1], s21, v156
	v_pk_fma_f32 v[84:85], v[140:141], v[188:189], v[84:85] op_sel_hi:[0,1,1]
	v_lshlrev_b32_e32 v180, 16, v107
	v_and_b32_e32 v181, 0xffff0000, v107
	s_and_b64 s[0:1], vcc, s[0:1]
	v_pk_fma_f32 v[84:85], v[142:143], v[180:181], v[84:85] op_sel_hi:[0,1,1]
	v_lshlrev_b32_e32 v176, 16, v111
	v_and_b32_e32 v177, 0xffff0000, v111
	v_cndmask_b32_e64 v212, 0, 1.0, s[0:1]
	v_cmp_ge_i32_e32 vcc, s20, v135
	v_cmp_lt_i32_e64 s[0:1], s20, v156
	v_pk_fma_f32 v[172:173], v[144:145], v[176:177], v[84:85] op_sel_hi:[0,1,1]
	s_and_b64 s[0:1], vcc, s[0:1]
	v_sub_u32_e32 v84, v156, v135
	s_waitcnt vmcnt(18)
; __device__ __forceinline__ unsigned cvt_pk_bf16(float lo, float hi) { const f32x2 v = (f32x2){lo, hi}; return __builtin_bit_cast(unsigned, __builtin_convertvector(v, bf16v2)); }
; __device__ __forceinline__ float bf_lo(unsigned w) { return __uint_as_float(w << 16); }
; __device__ __forceinline__ float bf_hi(unsigned w) { return __uint_as_float(w & 0xffff0000u); }
; __device__ __forceinline__ void phase_mixer(const Params& p, LAS unsigned char* lds, int l, bool with_ctx, int G, int tid, int wave, int lane, int rep_attn, int rep_pool) {
;     ...
;             for (int i = 0; i < 16; ++i) { const int tt = t + i - 8; const float wt = (tt >= st && tt < en) ? 1.f : 0.f; const u32x4 ww = w[o + i];
;                 acc[0] += wt * bf_lo(ww.x); acc[1] += wt * bf_hi(ww.x); acc[2] += wt * bf_lo(ww.y); acc[3] += wt * bf_hi(ww.y);
;                 acc[4] += wt * bf_lo(ww.z); acc[5] += wt * bf_hi(ww.z); acc[6] += wt * bf_lo(ww.w); acc[7] += wt * bf_hi(ww.w); }
;             const float ic = 1.f / (float)(en - st);
;             const u32x4 sw = w[o + 8];
;             u32x4 ov; ov.x = cvt_pk_bf16(acc[0] * ic - bf_lo(sw.x), acc[1] * ic - bf_hi(sw.x)); ov.y = cvt_pk_bf16(acc[2] * ic - bf_lo(sw.y), acc[3] * ic - bf_hi(sw.y));
;             ov.z = cvt_pk_bf16(acc[4] * ic - bf_lo(sw.z), acc[5] * ic - bf_hi(sw.z)); ov.w = cvt_pk_bf16(acc[6] * ic - bf_lo(sw.w), acc[7] * ic - bf_hi(sw.w));
;             *(u32x4*)(MIX + (size_t)(tok0 + o) * DM + 8 * lane) = ov;
	v_lshlrev_b32_e32 v100, 16, v122
	v_and_b32_e32 v101, 0xffff0000, v122
	v_cndmask_b32_e64 v122, 0, 1.0, s[0:1]
	v_cmp_ge_i32_e32 vcc, s19, v135
	v_cmp_lt_i32_e64 s[0:1], s19, v156
	v_cvt_f32_i32_e32 v84, v84
	s_and_b64 s[0:1], vcc, s[0:1]
	v_lshlrev_b32_e32 v104, 16, v120
	v_and_b32_e32 v105, 0xffff0000, v120
	v_cndmask_b32_e64 v120, 0, 1.0, s[0:1]
	v_cmp_ge_i32_e32 vcc, s10, v135
	v_cmp_lt_i32_e64 s[0:1], s10, v156
	s_and_b64 s[0:1], vcc, s[0:1]
	v_lshlrev_b32_e32 v146, 16, v112
	v_cndmask_b32_e64 v106, 0, 1.0, s[0:1]
	v_div_scale_f32 v85, s[0:1], v84, v84, 1.0
	v_rcp_f32_e32 v86, v85
	v_and_b32_e32 v147, 0xffff0000, v112
	v_lshlrev_b32_e32 v132, 16, v116
	v_and_b32_e32 v133, 0xffff0000, v116
	v_fma_f32 v87, -v85, v86, 1.0
	v_fmac_f32_e32 v86, v87, v86
	v_div_scale_f32 v87, vcc, 1.0, v84, 1.0
	v_mul_f32_e32 v88, v87, v86
	v_fma_f32 v89, -v85, v88, v87
	v_fmac_f32_e32 v88, v89, v86
	v_fma_f32 v85, -v85, v88, v87
	v_div_fmas_f32 v85, v85, v86, v88
	v_div_fixup_f32 v156, v85, v84, 1.0
	v_pk_fma_f32 v[84:85], v[218:219], v[146:147], v[152:153] op_sel_hi:[0,1,1]
	v_lshlrev_b32_e32 v152, 16, v80
	v_and_b32_e32 v153, 0xffff0000, v80
	v_pk_fma_f32 v[84:85], v[134:135], v[152:153], v[84:85] op_sel_hi:[0,1,1]
	v_pk_fma_f32 v[84:85], v[214:215], v[132:133], v[84:85] op_sel_hi:[0,1,1]
	v_lshlrev_b32_e32 v144, 16, v113
	v_and_b32_e32 v145, 0xffff0000, v113
	v_pk_fma_f32 v[84:85], v[216:217], v[104:105], v[84:85] op_sel_hi:[0,1,1]
	s_waitcnt vmcnt(17)
	v_lshlrev_b32_e32 v112, 16, v60
	v_and_b32_e32 v113, 0xffff0000, v60
	v_pk_fma_f32 v[84:85], v[110:111], v[112:113], v[84:85] op_sel_hi:[0,1,1]
	s_waitcnt vmcnt(16)
	v_lshlrev_b32_e32 v92, 16, v64
	v_and_b32_e32 v93, 0xffff0000, v64
	v_pk_fma_f32 v[84:85], v[212:213], v[92:93], v[84:85] op_sel_hi:[0,1,1]
	s_waitcnt vmcnt(15)
	v_lshlrev_b32_e32 v88, 16, v68
	v_and_b32_e32 v89, 0xffff0000, v68
	v_pk_fma_f32 v[84:85], v[122:123], v[88:89], v[84:85] op_sel_hi:[0,1,1]
	s_waitcnt vmcnt(14)
	v_lshlrev_b32_e32 v86, 16, v72
	v_and_b32_e32 v87, 0xffff0000, v72
	v_pk_fma_f32 v[90:91], v[120:121], v[86:87], v[84:85] op_sel_hi:[0,1,1]
	s_waitcnt vmcnt(13)
	v_lshlrev_b32_e32 v84, 16, v76
	v_and_b32_e32 v85, 0xffff0000, v76
	v_pk_fma_f32 v[90:91], v[106:107], v[84:85], v[90:91] op_sel_hi:[0,1,1]
	v_pk_fma_f32 v[90:91], v[156:157], v[90:91], v[152:153] op_sel_hi:[0,1,1] neg_lo:[0,0,1] neg_hi:[0,0,1]
	v_cvt_pk_bf16_f32 v60, v90, v91
	v_pk_fma_f32 v[90:91], v[218:219], v[144:145], v[154:155] op_sel_hi:[0,1,1]
	v_lshlrev_b32_e32 v154, 16, v81
	v_and_b32_e32 v155, 0xffff0000, v81
	v_lshlrev_b32_e32 v130, 16, v117
	v_and_b32_e32 v131, 0xffff0000, v117
	v_pk_fma_f32 v[80:81], v[134:135], v[154:155], v[90:91] op_sel_hi:[0,1,1]
	v_lshlrev_b32_e32 v102, 16, v121
	v_and_b32_e32 v103, 0xffff0000, v121
	v_pk_fma_f32 v[80:81], v[214:215], v[130:131], v[80:81] op_sel_hi:[0,1,1]
	v_lshlrev_b32_e32 v142, 16, v114
	v_and_b32_e32 v143, 0xffff0000, v114
	v_lshlrev_b32_e32 v140, 16, v115
	v_and_b32_e32 v141, 0xffff0000, v115
	v_pk_fma_f32 v[80:81], v[216:217], v[102:103], v[80:81] op_sel_hi:[0,1,1]
	v_lshlrev_b32_e32 v114, 16, v61
	v_and_b32_e32 v115, 0xffff0000, v61
	v_pk_fma_f32 v[80:81], v[110:111], v[114:115], v[80:81] op_sel_hi:[0,1,1]
	v_lshlrev_b32_e32 v94, 16, v65
	v_and_b32_e32 v95, 0xffff0000, v65
	v_pk_fma_f32 v[64:65], v[212:213], v[94:95], v[80:81] op_sel_hi:[0,1,1]
	v_lshlrev_b32_e32 v80, 16, v69
	v_and_b32_e32 v81, 0xffff0000, v69
	v_pk_fma_f32 v[64:65], v[122:123], v[80:81], v[64:65] op_sel_hi:[0,1,1]
	v_lshlrev_b32_e32 v72, 16, v73
	v_and_b32_e32 v73, 0xffff0000, v73
	v_pk_fma_f32 v[68:69], v[120:121], v[72:73], v[64:65] op_sel_hi:[0,1,1]
	v_lshlrev_b32_e32 v64, 16, v77
	v_and_b32_e32 v65, 0xffff0000, v77
	v_pk_fma_f32 v[68:69], v[106:107], v[64:65], v[68:69] op_sel_hi:[0,1,1]
	v_pk_fma_f32 v[68:69], v[156:157], v[68:69], v[154:155] op_sel_hi:[0,1,1] neg_lo:[0,0,1] neg_hi:[0,0,1]
	v_cvt_pk_bf16_f32 v61, v68, v69
	v_pk_fma_f32 v[68:69], v[218:219], v[142:143], v[96:97] op_sel_hi:[0,1,1]
	v_lshlrev_b32_e32 v170, 16, v82
	v_and_b32_e32 v171, 0xffff0000, v82
	v_lshlrev_b32_e32 v128, 16, v118
	v_and_b32_e32 v129, 0xffff0000, v118
	v_pk_fma_f32 v[68:69], v[134:135], v[170:171], v[68:69] op_sel_hi:[0,1,1]
	v_pk_fma_f32 v[68:69], v[214:215], v[128:129], v[68:69] op_sel_hi:[0,1,1]
	v_pk_fma_f32 v[68:69], v[216:217], v[100:101], v[68:69] op_sel_hi:[0,1,1]
	v_lshlrev_b32_e32 v116, 16, v62
	v_and_b32_e32 v117, 0xffff0000, v62
	v_pk_fma_f32 v[68:69], v[110:111], v[116:117], v[68:69] op_sel_hi:[0,1,1]
	v_lshlrev_b32_e32 v96, 16, v66
	v_and_b32_e32 v97, 0xffff0000, v66
	v_pk_fma_f32 v[68:69], v[212:213], v[96:97], v[68:69] op_sel_hi:[0,1,1]
	v_lshlrev_b32_e32 v90, 16, v70
	v_and_b32_e32 v91, 0xffff0000, v70
	v_pk_fma_f32 v[68:69], v[122:123], v[90:91], v[68:69] op_sel_hi:[0,1,1]
	v_lshlrev_b32_e32 v76, 16, v74
	v_and_b32_e32 v77, 0xffff0000, v74
	v_pk_fma_f32 v[224:225], v[120:121], v[76:77], v[68:69] op_sel_hi:[0,1,1]
	v_lshlrev_b32_e32 v68, 16, v78
	v_and_b32_e32 v69, 0xffff0000, v78
	v_pk_fma_f32 v[224:225], v[106:107], v[68:69], v[224:225] op_sel_hi:[0,1,1]
	v_pk_fma_f32 v[224:225], v[156:157], v[224:225], v[170:171] op_sel_hi:[0,1,1] neg_lo:[0,0,1] neg_hi:[0,0,1]
	v_cvt_pk_bf16_f32 v62, v224, v225
	v_pk_fma_f32 v[224:225], v[218:219], v[140:141], v[172:173] op_sel_hi:[0,1,1]
	v_lshlrev_b32_e32 v172, 16, v83
	v_and_b32_e32 v173, 0xffff0000, v83
	v_lshlrev_b32_e32 v118, 16, v119
	v_and_b32_e32 v119, 0xffff0000, v119
	v_pk_fma_f32 v[82:83], v[134:135], v[172:173], v[224:225] op_sel_hi:[0,1,1]
	v_lshlrev_b32_e32 v98, 16, v123
	v_and_b32_e32 v99, 0xffff0000, v123
	v_pk_fma_f32 v[82:83], v[214:215], v[118:119], v[82:83] op_sel_hi:[0,1,1]
	v_pk_fma_f32 v[82:83], v[216:217], v[98:99], v[82:83] op_sel_hi:[0,1,1]
	v_lshlrev_b32_e32 v134, 16, v63
	v_and_b32_e32 v135, 0xffff0000, v63
	v_pk_fma_f32 v[82:83], v[110:111], v[134:135], v[82:83] op_sel_hi:[0,1,1]
	v_lshlrev_b32_e32 v110, 16, v67
	v_and_b32_e32 v111, 0xffff0000, v67
	v_pk_fma_f32 v[66:67], v[212:213], v[110:111], v[82:83] op_sel_hi:[0,1,1]
	v_lshlrev_b32_e32 v82, 16, v71
	v_and_b32_e32 v83, 0xffff0000, v71
	v_pk_fma_f32 v[66:67], v[122:123], v[82:83], v[66:67] op_sel_hi:[0,1,1]
	v_lshlrev_b32_e32 v70, 16, v75
	v_and_b32_e32 v71, 0xffff0000, v75
	v_pk_fma_f32 v[74:75], v[120:121], v[70:71], v[66:67] op_sel_hi:[0,1,1]
	v_lshlrev_b32_e32 v66, 16, v79
	v_and_b32_e32 v67, 0xffff0000, v79
	global_load_dwordx4 v[4:7], v[0:1], off
	v_mad_i64_i32 v[0:1], s[62:63], s5, v223, v[124:125]
	v_pk_fma_f32 v[74:75], v[106:107], v[66:67], v[74:75] op_sel_hi:[0,1,1]
	s_ashr_i32 s5, s4, 31
	v_pk_fma_f32 v[74:75], v[156:157], v[74:75], v[172:173] op_sel_hi:[0,1,1] neg_lo:[0,0,1] neg_hi:[0,0,1]
	s_lshl_b64 s[0:1], s[4:5], 11
	v_cvt_pk_bf16_f32 v63, v74, v75
	v_lshl_add_u64 v[74:75], v[126:127], 0, s[0:1]
	global_load_dwordx4 v[0:3], v[0:1], off
	s_add_i32 s5, s8, 16
	global_store_dwordx4 v[74:75], v[60:63], off
	s_cmpk_lg_u32 s52, 0x800
	s_cbranch_scc1 .Lpool_std
; __device__ __forceinline__ unsigned cvt_pk_bf16(float lo, float hi) { const f32x2 v = (f32x2){lo, hi}; return __builtin_bit_cast(unsigned, __builtin_convertvector(v, bf16v2)); }
; __device__ __forceinline__ float bf_lo(unsigned w) { return __uint_as_float(w << 16); }
; __device__ __forceinline__ float bf_hi(unsigned w) { return __uint_as_float(w & 0xffff0000u); }
; __device__ __forceinline__ void phase_mixer(const Params& p, LAS unsigned char* lds, int l, bool with_ctx, int G, int tid, int wave, int lane, int rep_attn, int rep_pool) {
;     ...
;     for (int rp = 0; rp < rep_pool; ++rp)
; #pragma unroll 1
;     for (int run = gw; run < nrun; run += NGW) {
;         const int tok0 = run * 16; const bool isl = tok0 < ML;
;         const int base = isl ? (tok0 & ~(SEQ - 1)) : (ML + ((tok0 - ML) & ~(CT - 1))), len = isl ? SEQ : CT, t0 = tok0 - base;
;         u32x4 w[31];
; #pragma unroll
;         for (int i = 0; i < 31; ++i) { const int tt = min(max(t0 - 8 + i, 0), len - 1); w[i] = *(const u32x4*)(PB + (size_t)(base + tt) * PBW + 8 * lane); }
; #pragma unroll
;         for (int o = 0; o < 16; ++o) {
;             const int t = t0 + o, st = max(t - lo, 0), en = min(t + hi + 1, len);
;             float acc[8];
; #pragma unroll
;             for (int e = 0; e < 8; ++e) acc[e] = 0.f;
; #pragma unroll
;             for (int i = 0; i < 16; ++i) { const int tt = t + i - 8; const float wt = (tt >= st && tt < en) ? 1.f : 0.f; const u32x4 ww = w[o + i];
;                 acc[0] += wt * bf_lo(ww.x); acc[1] += wt * bf_hi(ww.x); acc[2] += wt * bf_lo(ww.y); acc[3] += wt * bf_hi(ww.y);
;                 acc[4] += wt * bf_lo(ww.z); acc[5] += wt * bf_hi(ww.z); acc[6] += wt * bf_lo(ww.w); acc[7] += wt * bf_hi(ww.w); }
;             const float ic = 1.f / (float)(en - st);
;             const u32x4 sw = w[o + 8];
;             u32x4 ov; ov.x = cvt_pk_bf16(acc[0] * ic - bf_lo(sw.x), acc[1] * ic - bf_hi(sw.x)); ov.y = cvt_pk_bf16(acc[2] * ic - bf_lo(sw.y), acc[3] * ic - bf_hi(sw.y));
;             ov.z = cvt_pk_bf16(acc[4] * ic - bf_lo(sw.z), acc[5] * ic - bf_hi(sw.z)); ov.w = cvt_pk_bf16(acc[6] * ic - bf_lo(sw.w), acc[7] * ic - bf_hi(sw.w));
;             *(u32x4*)(MIX + (size_t)(tok0 + o) * DM + 8 * lane) = ov;
	s_cmpk_ge_i32 s6, 0x800
	s_cbranch_scc1 .Lpool_last
	s_and_b32 s32, s6, 0x407
	s_cmpk_eq_i32 s32, 0x400
	s_cbranch_scc0 .Lpool_last
	s_sub_i32 s6, s6, 0x400
	s_lshr_b32 s6, s6, 3
	s_add_i32 s6, s6, 0x800
	s_branch .Lpool_next_done
.Lpool_last:
	s_mov_b32 s6, 0x7fffffff
	s_branch .Lpool_next_done
.Lpool_std:
	s_add_i32 s6, s6, s52
.Lpool_next_done:
	s_nop 0
	v_sub_u32_e32 v60, s26, v167
	v_add_u32_e32 v61, s26, v167
	v_max_i32_e32 v75, 0, v60
	v_min_i32_e32 v79, s9, v61
	v_cmp_ge_i32_e32 vcc, s33, v75
	v_cmp_lt_i32_e64 s[0:1], s33, v79
	s_and_b64 s[0:1], vcc, s[0:1]
	v_cmp_ge_i32_e32 vcc, s25, v75
	v_cndmask_b32_e64 v60, 0, 1.0, s[0:1]
	v_cmp_lt_i32_e64 s[0:1], s25, v79
	s_and_b64 s[0:1], vcc, s[0:1]
	v_cmp_ge_i32_e32 vcc, s24, v75
	v_cndmask_b32_e64 v74, 0, 1.0, s[0:1]
	v_cmp_lt_i32_e64 s[0:1], s24, v79
	s_and_b64 s[0:1], vcc, s[0:1]
	v_cmp_ge_i32_e32 vcc, s30, v75
	v_cndmask_b32_e64 v78, 0, 1.0, s[0:1]
	v_cmp_lt_i32_e64 s[0:1], s30, v79
	s_and_b64 s[0:1], vcc, s[0:1]
	v_cmp_ge_i32_e32 vcc, s29, v75
	v_cndmask_b32_e64 v106, 0, 1.0, s[0:1]
	v_cmp_lt_i32_e64 s[0:1], s29, v79
	s_and_b64 s[0:1], vcc, s[0:1]
	v_pk_fma_f32 v[62:63], v[60:61], v[204:205], 0 op_sel_hi:[0,1,0]
	v_cndmask_b32_e64 v120, 0, 1.0, s[0:1]
	v_cmp_ge_i32_e32 vcc, s28, v75
	v_cmp_lt_i32_e64 s[0:1], s28, v79
	v_pk_fma_f32 v[62:63], v[74:75], v[196:197], v[62:63] op_sel_hi:[0,1,1]
	s_and_b64 s[0:1], vcc, s[0:1]
	v_pk_fma_f32 v[62:63], v[78:79], v[190:191], v[62:63] op_sel_hi:[0,1,1]
	v_cndmask_b32_e64 v122, 0, 1.0, s[0:1]
	v_cmp_ge_i32_e32 vcc, s27, v75
	v_cmp_lt_i32_e64 s[0:1], s27, v79
	v_pk_fma_f32 v[62:63], v[106:107], v[182:183], v[62:63] op_sel_hi:[0,1,1]
	s_and_b64 s[0:1], vcc, s[0:1]
	v_pk_fma_f32 v[62:63], v[120:121], v[136:137], v[62:63] op_sel_hi:[0,1,1]
	v_cndmask_b32_e64 v156, 0, 1.0, s[0:1]
	v_pk_fma_f32 v[62:63], v[122:123], v[148:149], v[62:63] op_sel_hi:[0,1,1]
	v_pk_fma_f32 v[216:217], v[156:157], v[146:147], v[62:63] op_sel_hi:[0,1,1]
	v_pk_fma_f32 v[62:63], v[60:61], v[206:207], 0 op_sel_hi:[0,1,0]
	v_pk_fma_f32 v[62:63], v[74:75], v[198:199], v[62:63] op_sel_hi:[0,1,1]
	v_pk_fma_f32 v[62:63], v[78:79], v[192:193], v[62:63] op_sel_hi:[0,1,1]
	v_pk_fma_f32 v[62:63], v[106:107], v[184:185], v[62:63] op_sel_hi:[0,1,1]
	v_pk_fma_f32 v[62:63], v[120:121], v[138:139], v[62:63] op_sel_hi:[0,1,1]
	v_pk_fma_f32 v[62:63], v[122:123], v[150:151], v[62:63] op_sel_hi:[0,1,1]
	v_pk_fma_f32 v[214:215], v[156:157], v[144:145], v[62:63] op_sel_hi:[0,1,1]
	v_pk_fma_f32 v[62:63], v[60:61], v[208:209], 0 op_sel_hi:[0,1,0]
	v_pk_fma_f32 v[60:61], v[60:61], v[210:211], 0 op_sel_hi:[0,1,0]
	v_pk_fma_f32 v[62:63], v[74:75], v[200:201], v[62:63] op_sel_hi:[0,1,1]
	v_pk_fma_f32 v[60:61], v[74:75], v[202:203], v[60:61] op_sel_hi:[0,1,1]
	v_pk_fma_f32 v[62:63], v[78:79], v[108:109], v[62:63] op_sel_hi:[0,1,1]
	v_pk_fma_f32 v[60:61], v[78:79], v[194:195], v[60:61] op_sel_hi:[0,1,1]
	v_cmp_ge_i32_e32 vcc, s8, v75
	v_cmp_lt_i32_e64 s[0:1], s8, v79
	v_pk_fma_f32 v[62:63], v[106:107], v[186:187], v[62:63] op_sel_hi:[0,1,1]
	v_pk_fma_f32 v[60:61], v[106:107], v[188:189], v[60:61] op_sel_hi:[0,1,1]
	s_and_b64 s[0:1], vcc, s[0:1]
	v_pk_fma_f32 v[62:63], v[120:121], v[178:179], v[62:63] op_sel_hi:[0,1,1]
	v_pk_fma_f32 v[60:61], v[120:121], v[180:181], v[60:61] op_sel_hi:[0,1,1]
	v_cndmask_b32_e64 v120, 0, 1.0, s[0:1]
	v_cmp_ge_i32_e32 vcc, s26, v75
	v_cmp_lt_i32_e64 s[0:1], s26, v79
	s_and_b64 s[0:1], vcc, s[0:1]
	v_pk_fma_f32 v[62:63], v[122:123], v[174:175], v[62:63] op_sel_hi:[0,1,1]
	v_pk_fma_f32 v[60:61], v[122:123], v[176:177], v[60:61] op_sel_hi:[0,1,1]
	v_cndmask_b32_e64 v122, 0, 1.0, s[0:1]
	v_cmp_ge_i32_e32 vcc, s23, v75
	v_cmp_lt_i32_e64 s[0:1], s23, v79
	s_and_b64 s[0:1], vcc, s[0:1]
	v_pk_fma_f32 v[62:63], v[156:157], v[142:143], v[62:63] op_sel_hi:[0,1,1]
	v_pk_fma_f32 v[106:107], v[156:157], v[140:141], v[60:61] op_sel_hi:[0,1,1]
	v_cndmask_b32_e64 v156, 0, 1.0, s[0:1]
	v_cmp_ge_i32_e32 vcc, s22, v75
	v_cmp_lt_i32_e64 s[0:1], s22, v79
	s_and_b64 s[0:1], vcc, s[0:1]
	v_cmp_ge_i32_e32 vcc, s21, v75
	v_cndmask_b32_e64 v204, 0, 1.0, s[0:1]
	v_cmp_lt_i32_e64 s[0:1], s21, v79
	s_and_b64 s[0:1], vcc, s[0:1]
	v_cmp_ge_i32_e32 vcc, s20, v75
	v_cndmask_b32_e64 v206, 0, 1.0, s[0:1]
	v_cmp_lt_i32_e64 s[0:1], s20, v79
	s_and_b64 s[0:1], vcc, s[0:1]
	v_cmp_ge_i32_e32 vcc, s19, v75
	v_cndmask_b32_e64 v208, 0, 1.0, s[0:1]
	v_cmp_lt_i32_e64 s[0:1], s19, v79
	s_and_b64 s[0:1], vcc, s[0:1]
	v_sub_u32_e32 v60, v79, v75
	v_cndmask_b32_e64 v210, 0, 1.0, s[0:1]
	v_cmp_ge_i32_e32 vcc, s10, v75
	v_cmp_lt_i32_e64 s[0:1], s10, v79
	v_cvt_f32_i32_e32 v60, v60
	s_and_b64 s[0:1], vcc, s[0:1]
	v_cndmask_b32_e64 v212, 0, 1.0, s[0:1]
	v_cmp_ge_i32_e32 vcc, s11, v75
	v_cmp_lt_i32_e64 s[0:1], s11, v79
	s_and_b64 s[0:1], vcc, s[0:1]
	s_nop 0
	v_cndmask_b32_e64 v74, 0, 1.0, s[0:1]
	v_div_scale_f32 v61, s[0:1], v60, v60, 1.0
	v_rcp_f32_e32 v75, v61
	s_or_b32 s0, s4, 1
	s_ashr_i32 s1, s0, 31
	s_lshl_b64 s[0:1], s[0:1], 11
	v_fma_f32 v78, -v61, v75, 1.0
	v_fmac_f32_e32 v75, v78, v75
	v_div_scale_f32 v78, vcc, 1.0, v60, 1.0
	v_mul_f32_e32 v79, v78, v75
	v_fma_f32 v121, -v61, v79, v78
	v_fmac_f32_e32 v79, v121, v75
	v_fma_f32 v61, -v61, v79, v78
	v_div_fmas_f32 v61, v61, v75, v79
	v_div_fixup_f32 v78, v61, v60, 1.0
	v_pk_fma_f32 v[60:61], v[120:121], v[152:153], v[216:217] op_sel_hi:[0,1,1]
	v_pk_fma_f32 v[214:215], v[120:121], v[154:155], v[214:215] op_sel_hi:[0,1,1]
	v_pk_fma_f32 v[60:61], v[122:123], v[132:133], v[60:61] op_sel_hi:[0,1,1]
	v_pk_fma_f32 v[214:215], v[122:123], v[130:131], v[214:215] op_sel_hi:[0,1,1]
	v_pk_fma_f32 v[60:61], v[156:157], v[104:105], v[60:61] op_sel_hi:[0,1,1]
	v_pk_fma_f32 v[214:215], v[156:157], v[102:103], v[214:215] op_sel_hi:[0,1,1]
	v_pk_fma_f32 v[60:61], v[204:205], v[112:113], v[60:61] op_sel_hi:[0,1,1]
	v_pk_fma_f32 v[214:215], v[204:205], v[114:115], v[214:215] op_sel_hi:[0,1,1]
	v_pk_fma_f32 v[62:63], v[120:121], v[170:171], v[62:63] op_sel_hi:[0,1,1]
	v_pk_fma_f32 v[106:107], v[120:121], v[172:173], v[106:107] op_sel_hi:[0,1,1]
	v_pk_fma_f32 v[60:61], v[206:207], v[92:93], v[60:61] op_sel_hi:[0,1,1]
	v_pk_fma_f32 v[214:215], v[206:207], v[94:95], v[214:215] op_sel_hi:[0,1,1]
	v_pk_fma_f32 v[62:63], v[122:123], v[128:129], v[62:63] op_sel_hi:[0,1,1]
	v_pk_fma_f32 v[106:107], v[122:123], v[118:119], v[106:107] op_sel_hi:[0,1,1]
	v_pk_fma_f32 v[60:61], v[208:209], v[88:89], v[60:61] op_sel_hi:[0,1,1]
	v_pk_fma_f32 v[214:215], v[208:209], v[80:81], v[214:215] op_sel_hi:[0,1,1]
	v_pk_fma_f32 v[62:63], v[156:157], v[100:101], v[62:63] op_sel_hi:[0,1,1]
	v_pk_fma_f32 v[106:107], v[156:157], v[98:99], v[106:107] op_sel_hi:[0,1,1]
	v_pk_fma_f32 v[60:61], v[210:211], v[86:87], v[60:61] op_sel_hi:[0,1,1]
	v_pk_fma_f32 v[214:215], v[210:211], v[72:73], v[214:215] op_sel_hi:[0,1,1]
	v_pk_fma_f32 v[62:63], v[204:205], v[116:117], v[62:63] op_sel_hi:[0,1,1]
	v_pk_fma_f32 v[106:107], v[204:205], v[134:135], v[106:107] op_sel_hi:[0,1,1]
	v_pk_fma_f32 v[216:217], v[212:213], v[84:85], v[60:61] op_sel_hi:[0,1,1]
	s_waitcnt vmcnt(15)
; __device__ __forceinline__ unsigned cvt_pk_bf16(float lo, float hi) { const f32x2 v = (f32x2){lo, hi}; return __builtin_bit_cast(unsigned, __builtin_convertvector(v, bf16v2)); }
; __device__ __forceinline__ float bf_lo(unsigned w) { return __uint_as_float(w << 16); }
; __device__ __forceinline__ float bf_hi(unsigned w) { return __uint_as_float(w & 0xffff0000u); }
; __device__ __forceinline__ void phase_mixer(const Params& p, LAS unsigned char* lds, int l, bool with_ctx, int G, int tid, int wave, int lane, int rep_attn, int rep_pool) {
;     ...
;         for (int o = 0; o < 16; ++o) {
;             const int t = t0 + o, st = max(t - lo, 0), en = min(t + hi + 1, len);
;             float acc[8];
; #pragma unroll
;             for (int e = 0; e < 8; ++e) acc[e] = 0.f;
; #pragma unroll
;             for (int i = 0; i < 16; ++i) { const int tt = t + i - 8; const float wt = (tt >= st && tt < en) ? 1.f : 0.f; const u32x4 ww = w[o + i];
;                 acc[0] += wt * bf_lo(ww.x); acc[1] += wt * bf_hi(ww.x); acc[2] += wt * bf_lo(ww.y); acc[3] += wt * bf_hi(ww.y);
;                 acc[4] += wt * bf_lo(ww.z); acc[5] += wt * bf_hi(ww.z); acc[6] += wt * bf_lo(ww.w); acc[7] += wt * bf_hi(ww.w); }
;             const float ic = 1.f / (float)(en - st);
;             const u32x4 sw = w[o + 8];
;             u32x4 ov; ov.x = cvt_pk_bf16(acc[0] * ic - bf_lo(sw.x), acc[1] * ic - bf_hi(sw.x)); ov.y = cvt_pk_bf16(acc[2] * ic - bf_lo(sw.y), acc[3] * ic - bf_hi(sw.y));
;             ov.z = cvt_pk_bf16(acc[4] * ic - bf_lo(sw.z), acc[5] * ic - bf_hi(sw.z)); ov.w = cvt_pk_bf16(acc[6] * ic - bf_lo(sw.w), acc[7] * ic - bf_hi(sw.w));
;             *(u32x4*)(MIX + (size_t)(tok0 + o) * DM + 8 * lane) = ov;
	v_lshlrev_b32_e32 v60, 16, v56
	v_and_b32_e32 v61, 0xffff0000, v56
	v_pk_fma_f32 v[214:215], v[212:213], v[64:65], v[214:215] op_sel_hi:[0,1,1]
	v_lshlrev_b32_e32 v56, 16, v57
	v_and_b32_e32 v57, 0xffff0000, v57
	v_pk_fma_f32 v[62:63], v[206:207], v[96:97], v[62:63] op_sel_hi:[0,1,1]
	v_pk_fma_f32 v[106:107], v[206:207], v[110:111], v[106:107] op_sel_hi:[0,1,1]
	v_pk_fma_f32 v[214:215], v[74:75], v[56:57], v[214:215] op_sel_hi:[0,1,1]
	v_pk_fma_f32 v[62:63], v[208:209], v[90:91], v[62:63] op_sel_hi:[0,1,1]
	v_pk_fma_f32 v[106:107], v[208:209], v[82:83], v[106:107] op_sel_hi:[0,1,1]
	v_pk_fma_f32 v[214:215], v[78:79], v[214:215], v[130:131] op_sel_hi:[0,1,1] neg_lo:[0,0,1] neg_hi:[0,0,1]
	v_pk_fma_f32 v[62:63], v[210:211], v[76:77], v[62:63] op_sel_hi:[0,1,1]
	v_pk_fma_f32 v[106:107], v[210:211], v[70:71], v[106:107] op_sel_hi:[0,1,1]
	v_cvt_pk_bf16_f32 v225, v214, v215
	v_pk_fma_f32 v[214:215], v[212:213], v[68:69], v[62:63] op_sel_hi:[0,1,1]
	v_lshlrev_b32_e32 v62, 16, v58
	v_and_b32_e32 v63, 0xffff0000, v58
	v_pk_fma_f32 v[106:107], v[212:213], v[66:67], v[106:107] op_sel_hi:[0,1,1]
	v_lshlrev_b32_e32 v58, 16, v59
	v_and_b32_e32 v59, 0xffff0000, v59
	v_pk_fma_f32 v[216:217], v[74:75], v[60:61], v[216:217] op_sel_hi:[0,1,1]
	v_pk_fma_f32 v[214:215], v[74:75], v[62:63], v[214:215] op_sel_hi:[0,1,1]
	v_pk_fma_f32 v[74:75], v[74:75], v[58:59], v[106:107] op_sel_hi:[0,1,1]
	v_pk_fma_f32 v[216:217], v[78:79], v[216:217], v[132:133] op_sel_hi:[0,1,1] neg_lo:[0,0,1] neg_hi:[0,0,1]
	v_pk_fma_f32 v[214:215], v[78:79], v[214:215], v[128:129] op_sel_hi:[0,1,1] neg_lo:[0,0,1] neg_hi:[0,0,1]
	v_pk_fma_f32 v[74:75], v[78:79], v[74:75], v[118:119] op_sel_hi:[0,1,1] neg_lo:[0,0,1] neg_hi:[0,0,1]
	v_cvt_pk_bf16_f32 v224, v216, v217
	v_cvt_pk_bf16_f32 v226, v214, v215
	v_cvt_pk_bf16_f32 v227, v74, v75
	v_lshl_add_u64 v[74:75], v[126:127], 0, s[0:1]
	global_store_dwordx4 v[74:75], v[224:227], off
	v_sub_u32_e32 v74, s23, v167
	v_add_u32_e32 v75, s23, v167
	v_max_i32_e32 v107, 0, v74
	v_min_i32_e32 v121, s9, v75
	v_cmp_ge_i32_e32 vcc, s25, v107
	v_cmp_lt_i32_e64 s[0:1], s25, v121
	s_and_b64 s[0:1], vcc, s[0:1]
	v_cmp_ge_i32_e32 vcc, s24, v107
	v_cndmask_b32_e64 v74, 0, 1.0, s[0:1]
	v_cmp_lt_i32_e64 s[0:1], s24, v121
	s_and_b64 s[0:1], vcc, s[0:1]
	v_cmp_ge_i32_e32 vcc, s30, v107
	v_cndmask_b32_e64 v106, 0, 1.0, s[0:1]
	v_cmp_lt_i32_e64 s[0:1], s30, v121
	s_and_b64 s[0:1], vcc, s[0:1]
	v_cmp_ge_i32_e32 vcc, s29, v107
	v_cndmask_b32_e64 v120, 0, 1.0, s[0:1]
	v_cmp_lt_i32_e64 s[0:1], s29, v121
	s_and_b64 s[0:1], vcc, s[0:1]
	v_cmp_ge_i32_e32 vcc, s28, v107
	v_cndmask_b32_e64 v122, 0, 1.0, s[0:1]
	v_cmp_lt_i32_e64 s[0:1], s28, v121
	s_and_b64 s[0:1], vcc, s[0:1]
	v_pk_fma_f32 v[78:79], v[74:75], v[196:197], 0 op_sel_hi:[0,1,0]
	v_cndmask_b32_e64 v156, 0, 1.0, s[0:1]
	v_cmp_ge_i32_e32 vcc, s27, v107
	v_cmp_lt_i32_e64 s[0:1], s27, v121
	v_pk_fma_f32 v[78:79], v[106:107], v[190:191], v[78:79] op_sel_hi:[0,1,1]
	s_and_b64 s[0:1], vcc, s[0:1]
	v_pk_fma_f32 v[78:79], v[120:121], v[182:183], v[78:79] op_sel_hi:[0,1,1]
	v_cndmask_b32_e64 v204, 0, 1.0, s[0:1]
	v_cmp_ge_i32_e32 vcc, s8, v107
	v_cmp_lt_i32_e64 s[0:1], s8, v121
	v_pk_fma_f32 v[78:79], v[122:123], v[136:137], v[78:79] op_sel_hi:[0,1,1]
	s_and_b64 s[0:1], vcc, s[0:1]
	v_pk_fma_f32 v[78:79], v[156:157], v[148:149], v[78:79] op_sel_hi:[0,1,1]
	v_cndmask_b32_e64 v206, 0, 1.0, s[0:1]
	v_pk_fma_f32 v[78:79], v[204:205], v[146:147], v[78:79] op_sel_hi:[0,1,1]
	v_pk_fma_f32 v[212:213], v[206:207], v[152:153], v[78:79] op_sel_hi:[0,1,1]
	v_pk_fma_f32 v[78:79], v[74:75], v[198:199], 0 op_sel_hi:[0,1,0]
	v_pk_fma_f32 v[78:79], v[106:107], v[192:193], v[78:79] op_sel_hi:[0,1,1]
	v_pk_fma_f32 v[78:79], v[120:121], v[184:185], v[78:79] op_sel_hi:[0,1,1]
	v_pk_fma_f32 v[78:79], v[122:123], v[138:139], v[78:79] op_sel_hi:[0,1,1]
	v_pk_fma_f32 v[78:79], v[156:157], v[150:151], v[78:79] op_sel_hi:[0,1,1]
	v_pk_fma_f32 v[78:79], v[204:205], v[144:145], v[78:79] op_sel_hi:[0,1,1]
	v_pk_fma_f32 v[210:211], v[206:207], v[154:155], v[78:79] op_sel_hi:[0,1,1]
	v_pk_fma_f32 v[78:79], v[74:75], v[200:201], 0 op_sel_hi:[0,1,0]
	v_pk_fma_f32 v[74:75], v[74:75], v[202:203], 0 op_sel_hi:[0,1,0]
	v_pk_fma_f32 v[78:79], v[106:107], v[108:109], v[78:79] op_sel_hi:[0,1,1]
	v_pk_fma_f32 v[74:75], v[106:107], v[194:195], v[74:75] op_sel_hi:[0,1,1]
	v_pk_fma_f32 v[78:79], v[120:121], v[186:187], v[78:79] op_sel_hi:[0,1,1]
	v_pk_fma_f32 v[74:75], v[120:121], v[188:189], v[74:75] op_sel_hi:[0,1,1]
	v_cmp_ge_i32_e32 vcc, s26, v107
	v_cmp_lt_i32_e64 s[0:1], s26, v121
	v_pk_fma_f32 v[78:79], v[122:123], v[178:179], v[78:79] op_sel_hi:[0,1,1]
	v_pk_fma_f32 v[74:75], v[122:123], v[180:181], v[74:75] op_sel_hi:[0,1,1]
	s_and_b64 s[0:1], vcc, s[0:1]
	v_pk_fma_f32 v[78:79], v[156:157], v[174:175], v[78:79] op_sel_hi:[0,1,1]
	v_pk_fma_f32 v[74:75], v[156:157], v[176:177], v[74:75] op_sel_hi:[0,1,1]
	v_cndmask_b32_e64 v156, 0, 1.0, s[0:1]
	v_cmp_ge_i32_e32 vcc, s23, v107
	v_cmp_lt_i32_e64 s[0:1], s23, v121
	s_and_b64 s[0:1], vcc, s[0:1]
	v_cmp_ge_i32_e32 vcc, s22, v107
	v_cndmask_b32_e64 v196, 0, 1.0, s[0:1]
	v_cmp_lt_i32_e64 s[0:1], s22, v121
	s_and_b64 s[0:1], vcc, s[0:1]
	v_cmp_ge_i32_e32 vcc, s21, v107
	v_cndmask_b32_e64 v198, 0, 1.0, s[0:1]
	v_cmp_lt_i32_e64 s[0:1], s21, v121
	s_and_b64 s[0:1], vcc, s[0:1]
	v_cmp_ge_i32_e32 vcc, s20, v107
	v_cndmask_b32_e64 v200, 0, 1.0, s[0:1]
	v_cmp_lt_i32_e64 s[0:1], s20, v121
	s_and_b64 s[0:1], vcc, s[0:1]
	v_cmp_ge_i32_e32 vcc, s19, v107
	v_cndmask_b32_e64 v202, 0, 1.0, s[0:1]
	v_cmp_lt_i32_e64 s[0:1], s19, v121
	s_and_b64 s[0:1], vcc, s[0:1]
	v_pk_fma_f32 v[78:79], v[204:205], v[142:143], v[78:79] op_sel_hi:[0,1,1]
; __device__ __forceinline__ unsigned cvt_pk_bf16(float lo, float hi) { const f32x2 v = (f32x2){lo, hi}; return __builtin_bit_cast(unsigned, __builtin_convertvector(v, bf16v2)); }
; __device__ __forceinline__ float bf_lo(unsigned w) { return __uint_as_float(w << 16); }
; __device__ __forceinline__ float bf_hi(unsigned w) { return __uint_as_float(w & 0xffff0000u); }
; __device__ __forceinline__ void phase_mixer(const Params& p, LAS unsigned char* lds, int l, bool with_ctx, int G, int tid, int wave, int lane, int rep_attn, int rep_pool) {
;     ...
;         for (int o = 0; o < 16; ++o) {
;             const int t = t0 + o, st = max(t - lo, 0), en = min(t + hi + 1, len);
;             float acc[8];
; #pragma unroll
;             for (int e = 0; e < 8; ++e) acc[e] = 0.f;
; #pragma unroll
;             for (int i = 0; i < 16; ++i) { const int tt = t + i - 8; const float wt = (tt >= st && tt < en) ? 1.f : 0.f; const u32x4 ww = w[o + i];
;                 acc[0] += wt * bf_lo(ww.x); acc[1] += wt * bf_hi(ww.x); acc[2] += wt * bf_lo(ww.y); acc[3] += wt * bf_hi(ww.y);
;                 acc[4] += wt * bf_lo(ww.z); acc[5] += wt * bf_hi(ww.z); acc[6] += wt * bf_lo(ww.w); acc[7] += wt * bf_hi(ww.w); }
;             const float ic = 1.f / (float)(en - st);
;             const u32x4 sw = w[o + 8];
;             u32x4 ov; ov.x = cvt_pk_bf16(acc[0] * ic - bf_lo(sw.x), acc[1] * ic - bf_hi(sw.x)); ov.y = cvt_pk_bf16(acc[2] * ic - bf_lo(sw.y), acc[3] * ic - bf_hi(sw.y));
;             ov.z = cvt_pk_bf16(acc[4] * ic - bf_lo(sw.z), acc[5] * ic - bf_hi(sw.z)); ov.w = cvt_pk_bf16(acc[6] * ic - bf_lo(sw.w), acc[7] * ic - bf_hi(sw.w));
;             *(u32x4*)(MIX + (size_t)(tok0 + o) * DM + 8 * lane) = ov;
	v_pk_fma_f32 v[74:75], v[204:205], v[140:141], v[74:75] op_sel_hi:[0,1,1]
	v_cndmask_b32_e64 v204, 0, 1.0, s[0:1]
	v_cmp_ge_i32_e32 vcc, s10, v107
	v_cmp_lt_i32_e64 s[0:1], s10, v121
	v_pk_fma_f32 v[122:123], v[206:207], v[172:173], v[74:75] op_sel_hi:[0,1,1]
	s_and_b64 s[0:1], vcc, s[0:1]
	v_sub_u32_e32 v74, v121, v107
	v_pk_fma_f32 v[78:79], v[206:207], v[170:171], v[78:79] op_sel_hi:[0,1,1]
	v_cndmask_b32_e64 v206, 0, 1.0, s[0:1]
	v_cmp_ge_i32_e32 vcc, s11, v107
	v_cmp_lt_i32_e64 s[0:1], s11, v121
	v_cvt_f32_i32_e32 v74, v74
	s_and_b64 s[0:1], vcc, s[0:1]
	v_cndmask_b32_e64 v208, 0, 1.0, s[0:1]
	v_cmp_ge_i32_e32 vcc, s12, v107
	v_cmp_lt_i32_e64 s[0:1], s12, v121
	s_and_b64 s[0:1], vcc, s[0:1]
	v_pk_fma_f32 v[210:211], v[156:157], v[130:131], v[210:211] op_sel_hi:[0,1,1]
	v_cndmask_b32_e64 v106, 0, 1.0, s[0:1]
	v_div_scale_f32 v75, s[0:1], v74, v74, 1.0
	v_rcp_f32_e32 v107, v75
	v_pk_fma_f32 v[210:211], v[196:197], v[102:103], v[210:211] op_sel_hi:[0,1,1]
	v_pk_fma_f32 v[210:211], v[198:199], v[114:115], v[210:211] op_sel_hi:[0,1,1]
	v_pk_fma_f32 v[210:211], v[200:201], v[94:95], v[210:211] op_sel_hi:[0,1,1]
	v_fma_f32 v120, -v75, v107, 1.0
	v_fmac_f32_e32 v107, v120, v107
	v_div_scale_f32 v120, vcc, 1.0, v74, 1.0
	v_mul_f32_e32 v121, v120, v107
	v_fma_f32 v160, -v75, v121, v120
	v_fmac_f32_e32 v121, v160, v107
	v_fma_f32 v75, -v75, v121, v120
	v_div_fmas_f32 v75, v75, v107, v121
	v_div_fixup_f32 v120, v75, v74, 1.0
	v_pk_fma_f32 v[74:75], v[156:157], v[132:133], v[212:213] op_sel_hi:[0,1,1]
	v_pk_fma_f32 v[74:75], v[196:197], v[104:105], v[74:75] op_sel_hi:[0,1,1]
	v_pk_fma_f32 v[74:75], v[198:199], v[112:113], v[74:75] op_sel_hi:[0,1,1]
	v_pk_fma_f32 v[74:75], v[200:201], v[92:93], v[74:75] op_sel_hi:[0,1,1]
	v_pk_fma_f32 v[78:79], v[156:157], v[128:129], v[78:79] op_sel_hi:[0,1,1]
	v_pk_fma_f32 v[122:123], v[156:157], v[118:119], v[122:123] op_sel_hi:[0,1,1]
	v_pk_fma_f32 v[74:75], v[202:203], v[88:89], v[74:75] op_sel_hi:[0,1,1]
	v_pk_fma_f32 v[210:211], v[202:203], v[80:81], v[210:211] op_sel_hi:[0,1,1]
	v_pk_fma_f32 v[78:79], v[196:197], v[100:101], v[78:79] op_sel_hi:[0,1,1]
	v_pk_fma_f32 v[122:123], v[196:197], v[98:99], v[122:123] op_sel_hi:[0,1,1]
	v_pk_fma_f32 v[74:75], v[204:205], v[86:87], v[74:75] op_sel_hi:[0,1,1]
	v_pk_fma_f32 v[210:211], v[204:205], v[72:73], v[210:211] op_sel_hi:[0,1,1]
	v_pk_fma_f32 v[78:79], v[198:199], v[116:117], v[78:79] op_sel_hi:[0,1,1]
	v_pk_fma_f32 v[122:123], v[198:199], v[134:135], v[122:123] op_sel_hi:[0,1,1]
	v_pk_fma_f32 v[74:75], v[206:207], v[84:85], v[74:75] op_sel_hi:[0,1,1]
	v_pk_fma_f32 v[210:211], v[206:207], v[64:65], v[210:211] op_sel_hi:[0,1,1]
	v_pk_fma_f32 v[78:79], v[200:201], v[96:97], v[78:79] op_sel_hi:[0,1,1]
	v_pk_fma_f32 v[122:123], v[200:201], v[110:111], v[122:123] op_sel_hi:[0,1,1]
	v_pk_fma_f32 v[212:213], v[208:209], v[60:61], v[74:75] op_sel_hi:[0,1,1]
	s_waitcnt vmcnt(15)
	v_lshlrev_b32_e32 v74, 16, v52
	v_and_b32_e32 v75, 0xffff0000, v52
	v_pk_fma_f32 v[210:211], v[208:209], v[56:57], v[210:211] op_sel_hi:[0,1,1]
	v_lshlrev_b32_e32 v52, 16, v53
	v_and_b32_e32 v53, 0xffff0000, v53
	v_pk_fma_f32 v[78:79], v[202:203], v[90:91], v[78:79] op_sel_hi:[0,1,1]
	v_pk_fma_f32 v[122:123], v[202:203], v[82:83], v[122:123] op_sel_hi:[0,1,1]
	v_pk_fma_f32 v[212:213], v[106:107], v[74:75], v[212:213] op_sel_hi:[0,1,1]
	v_pk_fma_f32 v[210:211], v[106:107], v[52:53], v[210:211] op_sel_hi:[0,1,1]
	v_pk_fma_f32 v[78:79], v[204:205], v[76:77], v[78:79] op_sel_hi:[0,1,1]
	v_pk_fma_f32 v[122:123], v[204:205], v[70:71], v[122:123] op_sel_hi:[0,1,1]
	v_pk_fma_f32 v[212:213], v[120:121], v[212:213], v[104:105] op_sel_hi:[0,1,1] neg_lo:[0,0,1] neg_hi:[0,0,1]
	v_pk_fma_f32 v[210:211], v[120:121], v[210:211], v[102:103] op_sel_hi:[0,1,1] neg_lo:[0,0,1] neg_hi:[0,0,1]
	v_pk_fma_f32 v[78:79], v[206:207], v[68:69], v[78:79] op_sel_hi:[0,1,1]
	v_pk_fma_f32 v[122:123], v[206:207], v[66:67], v[122:123] op_sel_hi:[0,1,1]
	v_cvt_pk_bf16_f32 v212, v212, v213
	v_cvt_pk_bf16_f32 v213, v210, v211
	v_pk_fma_f32 v[210:211], v[208:209], v[62:63], v[78:79] op_sel_hi:[0,1,1]
	v_lshlrev_b32_e32 v78, 16, v54
	v_and_b32_e32 v79, 0xffff0000, v54
	v_pk_fma_f32 v[122:123], v[208:209], v[58:59], v[122:123] op_sel_hi:[0,1,1]
	v_lshlrev_b32_e32 v54, 16, v55
	v_and_b32_e32 v55, 0xffff0000, v55
	s_or_b32 s0, s4, 2
	v_pk_fma_f32 v[210:211], v[106:107], v[78:79], v[210:211] op_sel_hi:[0,1,1]
	v_pk_fma_f32 v[106:107], v[106:107], v[54:55], v[122:123] op_sel_hi:[0,1,1]
	s_ashr_i32 s1, s0, 31
	v_pk_fma_f32 v[210:211], v[120:121], v[210:211], v[100:101] op_sel_hi:[0,1,1] neg_lo:[0,0,1] neg_hi:[0,0,1]
	v_pk_fma_f32 v[106:107], v[120:121], v[106:107], v[98:99] op_sel_hi:[0,1,1] neg_lo:[0,0,1] neg_hi:[0,0,1]
	s_lshl_b64 s[0:1], s[0:1], 11
	v_cvt_pk_bf16_f32 v214, v210, v211
	v_cvt_pk_bf16_f32 v215, v106, v107
	v_lshl_add_u64 v[106:107], v[126:127], 0, s[0:1]
	global_store_dwordx4 v[106:107], v[212:215], off
	v_sub_u32_e32 v106, s22, v167
	v_add_u32_e32 v107, s22, v167
	v_max_i32_e32 v121, 0, v106
	v_min_i32_e32 v123, s9, v107
	v_cmp_ge_i32_e32 vcc, s24, v121
	v_cmp_lt_i32_e64 s[0:1], s24, v123
	s_and_b64 s[0:1], vcc, s[0:1]
	v_cmp_ge_i32_e32 vcc, s30, v121
	v_cndmask_b32_e64 v106, 0, 1.0, s[0:1]
	v_cmp_lt_i32_e64 s[0:1], s30, v123
	s_and_b64 s[0:1], vcc, s[0:1]
	v_cmp_ge_i32_e32 vcc, s29, v121
	v_cndmask_b32_e64 v120, 0, 1.0, s[0:1]
	v_cmp_lt_i32_e64 s[0:1], s29, v123
	s_and_b64 s[0:1], vcc, s[0:1]
	v_cmp_ge_i32_e32 vcc, s28, v121
	v_cndmask_b32_e64 v122, 0, 1.0, s[0:1]
	v_cmp_lt_i32_e64 s[0:1], s28, v123
	s_and_b64 s[0:1], vcc, s[0:1]
	v_cmp_ge_i32_e32 vcc, s27, v121
	v_cndmask_b32_e64 v156, 0, 1.0, s[0:1]
; __device__ __forceinline__ float bf_lo(unsigned w) { return __uint_as_float(w << 16); }
; __device__ __forceinline__ float bf_hi(unsigned w) { return __uint_as_float(w & 0xffff0000u); }
; __device__ __forceinline__ void phase_mixer(const Params& p, LAS unsigned char* lds, int l, bool with_ctx, int G, int tid, int wave, int lane, int rep_attn, int rep_pool) {
;     ...
;         for (int o = 0; o < 16; ++o) {
;             const int t = t0 + o, st = max(t - lo, 0), en = min(t + hi + 1, len);
;             float acc[8];
; #pragma unroll
;             for (int e = 0; e < 8; ++e) acc[e] = 0.f;
; #pragma unroll
;             for (int i = 0; i < 16; ++i) { const int tt = t + i - 8; const float wt = (tt >= st && tt < en) ? 1.f : 0.f; const u32x4 ww = w[o + i];
;                 acc[0] += wt * bf_lo(ww.x); acc[1] += wt * bf_hi(ww.x); acc[2] += wt * bf_lo(ww.y); acc[3] += wt * bf_hi(ww.y);
;                 acc[4] += wt * bf_lo(ww.z); acc[5] += wt * bf_hi(ww.z); acc[6] += wt * bf_lo(ww.w); acc[7] += wt * bf_hi(ww.w); }
;             const float ic = 1.f / (float)(en - st);
	v_cmp_lt_i32_e64 s[0:1], s27, v123
	s_and_b64 s[0:1], vcc, s[0:1]
	v_pk_fma_f32 v[190:191], v[106:107], v[190:191], 0 op_sel_hi:[0,1,0]
	v_cndmask_b32_e64 v196, 0, 1.0, s[0:1]
	v_cmp_ge_i32_e32 vcc, s8, v121
	v_cmp_lt_i32_e64 s[0:1], s8, v123
	v_pk_fma_f32 v[190:191], v[120:121], v[182:183], v[190:191] op_sel_hi:[0,1,1]
	s_and_b64 s[0:1], vcc, s[0:1]
	v_pk_fma_f32 v[190:191], v[122:123], v[136:137], v[190:191] op_sel_hi:[0,1,1]
	v_cndmask_b32_e64 v198, 0, 1.0, s[0:1]
	v_cmp_ge_i32_e32 vcc, s26, v121
	v_cmp_lt_i32_e64 s[0:1], s26, v123
	v_pk_fma_f32 v[190:191], v[156:157], v[148:149], v[190:191] op_sel_hi:[0,1,1]
	s_and_b64 s[0:1], vcc, s[0:1]
	v_pk_fma_f32 v[190:191], v[196:197], v[146:147], v[190:191] op_sel_hi:[0,1,1]
	v_cndmask_b32_e64 v200, 0, 1.0, s[0:1]
	v_pk_fma_f32 v[190:191], v[198:199], v[152:153], v[190:191] op_sel_hi:[0,1,1]
	v_pk_fma_f32 v[208:209], v[200:201], v[132:133], v[190:191] op_sel_hi:[0,1,1]
	v_pk_fma_f32 v[190:191], v[106:107], v[192:193], 0 op_sel_hi:[0,1,0]
	v_pk_fma_f32 v[108:109], v[106:107], v[108:109], 0 op_sel_hi:[0,1,0]
	v_pk_fma_f32 v[106:107], v[106:107], v[194:195], 0 op_sel_hi:[0,1,0]
	v_pk_fma_f32 v[190:191], v[120:121], v[184:185], v[190:191] op_sel_hi:[0,1,1]
	v_pk_fma_f32 v[108:109], v[120:121], v[186:187], v[108:109] op_sel_hi:[0,1,1]
	v_pk_fma_f32 v[106:107], v[120:121], v[188:189], v[106:107] op_sel_hi:[0,1,1]
	v_cmp_ge_i32_e32 vcc, s23, v121
	v_cmp_lt_i32_e64 s[0:1], s23, v123
	v_pk_fma_f32 v[190:191], v[122:123], v[138:139], v[190:191] op_sel_hi:[0,1,1]
	v_pk_fma_f32 v[108:109], v[122:123], v[178:179], v[108:109] op_sel_hi:[0,1,1]
	v_pk_fma_f32 v[106:107], v[122:123], v[180:181], v[106:107] op_sel_hi:[0,1,1]
	s_and_b64 s[0:1], vcc, s[0:1]
	v_pk_fma_f32 v[190:191], v[156:157], v[150:151], v[190:191] op_sel_hi:[0,1,1]
	v_pk_fma_f32 v[108:109], v[156:157], v[174:175], v[108:109] op_sel_hi:[0,1,1]
	v_pk_fma_f32 v[106:107], v[156:157], v[176:177], v[106:107] op_sel_hi:[0,1,1]
	v_cndmask_b32_e64 v156, 0, 1.0, s[0:1]
	v_cmp_ge_i32_e32 vcc, s22, v121
	v_cmp_lt_i32_e64 s[0:1], s22, v123
	s_and_b64 s[0:1], vcc, s[0:1]
	v_cmp_ge_i32_e32 vcc, s21, v121
	v_cndmask_b32_e64 v192, 0, 1.0, s[0:1]
	v_cmp_lt_i32_e64 s[0:1], s21, v123
	s_and_b64 s[0:1], vcc, s[0:1]
	v_cmp_ge_i32_e32 vcc, s20, v121
	v_cndmask_b32_e64 v194, 0, 1.0, s[0:1]
	v_cmp_lt_i32_e64 s[0:1], s20, v123
	s_and_b64 s[0:1], vcc, s[0:1]
	v_pk_fma_f32 v[190:191], v[196:197], v[144:145], v[190:191] op_sel_hi:[0,1,1]
	v_pk_fma_f32 v[108:109], v[196:197], v[142:143], v[108:109] op_sel_hi:[0,1,1]
	v_pk_fma_f32 v[106:107], v[196:197], v[140:141], v[106:107] op_sel_hi:[0,1,1]
	v_cndmask_b32_e64 v196, 0, 1.0, s[0:1]
	v_cmp_ge_i32_e32 vcc, s19, v121
	v_cmp_lt_i32_e64 s[0:1], s19, v123
	s_and_b64 s[0:1], vcc, s[0:1]
	v_pk_fma_f32 v[190:191], v[198:199], v[154:155], v[190:191] op_sel_hi:[0,1,1]
	v_pk_fma_f32 v[108:109], v[198:199], v[170:171], v[108:109] op_sel_hi:[0,1,1]
	v_pk_fma_f32 v[106:107], v[198:199], v[172:173], v[106:107] op_sel_hi:[0,1,1]
	v_cndmask_b32_e64 v198, 0, 1.0, s[0:1]
	v_cmp_ge_i32_e32 vcc, s10, v121
	v_cmp_lt_i32_e64 s[0:1], s10, v123
	s_and_b64 s[0:1], vcc, s[0:1]
	v_pk_fma_f32 v[206:207], v[200:201], v[130:131], v[190:191] op_sel_hi:[0,1,1]
	v_pk_fma_f32 v[108:109], v[200:201], v[128:129], v[108:109] op_sel_hi:[0,1,1]
	v_pk_fma_f32 v[190:191], v[200:201], v[118:119], v[106:107] op_sel_hi:[0,1,1]
	v_cndmask_b32_e64 v200, 0, 1.0, s[0:1]
	v_cmp_ge_i32_e32 vcc, s11, v121
	v_cmp_lt_i32_e64 s[0:1], s11, v123
	s_and_b64 s[0:1], vcc, s[0:1]
	v_sub_u32_e32 v106, v123, v121
	v_cndmask_b32_e64 v202, 0, 1.0, s[0:1]
	v_cmp_ge_i32_e32 vcc, s12, v121
	v_cmp_lt_i32_e64 s[0:1], s12, v123
	v_cvt_f32_i32_e32 v106, v106
	s_and_b64 s[0:1], vcc, s[0:1]
	v_cndmask_b32_e64 v204, 0, 1.0, s[0:1]
	v_cmp_ge_i32_e32 vcc, s13, v121
	v_cmp_lt_i32_e64 s[0:1], s13, v123
	s_and_b64 s[0:1], vcc, s[0:1]
	v_pk_fma_f32 v[206:207], v[156:157], v[102:103], v[206:207] op_sel_hi:[0,1,1]
	v_cndmask_b32_e64 v120, 0, 1.0, s[0:1]
	v_div_scale_f32 v107, s[0:1], v106, v106, 1.0
	v_rcp_f32_e32 v121, v107
	v_pk_fma_f32 v[206:207], v[192:193], v[114:115], v[206:207] op_sel_hi:[0,1,1]
	v_pk_fma_f32 v[206:207], v[194:195], v[94:95], v[206:207] op_sel_hi:[0,1,1]
	v_pk_fma_f32 v[206:207], v[196:197], v[80:81], v[206:207] op_sel_hi:[0,1,1]
	v_fma_f32 v122, -v107, v121, 1.0
	v_fmac_f32_e32 v121, v122, v121
	v_div_scale_f32 v122, vcc, 1.0, v106, 1.0
	v_mul_f32_e32 v123, v122, v121
	v_fma_f32 v160, -v107, v123, v122
	v_fmac_f32_e32 v123, v160, v121
	v_fma_f32 v107, -v107, v123, v122
	v_div_fmas_f32 v107, v107, v121, v123
	v_div_fixup_f32 v122, v107, v106, 1.0
	v_pk_fma_f32 v[106:107], v[156:157], v[104:105], v[208:209] op_sel_hi:[0,1,1]
	v_pk_fma_f32 v[106:107], v[192:193], v[112:113], v[106:107] op_sel_hi:[0,1,1]
	v_pk_fma_f32 v[106:107], v[194:195], v[92:93], v[106:107] op_sel_hi:[0,1,1]
	v_pk_fma_f32 v[106:107], v[196:197], v[88:89], v[106:107] op_sel_hi:[0,1,1]
	v_pk_fma_f32 v[108:109], v[156:157], v[100:101], v[108:109] op_sel_hi:[0,1,1]
	v_pk_fma_f32 v[190:191], v[156:157], v[98:99], v[190:191] op_sel_hi:[0,1,1]
	v_pk_fma_f32 v[106:107], v[198:199], v[86:87], v[106:107] op_sel_hi:[0,1,1]
	v_pk_fma_f32 v[206:207], v[198:199], v[72:73], v[206:207] op_sel_hi:[0,1,1]
	v_pk_fma_f32 v[108:109], v[192:193], v[116:117], v[108:109] op_sel_hi:[0,1,1]
	v_pk_fma_f32 v[190:191], v[192:193], v[134:135], v[190:191] op_sel_hi:[0,1,1]
	v_pk_fma_f32 v[106:107], v[200:201], v[84:85], v[106:107] op_sel_hi:[0,1,1]
	v_pk_fma_f32 v[206:207], v[200:201], v[64:65], v[206:207] op_sel_hi:[0,1,1]
	v_pk_fma_f32 v[108:109], v[194:195], v[96:97], v[108:109] op_sel_hi:[0,1,1]
	v_pk_fma_f32 v[190:191], v[194:195], v[110:111], v[190:191] op_sel_hi:[0,1,1]
	v_pk_fma_f32 v[106:107], v[202:203], v[60:61], v[106:107] op_sel_hi:[0,1,1]
	v_pk_fma_f32 v[206:207], v[202:203], v[56:57], v[206:207] op_sel_hi:[0,1,1]
	v_pk_fma_f32 v[108:109], v[196:197], v[90:91], v[108:109] op_sel_hi:[0,1,1]
	v_pk_fma_f32 v[190:191], v[196:197], v[82:83], v[190:191] op_sel_hi:[0,1,1]
	v_pk_fma_f32 v[208:209], v[204:205], v[74:75], v[106:107] op_sel_hi:[0,1,1]
	s_waitcnt vmcnt(15)
; __device__ __forceinline__ unsigned cvt_pk_bf16(float lo, float hi) { const f32x2 v = (f32x2){lo, hi}; return __builtin_bit_cast(unsigned, __builtin_convertvector(v, bf16v2)); }
; __device__ __forceinline__ float bf_lo(unsigned w) { return __uint_as_float(w << 16); }
; __device__ __forceinline__ float bf_hi(unsigned w) { return __uint_as_float(w & 0xffff0000u); }
; __device__ __forceinline__ void phase_mixer(const Params& p, LAS unsigned char* lds, int l, bool with_ctx, int G, int tid, int wave, int lane, int rep_attn, int rep_pool) {
;     ...
;         for (int o = 0; o < 16; ++o) {
;             const int t = t0 + o, st = max(t - lo, 0), en = min(t + hi + 1, len);
;             float acc[8];
; #pragma unroll
;             for (int e = 0; e < 8; ++e) acc[e] = 0.f;
; #pragma unroll
;             for (int i = 0; i < 16; ++i) { const int tt = t + i - 8; const float wt = (tt >= st && tt < en) ? 1.f : 0.f; const u32x4 ww = w[o + i];
;                 acc[0] += wt * bf_lo(ww.x); acc[1] += wt * bf_hi(ww.x); acc[2] += wt * bf_lo(ww.y); acc[3] += wt * bf_hi(ww.y);
;                 acc[4] += wt * bf_lo(ww.z); acc[5] += wt * bf_hi(ww.z); acc[6] += wt * bf_lo(ww.w); acc[7] += wt * bf_hi(ww.w); }
;             const float ic = 1.f / (float)(en - st);
;             const u32x4 sw = w[o + 8];
;             u32x4 ov; ov.x = cvt_pk_bf16(acc[0] * ic - bf_lo(sw.x), acc[1] * ic - bf_hi(sw.x)); ov.y = cvt_pk_bf16(acc[2] * ic - bf_lo(sw.y), acc[3] * ic - bf_hi(sw.y));
;             ov.z = cvt_pk_bf16(acc[4] * ic - bf_lo(sw.z), acc[5] * ic - bf_hi(sw.z)); ov.w = cvt_pk_bf16(acc[6] * ic - bf_lo(sw.w), acc[7] * ic - bf_hi(sw.w));
;             *(u32x4*)(MIX + (size_t)(tok0 + o) * DM + 8 * lane) = ov;
	v_lshlrev_b32_e32 v106, 16, v48
	v_and_b32_e32 v107, 0xffff0000, v48
	v_pk_fma_f32 v[206:207], v[204:205], v[52:53], v[206:207] op_sel_hi:[0,1,1]
	v_lshlrev_b32_e32 v48, 16, v49
	v_and_b32_e32 v49, 0xffff0000, v49
	v_pk_fma_f32 v[108:109], v[198:199], v[76:77], v[108:109] op_sel_hi:[0,1,1]
	v_pk_fma_f32 v[190:191], v[198:199], v[70:71], v[190:191] op_sel_hi:[0,1,1]
	v_pk_fma_f32 v[208:209], v[120:121], v[106:107], v[208:209] op_sel_hi:[0,1,1]
	v_pk_fma_f32 v[206:207], v[120:121], v[48:49], v[206:207] op_sel_hi:[0,1,1]
	v_pk_fma_f32 v[108:109], v[200:201], v[68:69], v[108:109] op_sel_hi:[0,1,1]
	v_pk_fma_f32 v[190:191], v[200:201], v[66:67], v[190:191] op_sel_hi:[0,1,1]
	v_pk_fma_f32 v[208:209], v[122:123], v[208:209], v[112:113] op_sel_hi:[0,1,1] neg_lo:[0,0,1] neg_hi:[0,0,1]
	v_pk_fma_f32 v[206:207], v[122:123], v[206:207], v[114:115] op_sel_hi:[0,1,1] neg_lo:[0,0,1] neg_hi:[0,0,1]
	v_pk_fma_f32 v[108:109], v[202:203], v[62:63], v[108:109] op_sel_hi:[0,1,1]
	v_pk_fma_f32 v[190:191], v[202:203], v[58:59], v[190:191] op_sel_hi:[0,1,1]
	v_cvt_pk_bf16_f32 v208, v208, v209
	v_cvt_pk_bf16_f32 v209, v206, v207
	v_pk_fma_f32 v[206:207], v[204:205], v[78:79], v[108:109] op_sel_hi:[0,1,1]
	v_lshlrev_b32_e32 v108, 16, v50
	v_and_b32_e32 v109, 0xffff0000, v50
	v_pk_fma_f32 v[190:191], v[204:205], v[54:55], v[190:191] op_sel_hi:[0,1,1]
	v_lshlrev_b32_e32 v50, 16, v51
	v_and_b32_e32 v51, 0xffff0000, v51
	s_or_b32 s0, s4, 3
	v_pk_fma_f32 v[206:207], v[120:121], v[108:109], v[206:207] op_sel_hi:[0,1,1]
	v_pk_fma_f32 v[120:121], v[120:121], v[50:51], v[190:191] op_sel_hi:[0,1,1]
	s_ashr_i32 s1, s0, 31
	v_pk_fma_f32 v[206:207], v[122:123], v[206:207], v[116:117] op_sel_hi:[0,1,1] neg_lo:[0,0,1] neg_hi:[0,0,1]
	v_pk_fma_f32 v[120:121], v[122:123], v[120:121], v[134:135] op_sel_hi:[0,1,1] neg_lo:[0,0,1] neg_hi:[0,0,1]
	s_lshl_b64 s[0:1], s[0:1], 11
	v_cvt_pk_bf16_f32 v210, v206, v207
	v_cvt_pk_bf16_f32 v211, v120, v121
	v_lshl_add_u64 v[120:121], v[126:127], 0, s[0:1]
	global_store_dwordx4 v[120:121], v[208:211], off
	v_sub_u32_e32 v120, s21, v167
	v_add_u32_e32 v121, s21, v167
	v_max_i32_e32 v160, 0, v120
	v_min_i32_e32 v161, s9, v121
	v_cmp_ge_i32_e32 vcc, s30, v160
	v_cmp_lt_i32_e64 s[0:1], s30, v161
	s_and_b64 s[0:1], vcc, s[0:1]
	v_cmp_ge_i32_e32 vcc, s29, v160
	v_cndmask_b32_e64 v120, 0, 1.0, s[0:1]
	v_cmp_lt_i32_e64 s[0:1], s29, v161
	s_and_b64 s[0:1], vcc, s[0:1]
	v_cmp_ge_i32_e32 vcc, s28, v160
	v_cndmask_b32_e64 v156, 0, 1.0, s[0:1]
	v_cmp_lt_i32_e64 s[0:1], s28, v161
	s_and_b64 s[0:1], vcc, s[0:1]
	v_cmp_ge_i32_e32 vcc, s27, v160
	v_cndmask_b32_e64 v190, 0, 1.0, s[0:1]
	v_cmp_lt_i32_e64 s[0:1], s27, v161
	s_and_b64 s[0:1], vcc, s[0:1]
	v_cmp_ge_i32_e32 vcc, s8, v160
	v_cndmask_b32_e64 v192, 0, 1.0, s[0:1]
	v_cmp_lt_i32_e64 s[0:1], s8, v161
	s_and_b64 s[0:1], vcc, s[0:1]
	v_pk_fma_f32 v[122:123], v[120:121], v[182:183], 0 op_sel_hi:[0,1,0]
	v_cndmask_b32_e64 v194, 0, 1.0, s[0:1]
	v_cmp_ge_i32_e32 vcc, s26, v160
	v_cmp_lt_i32_e64 s[0:1], s26, v161
	v_pk_fma_f32 v[122:123], v[156:157], v[136:137], v[122:123] op_sel_hi:[0,1,1]
	s_and_b64 s[0:1], vcc, s[0:1]
	v_pk_fma_f32 v[122:123], v[190:191], v[148:149], v[122:123] op_sel_hi:[0,1,1]
	v_cndmask_b32_e64 v196, 0, 1.0, s[0:1]
	v_cmp_ge_i32_e32 vcc, s23, v160
	v_cmp_lt_i32_e64 s[0:1], s23, v161
	v_pk_fma_f32 v[122:123], v[192:193], v[146:147], v[122:123] op_sel_hi:[0,1,1]
	s_and_b64 s[0:1], vcc, s[0:1]
	v_pk_fma_f32 v[122:123], v[194:195], v[152:153], v[122:123] op_sel_hi:[0,1,1]
	v_cndmask_b32_e64 v198, 0, 1.0, s[0:1]
	v_pk_fma_f32 v[122:123], v[196:197], v[132:133], v[122:123] op_sel_hi:[0,1,1]
	v_pk_fma_f32 v[204:205], v[198:199], v[104:105], v[122:123] op_sel_hi:[0,1,1]
	v_pk_fma_f32 v[122:123], v[120:121], v[184:185], 0 op_sel_hi:[0,1,0]
	v_pk_fma_f32 v[122:123], v[156:157], v[138:139], v[122:123] op_sel_hi:[0,1,1]
	v_pk_fma_f32 v[122:123], v[190:191], v[150:151], v[122:123] op_sel_hi:[0,1,1]
	v_pk_fma_f32 v[122:123], v[192:193], v[144:145], v[122:123] op_sel_hi:[0,1,1]
	v_pk_fma_f32 v[122:123], v[194:195], v[154:155], v[122:123] op_sel_hi:[0,1,1]
	v_cmp_ge_i32_e32 vcc, s22, v160
	v_cmp_lt_i32_e64 s[0:1], s22, v161
	v_pk_fma_f32 v[122:123], v[196:197], v[130:131], v[122:123] op_sel_hi:[0,1,1]
	s_and_b64 s[0:1], vcc, s[0:1]
	v_pk_fma_f32 v[202:203], v[198:199], v[102:103], v[122:123] op_sel_hi:[0,1,1]
	v_pk_fma_f32 v[122:123], v[120:121], v[186:187], 0 op_sel_hi:[0,1,0]
	v_cndmask_b32_e64 v186, 0, 1.0, s[0:1]
	v_cmp_ge_i32_e32 vcc, s21, v160
	v_cmp_lt_i32_e64 s[0:1], s21, v161
	s_and_b64 s[0:1], vcc, s[0:1]
	v_pk_fma_f32 v[120:121], v[120:121], v[188:189], 0 op_sel_hi:[0,1,0]
	v_cndmask_b32_e64 v188, 0, 1.0, s[0:1]
	v_cmp_ge_i32_e32 vcc, s20, v160
	v_cmp_lt_i32_e64 s[0:1], s20, v161
	v_pk_fma_f32 v[122:123], v[156:157], v[178:179], v[122:123] op_sel_hi:[0,1,1]
	v_pk_fma_f32 v[120:121], v[156:157], v[180:181], v[120:121] op_sel_hi:[0,1,1]
	s_and_b64 s[0:1], vcc, s[0:1]
	v_pk_fma_f32 v[122:123], v[190:191], v[174:175], v[122:123] op_sel_hi:[0,1,1]
	v_pk_fma_f32 v[120:121], v[190:191], v[176:177], v[120:121] op_sel_hi:[0,1,1]
	v_cndmask_b32_e64 v190, 0, 1.0, s[0:1]
	v_cmp_ge_i32_e32 vcc, s19, v160
	v_cmp_lt_i32_e64 s[0:1], s19, v161
	s_and_b64 s[0:1], vcc, s[0:1]
	v_pk_fma_f32 v[122:123], v[192:193], v[142:143], v[122:123] op_sel_hi:[0,1,1]
	v_pk_fma_f32 v[120:121], v[192:193], v[140:141], v[120:121] op_sel_hi:[0,1,1]
	v_cndmask_b32_e64 v192, 0, 1.0, s[0:1]
	v_cmp_ge_i32_e32 vcc, s10, v160
	v_cmp_lt_i32_e64 s[0:1], s10, v161
	s_and_b64 s[0:1], vcc, s[0:1]
	v_pk_fma_f32 v[122:123], v[194:195], v[170:171], v[122:123] op_sel_hi:[0,1,1]
	v_pk_fma_f32 v[120:121], v[194:195], v[172:173], v[120:121] op_sel_hi:[0,1,1]
; __device__ __forceinline__ unsigned cvt_pk_bf16(float lo, float hi) { const f32x2 v = (f32x2){lo, hi}; return __builtin_bit_cast(unsigned, __builtin_convertvector(v, bf16v2)); }
; __device__ __forceinline__ float bf_lo(unsigned w) { return __uint_as_float(w << 16); }
; __device__ __forceinline__ float bf_hi(unsigned w) { return __uint_as_float(w & 0xffff0000u); }
; __device__ __forceinline__ void phase_mixer(const Params& p, LAS unsigned char* lds, int l, bool with_ctx, int G, int tid, int wave, int lane, int rep_attn, int rep_pool) {
;     ...
;         for (int o = 0; o < 16; ++o) {
;             const int t = t0 + o, st = max(t - lo, 0), en = min(t + hi + 1, len);
;             float acc[8];
; #pragma unroll
;             for (int e = 0; e < 8; ++e) acc[e] = 0.f;
; #pragma unroll
;             for (int i = 0; i < 16; ++i) { const int tt = t + i - 8; const float wt = (tt >= st && tt < en) ? 1.f : 0.f; const u32x4 ww = w[o + i];
;                 acc[0] += wt * bf_lo(ww.x); acc[1] += wt * bf_hi(ww.x); acc[2] += wt * bf_lo(ww.y); acc[3] += wt * bf_hi(ww.y);
;                 acc[4] += wt * bf_lo(ww.z); acc[5] += wt * bf_hi(ww.z); acc[6] += wt * bf_lo(ww.w); acc[7] += wt * bf_hi(ww.w); }
;             const float ic = 1.f / (float)(en - st);
;             const u32x4 sw = w[o + 8];
;             u32x4 ov; ov.x = cvt_pk_bf16(acc[0] * ic - bf_lo(sw.x), acc[1] * ic - bf_hi(sw.x)); ov.y = cvt_pk_bf16(acc[2] * ic - bf_lo(sw.y), acc[3] * ic - bf_hi(sw.y));
;             ov.z = cvt_pk_bf16(acc[4] * ic - bf_lo(sw.z), acc[5] * ic - bf_hi(sw.z)); ov.w = cvt_pk_bf16(acc[6] * ic - bf_lo(sw.w), acc[7] * ic - bf_hi(sw.w));
;             *(u32x4*)(MIX + (size_t)(tok0 + o) * DM + 8 * lane) = ov;
	v_cndmask_b32_e64 v194, 0, 1.0, s[0:1]
	v_cmp_ge_i32_e32 vcc, s11, v160
	v_cmp_lt_i32_e64 s[0:1], s11, v161
	s_and_b64 s[0:1], vcc, s[0:1]
	v_pk_fma_f32 v[122:123], v[196:197], v[128:129], v[122:123] op_sel_hi:[0,1,1]
	v_pk_fma_f32 v[120:121], v[196:197], v[118:119], v[120:121] op_sel_hi:[0,1,1]
	v_cndmask_b32_e64 v196, 0, 1.0, s[0:1]
	v_cmp_ge_i32_e32 vcc, s12, v160
	v_cmp_lt_i32_e64 s[0:1], s12, v161
	v_pk_fma_f32 v[184:185], v[198:199], v[98:99], v[120:121] op_sel_hi:[0,1,1]
	s_and_b64 s[0:1], vcc, s[0:1]
	v_sub_u32_e32 v120, v161, v160
	v_pk_fma_f32 v[122:123], v[198:199], v[100:101], v[122:123] op_sel_hi:[0,1,1]
	v_cndmask_b32_e64 v198, 0, 1.0, s[0:1]
	v_cmp_ge_i32_e32 vcc, s13, v160
	v_cmp_lt_i32_e64 s[0:1], s13, v161
	v_cvt_f32_i32_e32 v120, v120
	s_and_b64 s[0:1], vcc, s[0:1]
	v_cndmask_b32_e64 v200, 0, 1.0, s[0:1]
	v_cmp_ge_i32_e32 vcc, s14, v160
	v_cmp_lt_i32_e64 s[0:1], s14, v161
	s_and_b64 s[0:1], vcc, s[0:1]
	v_pk_fma_f32 v[202:203], v[186:187], v[114:115], v[202:203] op_sel_hi:[0,1,1]
	v_cndmask_b32_e64 v156, 0, 1.0, s[0:1]
	v_div_scale_f32 v121, s[0:1], v120, v120, 1.0
	v_rcp_f32_e32 v160, v121
	v_pk_fma_f32 v[202:203], v[188:189], v[94:95], v[202:203] op_sel_hi:[0,1,1]
	v_pk_fma_f32 v[202:203], v[190:191], v[80:81], v[202:203] op_sel_hi:[0,1,1]
	v_pk_fma_f32 v[202:203], v[192:193], v[72:73], v[202:203] op_sel_hi:[0,1,1]
	v_fma_f32 v161, -v121, v160, 1.0
	v_fmac_f32_e32 v160, v161, v160
	v_div_scale_f32 v161, vcc, 1.0, v120, 1.0
	v_mul_f32_e32 v182, v161, v160
	v_fma_f32 v183, -v121, v182, v161
	v_fmac_f32_e32 v182, v183, v160
	v_fma_f32 v121, -v121, v182, v161
	v_div_fmas_f32 v121, v121, v160, v182
	v_div_fixup_f32 v182, v121, v120, 1.0
	v_pk_fma_f32 v[120:121], v[186:187], v[112:113], v[204:205] op_sel_hi:[0,1,1]
	v_pk_fma_f32 v[120:121], v[188:189], v[92:93], v[120:121] op_sel_hi:[0,1,1]
	v_pk_fma_f32 v[120:121], v[190:191], v[88:89], v[120:121] op_sel_hi:[0,1,1]
	v_pk_fma_f32 v[120:121], v[192:193], v[86:87], v[120:121] op_sel_hi:[0,1,1]
	v_pk_fma_f32 v[122:123], v[186:187], v[116:117], v[122:123] op_sel_hi:[0,1,1]
	v_pk_fma_f32 v[184:185], v[186:187], v[134:135], v[184:185] op_sel_hi:[0,1,1]
	v_pk_fma_f32 v[120:121], v[194:195], v[84:85], v[120:121] op_sel_hi:[0,1,1]
	v_pk_fma_f32 v[202:203], v[194:195], v[64:65], v[202:203] op_sel_hi:[0,1,1]
	v_pk_fma_f32 v[122:123], v[188:189], v[96:97], v[122:123] op_sel_hi:[0,1,1]
	v_pk_fma_f32 v[184:185], v[188:189], v[110:111], v[184:185] op_sel_hi:[0,1,1]
	v_pk_fma_f32 v[120:121], v[196:197], v[60:61], v[120:121] op_sel_hi:[0,1,1]
	v_pk_fma_f32 v[202:203], v[196:197], v[56:57], v[202:203] op_sel_hi:[0,1,1]
	v_pk_fma_f32 v[122:123], v[190:191], v[90:91], v[122:123] op_sel_hi:[0,1,1]
	v_pk_fma_f32 v[184:185], v[190:191], v[82:83], v[184:185] op_sel_hi:[0,1,1]
	v_pk_fma_f32 v[120:121], v[198:199], v[74:75], v[120:121] op_sel_hi:[0,1,1]
	v_pk_fma_f32 v[202:203], v[198:199], v[52:53], v[202:203] op_sel_hi:[0,1,1]
	v_pk_fma_f32 v[122:123], v[192:193], v[76:77], v[122:123] op_sel_hi:[0,1,1]
	v_pk_fma_f32 v[184:185], v[192:193], v[70:71], v[184:185] op_sel_hi:[0,1,1]
	v_pk_fma_f32 v[204:205], v[200:201], v[106:107], v[120:121] op_sel_hi:[0,1,1]
	s_waitcnt vmcnt(15)
	v_lshlrev_b32_e32 v120, 16, v44
	v_and_b32_e32 v121, 0xffff0000, v44
	v_pk_fma_f32 v[202:203], v[200:201], v[48:49], v[202:203] op_sel_hi:[0,1,1]
	v_lshlrev_b32_e32 v44, 16, v45
	v_and_b32_e32 v45, 0xffff0000, v45
	v_pk_fma_f32 v[122:123], v[194:195], v[68:69], v[122:123] op_sel_hi:[0,1,1]
	v_pk_fma_f32 v[184:185], v[194:195], v[66:67], v[184:185] op_sel_hi:[0,1,1]
	v_pk_fma_f32 v[204:205], v[156:157], v[120:121], v[204:205] op_sel_hi:[0,1,1]
	v_pk_fma_f32 v[202:203], v[156:157], v[44:45], v[202:203] op_sel_hi:[0,1,1]
	v_pk_fma_f32 v[122:123], v[196:197], v[62:63], v[122:123] op_sel_hi:[0,1,1]
	v_pk_fma_f32 v[184:185], v[196:197], v[58:59], v[184:185] op_sel_hi:[0,1,1]
	v_pk_fma_f32 v[204:205], v[182:183], v[204:205], v[92:93] op_sel_hi:[0,1,1] neg_lo:[0,0,1] neg_hi:[0,0,1]
	v_pk_fma_f32 v[202:203], v[182:183], v[202:203], v[94:95] op_sel_hi:[0,1,1] neg_lo:[0,0,1] neg_hi:[0,0,1]
	v_pk_fma_f32 v[122:123], v[198:199], v[78:79], v[122:123] op_sel_hi:[0,1,1]
	v_pk_fma_f32 v[184:185], v[198:199], v[54:55], v[184:185] op_sel_hi:[0,1,1]
	v_cvt_pk_bf16_f32 v204, v204, v205
	v_cvt_pk_bf16_f32 v205, v202, v203
	v_pk_fma_f32 v[202:203], v[200:201], v[108:109], v[122:123] op_sel_hi:[0,1,1]
	v_lshlrev_b32_e32 v122, 16, v46
	v_and_b32_e32 v123, 0xffff0000, v46
	v_pk_fma_f32 v[184:185], v[200:201], v[50:51], v[184:185] op_sel_hi:[0,1,1]
	v_lshlrev_b32_e32 v46, 16, v47
	v_and_b32_e32 v47, 0xffff0000, v47
	s_or_b32 s0, s4, 4
	v_pk_fma_f32 v[202:203], v[156:157], v[122:123], v[202:203] op_sel_hi:[0,1,1]
	v_pk_fma_f32 v[184:185], v[156:157], v[46:47], v[184:185] op_sel_hi:[0,1,1]
	s_ashr_i32 s1, s0, 31
	v_sub_u32_e32 v156, s20, v167
	v_add_u32_e32 v160, s20, v167
	v_pk_fma_f32 v[202:203], v[182:183], v[202:203], v[96:97] op_sel_hi:[0,1,1] neg_lo:[0,0,1] neg_hi:[0,0,1]
	v_pk_fma_f32 v[182:183], v[182:183], v[184:185], v[110:111] op_sel_hi:[0,1,1] neg_lo:[0,0,1] neg_hi:[0,0,1]
	s_lshl_b64 s[0:1], s[0:1], 11
	v_max_i32_e32 v161, 0, v156
	v_min_i32_e32 v160, s9, v160
	v_cvt_pk_bf16_f32 v207, v182, v183
	v_lshl_add_u64 v[182:183], v[126:127], 0, s[0:1]
	v_cmp_ge_i32_e32 vcc, s29, v161
	v_cmp_lt_i32_e64 s[0:1], s29, v160
	s_and_b64 s[0:1], vcc, s[0:1]
	v_cmp_ge_i32_e32 vcc, s28, v161
	v_cndmask_b32_e64 v156, 0, 1.0, s[0:1]
	v_cmp_lt_i32_e64 s[0:1], s28, v160
	v_cvt_pk_bf16_f32 v206, v202, v203
	s_and_b64 s[0:1], vcc, s[0:1]
	global_store_dwordx4 v[182:183], v[204:207], off
	v_cndmask_b32_e64 v182, 0, 1.0, s[0:1]
	v_cmp_ge_i32_e32 vcc, s27, v161
; __device__ __forceinline__ float bf_lo(unsigned w) { return __uint_as_float(w << 16); }
; __device__ __forceinline__ float bf_hi(unsigned w) { return __uint_as_float(w & 0xffff0000u); }
; __device__ __forceinline__ void phase_mixer(const Params& p, LAS unsigned char* lds, int l, bool with_ctx, int G, int tid, int wave, int lane, int rep_attn, int rep_pool) {
;     ...
;         for (int o = 0; o < 16; ++o) {
;             const int t = t0 + o, st = max(t - lo, 0), en = min(t + hi + 1, len);
;             float acc[8];
; #pragma unroll
;             for (int e = 0; e < 8; ++e) acc[e] = 0.f;
; #pragma unroll
;             for (int i = 0; i < 16; ++i) { const int tt = t + i - 8; const float wt = (tt >= st && tt < en) ? 1.f : 0.f; const u32x4 ww = w[o + i];
;                 acc[0] += wt * bf_lo(ww.x); acc[1] += wt * bf_hi(ww.x); acc[2] += wt * bf_lo(ww.y); acc[3] += wt * bf_hi(ww.y);
;                 acc[4] += wt * bf_lo(ww.z); acc[5] += wt * bf_hi(ww.z); acc[6] += wt * bf_lo(ww.w); acc[7] += wt * bf_hi(ww.w); }
;             const float ic = 1.f / (float)(en - st);
	v_cmp_lt_i32_e64 s[0:1], s27, v160
	s_and_b64 s[0:1], vcc, s[0:1]
	v_cmp_ge_i32_e32 vcc, s8, v161
	v_cndmask_b32_e64 v184, 0, 1.0, s[0:1]
	v_cmp_lt_i32_e64 s[0:1], s8, v160
	s_and_b64 s[0:1], vcc, s[0:1]
	v_cmp_ge_i32_e32 vcc, s26, v161
	v_cndmask_b32_e64 v186, 0, 1.0, s[0:1]
	v_cmp_lt_i32_e64 s[0:1], s26, v160
	s_and_b64 s[0:1], vcc, s[0:1]
	v_pk_fma_f32 v[138:139], v[156:157], v[138:139], 0 op_sel_hi:[0,1,0]
	v_cndmask_b32_e64 v188, 0, 1.0, s[0:1]
	v_cmp_ge_i32_e32 vcc, s23, v161
	v_cmp_lt_i32_e64 s[0:1], s23, v160
	v_pk_fma_f32 v[138:139], v[182:183], v[150:151], v[138:139] op_sel_hi:[0,1,1]
	s_and_b64 s[0:1], vcc, s[0:1]
	v_pk_fma_f32 v[138:139], v[184:185], v[144:145], v[138:139] op_sel_hi:[0,1,1]
	v_cndmask_b32_e64 v190, 0, 1.0, s[0:1]
	v_cmp_ge_i32_e32 vcc, s22, v161
	v_cmp_lt_i32_e64 s[0:1], s22, v160
	v_pk_fma_f32 v[138:139], v[186:187], v[154:155], v[138:139] op_sel_hi:[0,1,1]
	s_and_b64 s[0:1], vcc, s[0:1]
	v_pk_fma_f32 v[138:139], v[188:189], v[130:131], v[138:139] op_sel_hi:[0,1,1]
	v_cndmask_b32_e64 v192, 0, 1.0, s[0:1]
	v_pk_fma_f32 v[138:139], v[190:191], v[102:103], v[138:139] op_sel_hi:[0,1,1]
	v_cmp_ge_i32_e32 vcc, s21, v161
	v_cmp_lt_i32_e64 s[0:1], s21, v160
	v_pk_fma_f32 v[136:137], v[156:157], v[136:137], 0 op_sel_hi:[0,1,0]
	v_pk_fma_f32 v[198:199], v[192:193], v[114:115], v[138:139] op_sel_hi:[0,1,1]
	v_pk_fma_f32 v[138:139], v[156:157], v[178:179], 0 op_sel_hi:[0,1,0]
	v_pk_fma_f32 v[178:179], v[156:157], v[180:181], 0 op_sel_hi:[0,1,0]
	s_and_b64 s[0:1], vcc, s[0:1]
	v_pk_fma_f32 v[136:137], v[182:183], v[148:149], v[136:137] op_sel_hi:[0,1,1]
	v_pk_fma_f32 v[138:139], v[182:183], v[174:175], v[138:139] op_sel_hi:[0,1,1]
	v_pk_fma_f32 v[178:179], v[182:183], v[176:177], v[178:179] op_sel_hi:[0,1,1]
	v_cndmask_b32_e64 v182, 0, 1.0, s[0:1]
	v_cmp_ge_i32_e32 vcc, s20, v161
	v_cmp_lt_i32_e64 s[0:1], s20, v160
	s_and_b64 s[0:1], vcc, s[0:1]
	v_pk_fma_f32 v[136:137], v[184:185], v[146:147], v[136:137] op_sel_hi:[0,1,1]
	v_pk_fma_f32 v[138:139], v[184:185], v[142:143], v[138:139] op_sel_hi:[0,1,1]
	v_pk_fma_f32 v[178:179], v[184:185], v[140:141], v[178:179] op_sel_hi:[0,1,1]
	v_cndmask_b32_e64 v184, 0, 1.0, s[0:1]
	v_cmp_ge_i32_e32 vcc, s19, v161
	v_cmp_lt_i32_e64 s[0:1], s19, v160
	s_and_b64 s[0:1], vcc, s[0:1]
	v_pk_fma_f32 v[136:137], v[186:187], v[152:153], v[136:137] op_sel_hi:[0,1,1]
	v_pk_fma_f32 v[138:139], v[186:187], v[170:171], v[138:139] op_sel_hi:[0,1,1]
	v_pk_fma_f32 v[178:179], v[186:187], v[172:173], v[178:179] op_sel_hi:[0,1,1]
	v_cndmask_b32_e64 v186, 0, 1.0, s[0:1]
	v_cmp_ge_i32_e32 vcc, s10, v161
	v_cmp_lt_i32_e64 s[0:1], s10, v160
	s_and_b64 s[0:1], vcc, s[0:1]
	v_pk_fma_f32 v[136:137], v[188:189], v[132:133], v[136:137] op_sel_hi:[0,1,1]
	v_pk_fma_f32 v[138:139], v[188:189], v[128:129], v[138:139] op_sel_hi:[0,1,1]
	v_pk_fma_f32 v[178:179], v[188:189], v[118:119], v[178:179] op_sel_hi:[0,1,1]
	v_cndmask_b32_e64 v188, 0, 1.0, s[0:1]
	v_cmp_ge_i32_e32 vcc, s11, v161
	v_cmp_lt_i32_e64 s[0:1], s11, v160
	s_and_b64 s[0:1], vcc, s[0:1]
	v_pk_fma_f32 v[136:137], v[190:191], v[104:105], v[136:137] op_sel_hi:[0,1,1]
	v_pk_fma_f32 v[138:139], v[190:191], v[100:101], v[138:139] op_sel_hi:[0,1,1]
	v_pk_fma_f32 v[178:179], v[190:191], v[98:99], v[178:179] op_sel_hi:[0,1,1]
	v_cndmask_b32_e64 v190, 0, 1.0, s[0:1]
	v_cmp_ge_i32_e32 vcc, s12, v161
	v_cmp_lt_i32_e64 s[0:1], s12, v160
	s_and_b64 s[0:1], vcc, s[0:1]
	v_pk_fma_f32 v[136:137], v[192:193], v[112:113], v[136:137] op_sel_hi:[0,1,1]
	v_pk_fma_f32 v[138:139], v[192:193], v[116:117], v[138:139] op_sel_hi:[0,1,1]
	v_pk_fma_f32 v[180:181], v[192:193], v[134:135], v[178:179] op_sel_hi:[0,1,1]
	v_cndmask_b32_e64 v192, 0, 1.0, s[0:1]
	v_cmp_ge_i32_e32 vcc, s13, v161
	v_cmp_lt_i32_e64 s[0:1], s13, v160
	s_and_b64 s[0:1], vcc, s[0:1]
	v_cmp_ge_i32_e32 vcc, s14, v161
	v_cndmask_b32_e64 v194, 0, 1.0, s[0:1]
	v_cmp_lt_i32_e64 s[0:1], s14, v160
	s_and_b64 s[0:1], vcc, s[0:1]
	v_cmp_ge_i32_e32 vcc, s15, v161
	v_cndmask_b32_e64 v196, 0, 1.0, s[0:1]
	v_cmp_lt_i32_e64 s[0:1], s15, v160
	v_sub_u32_e32 v160, v160, v161
	v_cvt_f32_i32_e32 v160, v160
	s_and_b64 s[0:1], vcc, s[0:1]
	v_cndmask_b32_e64 v156, 0, 1.0, s[0:1]
	v_div_scale_f32 v161, s[0:1], v160, v160, 1.0
	v_rcp_f32_e32 v178, v161
	s_or_b32 s0, s4, 5
	s_ashr_i32 s1, s0, 31
	s_lshl_b64 s[0:1], s[0:1], 11
	v_fma_f32 v179, -v161, v178, 1.0
	v_fmac_f32_e32 v178, v179, v178
	v_div_scale_f32 v179, vcc, 1.0, v160, 1.0
	v_mul_f32_e32 v183, v179, v178
	v_fma_f32 v185, -v161, v183, v179
	v_fmac_f32_e32 v183, v185, v178
	v_pk_fma_f32 v[136:137], v[182:183], v[92:93], v[136:137] op_sel_hi:[0,1,1]
	v_pk_fma_f32 v[198:199], v[182:183], v[94:95], v[198:199] op_sel_hi:[0,1,1]
	v_pk_fma_f32 v[136:137], v[184:185], v[88:89], v[136:137] op_sel_hi:[0,1,1]
	v_pk_fma_f32 v[198:199], v[184:185], v[80:81], v[198:199] op_sel_hi:[0,1,1]
	v_pk_fma_f32 v[136:137], v[186:187], v[86:87], v[136:137] op_sel_hi:[0,1,1]
	v_pk_fma_f32 v[198:199], v[186:187], v[72:73], v[198:199] op_sel_hi:[0,1,1]
	v_pk_fma_f32 v[136:137], v[188:189], v[84:85], v[136:137] op_sel_hi:[0,1,1]
	v_pk_fma_f32 v[198:199], v[188:189], v[64:65], v[198:199] op_sel_hi:[0,1,1]
	v_pk_fma_f32 v[138:139], v[182:183], v[96:97], v[138:139] op_sel_hi:[0,1,1]
	v_pk_fma_f32 v[180:181], v[182:183], v[110:111], v[180:181] op_sel_hi:[0,1,1]
	v_pk_fma_f32 v[136:137], v[190:191], v[60:61], v[136:137] op_sel_hi:[0,1,1]
	v_pk_fma_f32 v[198:199], v[190:191], v[56:57], v[198:199] op_sel_hi:[0,1,1]
	v_pk_fma_f32 v[138:139], v[184:185], v[90:91], v[138:139] op_sel_hi:[0,1,1]
	v_pk_fma_f32 v[180:181], v[184:185], v[82:83], v[180:181] op_sel_hi:[0,1,1]
	v_pk_fma_f32 v[136:137], v[192:193], v[74:75], v[136:137] op_sel_hi:[0,1,1]
	v_pk_fma_f32 v[198:199], v[192:193], v[52:53], v[198:199] op_sel_hi:[0,1,1]
	v_pk_fma_f32 v[138:139], v[186:187], v[76:77], v[138:139] op_sel_hi:[0,1,1]
	v_pk_fma_f32 v[180:181], v[186:187], v[70:71], v[180:181] op_sel_hi:[0,1,1]
	v_fma_f32 v161, -v161, v183, v179
	v_pk_fma_f32 v[136:137], v[194:195], v[106:107], v[136:137] op_sel_hi:[0,1,1]
	v_pk_fma_f32 v[198:199], v[194:195], v[48:49], v[198:199] op_sel_hi:[0,1,1]
	v_pk_fma_f32 v[138:139], v[188:189], v[68:69], v[138:139] op_sel_hi:[0,1,1]
	v_pk_fma_f32 v[180:181], v[188:189], v[66:67], v[180:181] op_sel_hi:[0,1,1]
	v_div_fmas_f32 v161, v161, v178, v183
	v_pk_fma_f32 v[200:201], v[196:197], v[120:121], v[136:137] op_sel_hi:[0,1,1]
	s_waitcnt vmcnt(15)
; __device__ __forceinline__ unsigned cvt_pk_bf16(float lo, float hi) { const f32x2 v = (f32x2){lo, hi}; return __builtin_bit_cast(unsigned, __builtin_convertvector(v, bf16v2)); }
; __device__ __forceinline__ float bf_lo(unsigned w) { return __uint_as_float(w << 16); }
; __device__ __forceinline__ float bf_hi(unsigned w) { return __uint_as_float(w & 0xffff0000u); }
; __device__ __forceinline__ void phase_mixer(const Params& p, LAS unsigned char* lds, int l, bool with_ctx, int G, int tid, int wave, int lane, int rep_attn, int rep_pool) {
;     ...
;         for (int o = 0; o < 16; ++o) {
;             const int t = t0 + o, st = max(t - lo, 0), en = min(t + hi + 1, len);
;             float acc[8];
; #pragma unroll
;             for (int e = 0; e < 8; ++e) acc[e] = 0.f;
; #pragma unroll
;             for (int i = 0; i < 16; ++i) { const int tt = t + i - 8; const float wt = (tt >= st && tt < en) ? 1.f : 0.f; const u32x4 ww = w[o + i];
;                 acc[0] += wt * bf_lo(ww.x); acc[1] += wt * bf_hi(ww.x); acc[2] += wt * bf_lo(ww.y); acc[3] += wt * bf_hi(ww.y);
;                 acc[4] += wt * bf_lo(ww.z); acc[5] += wt * bf_hi(ww.z); acc[6] += wt * bf_lo(ww.w); acc[7] += wt * bf_hi(ww.w); }
;             const float ic = 1.f / (float)(en - st);
;             const u32x4 sw = w[o + 8];
;             u32x4 ov; ov.x = cvt_pk_bf16(acc[0] * ic - bf_lo(sw.x), acc[1] * ic - bf_hi(sw.x)); ov.y = cvt_pk_bf16(acc[2] * ic - bf_lo(sw.y), acc[3] * ic - bf_hi(sw.y));
;             ov.z = cvt_pk_bf16(acc[4] * ic - bf_lo(sw.z), acc[5] * ic - bf_hi(sw.z)); ov.w = cvt_pk_bf16(acc[6] * ic - bf_lo(sw.w), acc[7] * ic - bf_hi(sw.w));
;             *(u32x4*)(MIX + (size_t)(tok0 + o) * DM + 8 * lane) = ov;
	v_lshlrev_b32_e32 v136, 16, v40
	v_and_b32_e32 v137, 0xffff0000, v40
	v_pk_fma_f32 v[198:199], v[196:197], v[44:45], v[198:199] op_sel_hi:[0,1,1]
	v_lshlrev_b32_e32 v40, 16, v41
	v_and_b32_e32 v41, 0xffff0000, v41
	v_pk_fma_f32 v[138:139], v[190:191], v[62:63], v[138:139] op_sel_hi:[0,1,1]
	v_pk_fma_f32 v[180:181], v[190:191], v[58:59], v[180:181] op_sel_hi:[0,1,1]
	v_div_fixup_f32 v178, v161, v160, 1.0
	v_pk_fma_f32 v[200:201], v[156:157], v[136:137], v[200:201] op_sel_hi:[0,1,1]
	v_pk_fma_f32 v[198:199], v[156:157], v[40:41], v[198:199] op_sel_hi:[0,1,1]
	v_pk_fma_f32 v[138:139], v[192:193], v[78:79], v[138:139] op_sel_hi:[0,1,1]
	v_pk_fma_f32 v[180:181], v[192:193], v[54:55], v[180:181] op_sel_hi:[0,1,1]
	v_pk_fma_f32 v[200:201], v[178:179], v[200:201], v[88:89] op_sel_hi:[0,1,1] neg_lo:[0,0,1] neg_hi:[0,0,1]
	v_pk_fma_f32 v[198:199], v[178:179], v[198:199], v[80:81] op_sel_hi:[0,1,1] neg_lo:[0,0,1] neg_hi:[0,0,1]
	v_pk_fma_f32 v[138:139], v[194:195], v[108:109], v[138:139] op_sel_hi:[0,1,1]
	v_pk_fma_f32 v[180:181], v[194:195], v[50:51], v[180:181] op_sel_hi:[0,1,1]
	v_cvt_pk_bf16_f32 v200, v200, v201
	v_cvt_pk_bf16_f32 v201, v198, v199
	v_pk_fma_f32 v[198:199], v[196:197], v[122:123], v[138:139] op_sel_hi:[0,1,1]
	v_lshlrev_b32_e32 v138, 16, v42
	v_and_b32_e32 v139, 0xffff0000, v42
	v_pk_fma_f32 v[180:181], v[196:197], v[46:47], v[180:181] op_sel_hi:[0,1,1]
	v_lshlrev_b32_e32 v42, 16, v43
	v_and_b32_e32 v43, 0xffff0000, v43
	v_pk_fma_f32 v[198:199], v[156:157], v[138:139], v[198:199] op_sel_hi:[0,1,1]
	v_pk_fma_f32 v[180:181], v[156:157], v[42:43], v[180:181] op_sel_hi:[0,1,1]
	v_sub_u32_e32 v156, s19, v167
	v_add_u32_e32 v160, s19, v167
	v_pk_fma_f32 v[198:199], v[178:179], v[198:199], v[90:91] op_sel_hi:[0,1,1] neg_lo:[0,0,1] neg_hi:[0,0,1]
	v_pk_fma_f32 v[178:179], v[178:179], v[180:181], v[82:83] op_sel_hi:[0,1,1] neg_lo:[0,0,1] neg_hi:[0,0,1]
	v_max_i32_e32 v161, 0, v156
	v_min_i32_e32 v160, s9, v160
	v_cvt_pk_bf16_f32 v203, v178, v179
	v_lshl_add_u64 v[178:179], v[126:127], 0, s[0:1]
	v_cmp_ge_i32_e32 vcc, s28, v161
	v_cmp_lt_i32_e64 s[0:1], s28, v160
	s_and_b64 s[0:1], vcc, s[0:1]
	v_cmp_ge_i32_e32 vcc, s27, v161
	v_cndmask_b32_e64 v156, 0, 1.0, s[0:1]
	v_cmp_lt_i32_e64 s[0:1], s27, v160
	v_cvt_pk_bf16_f32 v202, v198, v199
	s_and_b64 s[0:1], vcc, s[0:1]
	global_store_dwordx4 v[178:179], v[200:203], off
	v_cndmask_b32_e64 v178, 0, 1.0, s[0:1]
	v_cmp_ge_i32_e32 vcc, s8, v161
	v_cmp_lt_i32_e64 s[0:1], s8, v160
	s_and_b64 s[0:1], vcc, s[0:1]
	v_cmp_ge_i32_e32 vcc, s26, v161
	v_cndmask_b32_e64 v180, 0, 1.0, s[0:1]
	v_cmp_lt_i32_e64 s[0:1], s26, v160
	s_and_b64 s[0:1], vcc, s[0:1]
	v_cmp_ge_i32_e32 vcc, s23, v161
	v_cndmask_b32_e64 v182, 0, 1.0, s[0:1]
	v_cmp_lt_i32_e64 s[0:1], s23, v160
	s_and_b64 s[0:1], vcc, s[0:1]
	v_pk_fma_f32 v[150:151], v[156:157], v[150:151], 0 op_sel_hi:[0,1,0]
	v_cndmask_b32_e64 v184, 0, 1.0, s[0:1]
	v_cmp_ge_i32_e32 vcc, s22, v161
	v_cmp_lt_i32_e64 s[0:1], s22, v160
	v_pk_fma_f32 v[150:151], v[178:179], v[144:145], v[150:151] op_sel_hi:[0,1,1]
	s_and_b64 s[0:1], vcc, s[0:1]
	v_pk_fma_f32 v[150:151], v[180:181], v[154:155], v[150:151] op_sel_hi:[0,1,1]
	v_cndmask_b32_e64 v186, 0, 1.0, s[0:1]
	v_cmp_ge_i32_e32 vcc, s21, v161
	v_cmp_lt_i32_e64 s[0:1], s21, v160
	v_pk_fma_f32 v[150:151], v[182:183], v[130:131], v[150:151] op_sel_hi:[0,1,1]
	s_and_b64 s[0:1], vcc, s[0:1]
	v_pk_fma_f32 v[150:151], v[184:185], v[102:103], v[150:151] op_sel_hi:[0,1,1]
	v_cndmask_b32_e64 v188, 0, 1.0, s[0:1]
	v_pk_fma_f32 v[150:151], v[186:187], v[114:115], v[150:151] op_sel_hi:[0,1,1]
	v_cmp_ge_i32_e32 vcc, s20, v161
	v_cmp_lt_i32_e64 s[0:1], s20, v160
	v_pk_fma_f32 v[148:149], v[156:157], v[148:149], 0 op_sel_hi:[0,1,0]
	v_pk_fma_f32 v[194:195], v[188:189], v[94:95], v[150:151] op_sel_hi:[0,1,1]
	v_pk_fma_f32 v[150:151], v[156:157], v[174:175], 0 op_sel_hi:[0,1,0]
	v_pk_fma_f32 v[174:175], v[156:157], v[176:177], 0 op_sel_hi:[0,1,0]
	s_and_b64 s[0:1], vcc, s[0:1]
	v_pk_fma_f32 v[148:149], v[178:179], v[146:147], v[148:149] op_sel_hi:[0,1,1]
	v_pk_fma_f32 v[150:151], v[178:179], v[142:143], v[150:151] op_sel_hi:[0,1,1]
	v_pk_fma_f32 v[174:175], v[178:179], v[140:141], v[174:175] op_sel_hi:[0,1,1]
	v_cndmask_b32_e64 v178, 0, 1.0, s[0:1]
	v_cmp_ge_i32_e32 vcc, s19, v161
	v_cmp_lt_i32_e64 s[0:1], s19, v160
	s_and_b64 s[0:1], vcc, s[0:1]
	v_pk_fma_f32 v[148:149], v[180:181], v[152:153], v[148:149] op_sel_hi:[0,1,1]
	v_pk_fma_f32 v[150:151], v[180:181], v[170:171], v[150:151] op_sel_hi:[0,1,1]
	v_pk_fma_f32 v[174:175], v[180:181], v[172:173], v[174:175] op_sel_hi:[0,1,1]
	v_cndmask_b32_e64 v180, 0, 1.0, s[0:1]
	v_cmp_ge_i32_e32 vcc, s10, v161
	v_cmp_lt_i32_e64 s[0:1], s10, v160
	s_and_b64 s[0:1], vcc, s[0:1]
	v_pk_fma_f32 v[148:149], v[182:183], v[132:133], v[148:149] op_sel_hi:[0,1,1]
	v_pk_fma_f32 v[150:151], v[182:183], v[128:129], v[150:151] op_sel_hi:[0,1,1]
	v_pk_fma_f32 v[174:175], v[182:183], v[118:119], v[174:175] op_sel_hi:[0,1,1]
	v_cndmask_b32_e64 v182, 0, 1.0, s[0:1]
	v_cmp_ge_i32_e32 vcc, s11, v161
	v_cmp_lt_i32_e64 s[0:1], s11, v160
	s_and_b64 s[0:1], vcc, s[0:1]
	v_pk_fma_f32 v[148:149], v[184:185], v[104:105], v[148:149] op_sel_hi:[0,1,1]
	v_pk_fma_f32 v[150:151], v[184:185], v[100:101], v[150:151] op_sel_hi:[0,1,1]
	v_pk_fma_f32 v[174:175], v[184:185], v[98:99], v[174:175] op_sel_hi:[0,1,1]
	v_cndmask_b32_e64 v184, 0, 1.0, s[0:1]
	v_cmp_ge_i32_e32 vcc, s12, v161
	v_cmp_lt_i32_e64 s[0:1], s12, v160
	s_and_b64 s[0:1], vcc, s[0:1]
	v_pk_fma_f32 v[148:149], v[186:187], v[112:113], v[148:149] op_sel_hi:[0,1,1]
	v_pk_fma_f32 v[150:151], v[186:187], v[116:117], v[150:151] op_sel_hi:[0,1,1]
; __device__ __forceinline__ unsigned cvt_pk_bf16(float lo, float hi) { const f32x2 v = (f32x2){lo, hi}; return __builtin_bit_cast(unsigned, __builtin_convertvector(v, bf16v2)); }
; __device__ __forceinline__ float bf_lo(unsigned w) { return __uint_as_float(w << 16); }
; __device__ __forceinline__ float bf_hi(unsigned w) { return __uint_as_float(w & 0xffff0000u); }
; __device__ __forceinline__ void phase_mixer(const Params& p, LAS unsigned char* lds, int l, bool with_ctx, int G, int tid, int wave, int lane, int rep_attn, int rep_pool) {
;     ...
;         for (int o = 0; o < 16; ++o) {
;             const int t = t0 + o, st = max(t - lo, 0), en = min(t + hi + 1, len);
;             float acc[8];
; #pragma unroll
;             for (int e = 0; e < 8; ++e) acc[e] = 0.f;
; #pragma unroll
;             for (int i = 0; i < 16; ++i) { const int tt = t + i - 8; const float wt = (tt >= st && tt < en) ? 1.f : 0.f; const u32x4 ww = w[o + i];
;                 acc[0] += wt * bf_lo(ww.x); acc[1] += wt * bf_hi(ww.x); acc[2] += wt * bf_lo(ww.y); acc[3] += wt * bf_hi(ww.y);
;                 acc[4] += wt * bf_lo(ww.z); acc[5] += wt * bf_hi(ww.z); acc[6] += wt * bf_lo(ww.w); acc[7] += wt * bf_hi(ww.w); }
;             const float ic = 1.f / (float)(en - st);
;             const u32x4 sw = w[o + 8];
;             u32x4 ov; ov.x = cvt_pk_bf16(acc[0] * ic - bf_lo(sw.x), acc[1] * ic - bf_hi(sw.x)); ov.y = cvt_pk_bf16(acc[2] * ic - bf_lo(sw.y), acc[3] * ic - bf_hi(sw.y));
;             ov.z = cvt_pk_bf16(acc[4] * ic - bf_lo(sw.z), acc[5] * ic - bf_hi(sw.z)); ov.w = cvt_pk_bf16(acc[6] * ic - bf_lo(sw.w), acc[7] * ic - bf_hi(sw.w));
;             *(u32x4*)(MIX + (size_t)(tok0 + o) * DM + 8 * lane) = ov;
	v_pk_fma_f32 v[174:175], v[186:187], v[134:135], v[174:175] op_sel_hi:[0,1,1]
	v_cndmask_b32_e64 v186, 0, 1.0, s[0:1]
	v_cmp_ge_i32_e32 vcc, s13, v161
	v_cmp_lt_i32_e64 s[0:1], s13, v160
	s_and_b64 s[0:1], vcc, s[0:1]
	v_pk_fma_f32 v[148:149], v[188:189], v[92:93], v[148:149] op_sel_hi:[0,1,1]
	v_pk_fma_f32 v[150:151], v[188:189], v[96:97], v[150:151] op_sel_hi:[0,1,1]
	v_pk_fma_f32 v[176:177], v[188:189], v[110:111], v[174:175] op_sel_hi:[0,1,1]
	v_cndmask_b32_e64 v188, 0, 1.0, s[0:1]
	v_cmp_ge_i32_e32 vcc, s14, v161
	v_cmp_lt_i32_e64 s[0:1], s14, v160
	s_and_b64 s[0:1], vcc, s[0:1]
	v_cmp_ge_i32_e32 vcc, s15, v161
	v_cndmask_b32_e64 v190, 0, 1.0, s[0:1]
	v_cmp_lt_i32_e64 s[0:1], s15, v160
	s_and_b64 s[0:1], vcc, s[0:1]
	v_cmp_ge_i32_e32 vcc, s17, v161
	v_cndmask_b32_e64 v192, 0, 1.0, s[0:1]
	v_cmp_lt_i32_e64 s[0:1], s17, v160
	v_sub_u32_e32 v160, v160, v161
	v_cvt_f32_i32_e32 v160, v160
	s_and_b64 s[0:1], vcc, s[0:1]
	v_cndmask_b32_e64 v156, 0, 1.0, s[0:1]
	v_div_scale_f32 v161, s[0:1], v160, v160, 1.0
	v_rcp_f32_e32 v174, v161
	s_or_b32 s0, s4, 6
	s_ashr_i32 s1, s0, 31
	s_lshl_b64 s[0:1], s[0:1], 11
	v_fma_f32 v175, -v161, v174, 1.0
	v_fmac_f32_e32 v174, v175, v174
	v_div_scale_f32 v175, vcc, 1.0, v160, 1.0
	v_mul_f32_e32 v179, v175, v174
	v_fma_f32 v181, -v161, v179, v175
	v_fmac_f32_e32 v179, v181, v174
	v_pk_fma_f32 v[148:149], v[178:179], v[88:89], v[148:149] op_sel_hi:[0,1,1]
	v_pk_fma_f32 v[194:195], v[178:179], v[80:81], v[194:195] op_sel_hi:[0,1,1]
	v_pk_fma_f32 v[148:149], v[180:181], v[86:87], v[148:149] op_sel_hi:[0,1,1]
	v_pk_fma_f32 v[194:195], v[180:181], v[72:73], v[194:195] op_sel_hi:[0,1,1]
	v_pk_fma_f32 v[148:149], v[182:183], v[84:85], v[148:149] op_sel_hi:[0,1,1]
	v_pk_fma_f32 v[194:195], v[182:183], v[64:65], v[194:195] op_sel_hi:[0,1,1]
	v_pk_fma_f32 v[148:149], v[184:185], v[60:61], v[148:149] op_sel_hi:[0,1,1]
	v_pk_fma_f32 v[194:195], v[184:185], v[56:57], v[194:195] op_sel_hi:[0,1,1]
	v_pk_fma_f32 v[150:151], v[178:179], v[90:91], v[150:151] op_sel_hi:[0,1,1]
	v_pk_fma_f32 v[176:177], v[178:179], v[82:83], v[176:177] op_sel_hi:[0,1,1]
	v_pk_fma_f32 v[148:149], v[186:187], v[74:75], v[148:149] op_sel_hi:[0,1,1]
	v_pk_fma_f32 v[194:195], v[186:187], v[52:53], v[194:195] op_sel_hi:[0,1,1]
	v_pk_fma_f32 v[150:151], v[180:181], v[76:77], v[150:151] op_sel_hi:[0,1,1]
	v_pk_fma_f32 v[176:177], v[180:181], v[70:71], v[176:177] op_sel_hi:[0,1,1]
	v_pk_fma_f32 v[148:149], v[188:189], v[106:107], v[148:149] op_sel_hi:[0,1,1]
	v_pk_fma_f32 v[194:195], v[188:189], v[48:49], v[194:195] op_sel_hi:[0,1,1]
	v_pk_fma_f32 v[150:151], v[182:183], v[68:69], v[150:151] op_sel_hi:[0,1,1]
	v_pk_fma_f32 v[176:177], v[182:183], v[66:67], v[176:177] op_sel_hi:[0,1,1]
	v_fma_f32 v161, -v161, v179, v175
	v_pk_fma_f32 v[148:149], v[190:191], v[120:121], v[148:149] op_sel_hi:[0,1,1]
	v_pk_fma_f32 v[194:195], v[190:191], v[44:45], v[194:195] op_sel_hi:[0,1,1]
	v_pk_fma_f32 v[150:151], v[184:185], v[62:63], v[150:151] op_sel_hi:[0,1,1]
	v_pk_fma_f32 v[176:177], v[184:185], v[58:59], v[176:177] op_sel_hi:[0,1,1]
	v_div_fmas_f32 v161, v161, v174, v179
	v_pk_fma_f32 v[196:197], v[192:193], v[136:137], v[148:149] op_sel_hi:[0,1,1]
	s_waitcnt vmcnt(15)
	v_lshlrev_b32_e32 v148, 16, v36
	v_and_b32_e32 v149, 0xffff0000, v36
	v_pk_fma_f32 v[194:195], v[192:193], v[40:41], v[194:195] op_sel_hi:[0,1,1]
	v_lshlrev_b32_e32 v36, 16, v37
	v_and_b32_e32 v37, 0xffff0000, v37
	v_pk_fma_f32 v[150:151], v[186:187], v[78:79], v[150:151] op_sel_hi:[0,1,1]
	v_pk_fma_f32 v[176:177], v[186:187], v[54:55], v[176:177] op_sel_hi:[0,1,1]
	v_div_fixup_f32 v174, v161, v160, 1.0
	v_pk_fma_f32 v[196:197], v[156:157], v[148:149], v[196:197] op_sel_hi:[0,1,1]
	v_pk_fma_f32 v[194:195], v[156:157], v[36:37], v[194:195] op_sel_hi:[0,1,1]
	v_pk_fma_f32 v[150:151], v[188:189], v[108:109], v[150:151] op_sel_hi:[0,1,1]
	v_pk_fma_f32 v[176:177], v[188:189], v[50:51], v[176:177] op_sel_hi:[0,1,1]
	v_pk_fma_f32 v[196:197], v[174:175], v[196:197], v[86:87] op_sel_hi:[0,1,1] neg_lo:[0,0,1] neg_hi:[0,0,1]
	v_pk_fma_f32 v[194:195], v[174:175], v[194:195], v[72:73] op_sel_hi:[0,1,1] neg_lo:[0,0,1] neg_hi:[0,0,1]
	v_pk_fma_f32 v[150:151], v[190:191], v[122:123], v[150:151] op_sel_hi:[0,1,1]
	v_pk_fma_f32 v[176:177], v[190:191], v[46:47], v[176:177] op_sel_hi:[0,1,1]
	v_cvt_pk_bf16_f32 v196, v196, v197
	v_cvt_pk_bf16_f32 v197, v194, v195
	v_pk_fma_f32 v[194:195], v[192:193], v[138:139], v[150:151] op_sel_hi:[0,1,1]
	v_lshlrev_b32_e32 v150, 16, v38
	v_and_b32_e32 v151, 0xffff0000, v38
	v_pk_fma_f32 v[176:177], v[192:193], v[42:43], v[176:177] op_sel_hi:[0,1,1]
	v_lshlrev_b32_e32 v38, 16, v39
	v_and_b32_e32 v39, 0xffff0000, v39
	v_pk_fma_f32 v[194:195], v[156:157], v[150:151], v[194:195] op_sel_hi:[0,1,1]
	v_pk_fma_f32 v[176:177], v[156:157], v[38:39], v[176:177] op_sel_hi:[0,1,1]
	v_sub_u32_e32 v156, s10, v167
	v_add_u32_e32 v160, s10, v167
	v_pk_fma_f32 v[194:195], v[174:175], v[194:195], v[76:77] op_sel_hi:[0,1,1] neg_lo:[0,0,1] neg_hi:[0,0,1]
	v_pk_fma_f32 v[174:175], v[174:175], v[176:177], v[70:71] op_sel_hi:[0,1,1] neg_lo:[0,0,1] neg_hi:[0,0,1]
	v_max_i32_e32 v161, 0, v156
	v_min_i32_e32 v160, s9, v160
	v_cvt_pk_bf16_f32 v199, v174, v175
	v_lshl_add_u64 v[174:175], v[126:127], 0, s[0:1]
	v_cmp_ge_i32_e32 vcc, s27, v161
	v_cmp_lt_i32_e64 s[0:1], s27, v160
	s_and_b64 s[0:1], vcc, s[0:1]
	v_cmp_ge_i32_e32 vcc, s8, v161
	v_cndmask_b32_e64 v156, 0, 1.0, s[0:1]
	v_cmp_lt_i32_e64 s[0:1], s8, v160
	v_cvt_pk_bf16_f32 v198, v194, v195
	s_and_b64 s[0:1], vcc, s[0:1]
	global_store_dwordx4 v[174:175], v[196:199], off
	v_cndmask_b32_e64 v174, 0, 1.0, s[0:1]
	v_cmp_ge_i32_e32 vcc, s26, v161
; __device__ __forceinline__ unsigned cvt_pk_bf16(float lo, float hi) { const f32x2 v = (f32x2){lo, hi}; return __builtin_bit_cast(unsigned, __builtin_convertvector(v, bf16v2)); }
; __device__ __forceinline__ float bf_lo(unsigned w) { return __uint_as_float(w << 16); }
; __device__ __forceinline__ float bf_hi(unsigned w) { return __uint_as_float(w & 0xffff0000u); }
; __device__ __forceinline__ void phase_mixer(const Params& p, LAS unsigned char* lds, int l, bool with_ctx, int G, int tid, int wave, int lane, int rep_attn, int rep_pool) {
;     ...
;         for (int o = 0; o < 16; ++o) {
;             const int t = t0 + o, st = max(t - lo, 0), en = min(t + hi + 1, len);
;             float acc[8];
; #pragma unroll
;             for (int e = 0; e < 8; ++e) acc[e] = 0.f;
; #pragma unroll
;             for (int i = 0; i < 16; ++i) { const int tt = t + i - 8; const float wt = (tt >= st && tt < en) ? 1.f : 0.f; const u32x4 ww = w[o + i];
;                 acc[0] += wt * bf_lo(ww.x); acc[1] += wt * bf_hi(ww.x); acc[2] += wt * bf_lo(ww.y); acc[3] += wt * bf_hi(ww.y);
;                 acc[4] += wt * bf_lo(ww.z); acc[5] += wt * bf_hi(ww.z); acc[6] += wt * bf_lo(ww.w); acc[7] += wt * bf_hi(ww.w); }
;             const float ic = 1.f / (float)(en - st);
;             const u32x4 sw = w[o + 8];
;             u32x4 ov; ov.x = cvt_pk_bf16(acc[0] * ic - bf_lo(sw.x), acc[1] * ic - bf_hi(sw.x)); ov.y = cvt_pk_bf16(acc[2] * ic - bf_lo(sw.y), acc[3] * ic - bf_hi(sw.y));
	v_cmp_lt_i32_e64 s[0:1], s26, v160
	s_and_b64 s[0:1], vcc, s[0:1]
	v_cmp_ge_i32_e32 vcc, s23, v161
	v_cndmask_b32_e64 v176, 0, 1.0, s[0:1]
	v_cmp_lt_i32_e64 s[0:1], s23, v160
	s_and_b64 s[0:1], vcc, s[0:1]
	v_cmp_ge_i32_e32 vcc, s22, v161
	v_cndmask_b32_e64 v178, 0, 1.0, s[0:1]
	v_cmp_lt_i32_e64 s[0:1], s22, v160
	s_and_b64 s[0:1], vcc, s[0:1]
	v_cmp_ge_i32_e32 vcc, s21, v161
	v_cndmask_b32_e64 v180, 0, 1.0, s[0:1]
	v_cmp_lt_i32_e64 s[0:1], s21, v160
	s_and_b64 s[0:1], vcc, s[0:1]
	v_cmp_ge_i32_e32 vcc, s20, v161
	v_cndmask_b32_e64 v182, 0, 1.0, s[0:1]
	v_cmp_lt_i32_e64 s[0:1], s20, v160
	s_and_b64 s[0:1], vcc, s[0:1]
	v_pk_fma_f32 v[146:147], v[156:157], v[146:147], 0 op_sel_hi:[0,1,0]
	v_cndmask_b32_e64 v184, 0, 1.0, s[0:1]
	v_pk_fma_f32 v[144:145], v[156:157], v[144:145], 0 op_sel_hi:[0,1,0]
	v_pk_fma_f32 v[142:143], v[156:157], v[142:143], 0 op_sel_hi:[0,1,0]
	v_pk_fma_f32 v[140:141], v[156:157], v[140:141], 0 op_sel_hi:[0,1,0]
	v_cmp_ge_i32_e32 vcc, s19, v161
	v_cmp_lt_i32_e64 s[0:1], s19, v160
	v_pk_fma_f32 v[146:147], v[174:175], v[152:153], v[146:147] op_sel_hi:[0,1,1]
	v_pk_fma_f32 v[144:145], v[174:175], v[154:155], v[144:145] op_sel_hi:[0,1,1]
	v_pk_fma_f32 v[142:143], v[174:175], v[170:171], v[142:143] op_sel_hi:[0,1,1]
	v_pk_fma_f32 v[140:141], v[174:175], v[172:173], v[140:141] op_sel_hi:[0,1,1]
	s_and_b64 s[0:1], vcc, s[0:1]
	v_pk_fma_f32 v[146:147], v[176:177], v[132:133], v[146:147] op_sel_hi:[0,1,1]
	v_pk_fma_f32 v[144:145], v[176:177], v[130:131], v[144:145] op_sel_hi:[0,1,1]
	v_pk_fma_f32 v[142:143], v[176:177], v[128:129], v[142:143] op_sel_hi:[0,1,1]
	v_pk_fma_f32 v[140:141], v[176:177], v[118:119], v[140:141] op_sel_hi:[0,1,1]
	v_cndmask_b32_e64 v176, 0, 1.0, s[0:1]
	v_cmp_ge_i32_e32 vcc, s10, v161
	v_cmp_lt_i32_e64 s[0:1], s10, v160
	s_and_b64 s[0:1], vcc, s[0:1]
	v_pk_fma_f32 v[146:147], v[178:179], v[104:105], v[146:147] op_sel_hi:[0,1,1]
	v_pk_fma_f32 v[144:145], v[178:179], v[102:103], v[144:145] op_sel_hi:[0,1,1]
	v_pk_fma_f32 v[142:143], v[178:179], v[100:101], v[142:143] op_sel_hi:[0,1,1]
	v_pk_fma_f32 v[140:141], v[178:179], v[98:99], v[140:141] op_sel_hi:[0,1,1]
	v_cndmask_b32_e64 v178, 0, 1.0, s[0:1]
	v_cmp_ge_i32_e32 vcc, s11, v161
	v_cmp_lt_i32_e64 s[0:1], s11, v160
	s_and_b64 s[0:1], vcc, s[0:1]
	v_pk_fma_f32 v[146:147], v[180:181], v[112:113], v[146:147] op_sel_hi:[0,1,1]
	v_pk_fma_f32 v[144:145], v[180:181], v[114:115], v[144:145] op_sel_hi:[0,1,1]
	v_pk_fma_f32 v[142:143], v[180:181], v[116:117], v[142:143] op_sel_hi:[0,1,1]
	v_pk_fma_f32 v[140:141], v[180:181], v[134:135], v[140:141] op_sel_hi:[0,1,1]
	v_cndmask_b32_e64 v180, 0, 1.0, s[0:1]
	v_cmp_ge_i32_e32 vcc, s12, v161
	v_cmp_lt_i32_e64 s[0:1], s12, v160
	s_and_b64 s[0:1], vcc, s[0:1]
	v_pk_fma_f32 v[146:147], v[182:183], v[92:93], v[146:147] op_sel_hi:[0,1,1]
	v_pk_fma_f32 v[144:145], v[182:183], v[94:95], v[144:145] op_sel_hi:[0,1,1]
	v_pk_fma_f32 v[142:143], v[182:183], v[96:97], v[142:143] op_sel_hi:[0,1,1]
	v_pk_fma_f32 v[140:141], v[182:183], v[110:111], v[140:141] op_sel_hi:[0,1,1]
	v_cndmask_b32_e64 v182, 0, 1.0, s[0:1]
	v_cmp_ge_i32_e32 vcc, s13, v161
	v_cmp_lt_i32_e64 s[0:1], s13, v160
	s_and_b64 s[0:1], vcc, s[0:1]
	v_pk_fma_f32 v[196:197], v[184:185], v[88:89], v[146:147] op_sel_hi:[0,1,1]
	v_pk_fma_f32 v[194:195], v[184:185], v[80:81], v[144:145] op_sel_hi:[0,1,1]
	v_pk_fma_f32 v[192:193], v[184:185], v[90:91], v[142:143] op_sel_hi:[0,1,1]
	v_pk_fma_f32 v[174:175], v[184:185], v[82:83], v[140:141] op_sel_hi:[0,1,1]
	v_cndmask_b32_e64 v184, 0, 1.0, s[0:1]
	v_cmp_ge_i32_e32 vcc, s14, v161
	v_cmp_lt_i32_e64 s[0:1], s14, v160
	s_and_b64 s[0:1], vcc, s[0:1]
	v_cmp_ge_i32_e32 vcc, s15, v161
	v_cndmask_b32_e64 v186, 0, 1.0, s[0:1]
	v_cmp_lt_i32_e64 s[0:1], s15, v160
	s_and_b64 s[0:1], vcc, s[0:1]
	v_sub_u32_e32 v140, v160, v161
	v_cndmask_b32_e64 v188, 0, 1.0, s[0:1]
	v_cmp_ge_i32_e32 vcc, s17, v161
	v_cmp_lt_i32_e64 s[0:1], s17, v160
	v_cvt_f32_i32_e32 v140, v140
	s_and_b64 s[0:1], vcc, s[0:1]
	v_cndmask_b32_e64 v190, 0, 1.0, s[0:1]
	v_cmp_ge_i32_e32 vcc, s16, v161
	v_cmp_lt_i32_e64 s[0:1], s16, v160
	s_and_b64 s[0:1], vcc, s[0:1]
	s_nop 0
	v_cndmask_b32_e64 v146, 0, 1.0, s[0:1]
	v_div_scale_f32 v141, s[0:1], v140, v140, 1.0
	v_rcp_f32_e32 v142, v141
	s_or_b32 s0, s4, 7
	s_ashr_i32 s1, s0, 31
	s_lshl_b64 s[0:1], s[0:1], 11
	v_fma_f32 v143, -v141, v142, 1.0
	v_fmac_f32_e32 v142, v143, v142
	v_div_scale_f32 v143, vcc, 1.0, v140, 1.0
	v_mul_f32_e32 v144, v143, v142
	v_fma_f32 v145, -v141, v144, v143
	v_fmac_f32_e32 v144, v145, v142
	v_fma_f32 v141, -v141, v144, v143
	v_div_fmas_f32 v141, v141, v142, v144
	v_div_fixup_f32 v156, v141, v140, 1.0
	v_pk_fma_f32 v[140:141], v[176:177], v[86:87], v[196:197] op_sel_hi:[0,1,1]
	v_pk_fma_f32 v[140:141], v[178:179], v[84:85], v[140:141] op_sel_hi:[0,1,1]
	v_pk_fma_f32 v[140:141], v[180:181], v[60:61], v[140:141] op_sel_hi:[0,1,1]
	v_pk_fma_f32 v[140:141], v[182:183], v[74:75], v[140:141] op_sel_hi:[0,1,1]
	v_pk_fma_f32 v[140:141], v[184:185], v[106:107], v[140:141] op_sel_hi:[0,1,1]
	v_pk_fma_f32 v[140:141], v[186:187], v[120:121], v[140:141] op_sel_hi:[0,1,1]
	v_pk_fma_f32 v[140:141], v[188:189], v[136:137], v[140:141] op_sel_hi:[0,1,1]
	v_pk_fma_f32 v[140:141], v[190:191], v[148:149], v[140:141] op_sel_hi:[0,1,1]
	s_waitcnt vmcnt(15)
; __device__ __forceinline__ unsigned cvt_pk_bf16(float lo, float hi) { const f32x2 v = (f32x2){lo, hi}; return __builtin_bit_cast(unsigned, __builtin_convertvector(v, bf16v2)); }
; __device__ __forceinline__ float bf_lo(unsigned w) { return __uint_as_float(w << 16); }
; __device__ __forceinline__ float bf_hi(unsigned w) { return __uint_as_float(w & 0xffff0000u); }
; __device__ __forceinline__ void phase_mixer(const Params& p, LAS unsigned char* lds, int l, bool with_ctx, int G, int tid, int wave, int lane, int rep_attn, int rep_pool) {
;     ...
;         for (int o = 0; o < 16; ++o) {
;             const int t = t0 + o, st = max(t - lo, 0), en = min(t + hi + 1, len);
;             float acc[8];
; #pragma unroll
;             for (int e = 0; e < 8; ++e) acc[e] = 0.f;
; #pragma unroll
;             for (int i = 0; i < 16; ++i) { const int tt = t + i - 8; const float wt = (tt >= st && tt < en) ? 1.f : 0.f; const u32x4 ww = w[o + i];
;                 acc[0] += wt * bf_lo(ww.x); acc[1] += wt * bf_hi(ww.x); acc[2] += wt * bf_lo(ww.y); acc[3] += wt * bf_hi(ww.y);
;                 acc[4] += wt * bf_lo(ww.z); acc[5] += wt * bf_hi(ww.z); acc[6] += wt * bf_lo(ww.w); acc[7] += wt * bf_hi(ww.w); }
;             const float ic = 1.f / (float)(en - st);
;             const u32x4 sw = w[o + 8];
;             u32x4 ov; ov.x = cvt_pk_bf16(acc[0] * ic - bf_lo(sw.x), acc[1] * ic - bf_hi(sw.x)); ov.y = cvt_pk_bf16(acc[2] * ic - bf_lo(sw.y), acc[3] * ic - bf_hi(sw.y));
;             ov.z = cvt_pk_bf16(acc[4] * ic - bf_lo(sw.z), acc[5] * ic - bf_hi(sw.z)); ov.w = cvt_pk_bf16(acc[6] * ic - bf_lo(sw.w), acc[7] * ic - bf_hi(sw.w));
;             *(u32x4*)(MIX + (size_t)(tok0 + o) * DM + 8 * lane) = ov;
	v_lshlrev_b32_e32 v144, 16, v32
	v_and_b32_e32 v145, 0xffff0000, v32
	v_pk_fma_f32 v[140:141], v[146:147], v[144:145], v[140:141] op_sel_hi:[0,1,1]
	v_pk_fma_f32 v[140:141], v[156:157], v[140:141], v[84:85] op_sel_hi:[0,1,1] neg_lo:[0,0,1] neg_hi:[0,0,1]
	v_cvt_pk_bf16_f32 v196, v140, v141
	v_pk_fma_f32 v[140:141], v[176:177], v[72:73], v[194:195] op_sel_hi:[0,1,1]
	v_pk_fma_f32 v[140:141], v[178:179], v[64:65], v[140:141] op_sel_hi:[0,1,1]
	v_pk_fma_f32 v[140:141], v[180:181], v[56:57], v[140:141] op_sel_hi:[0,1,1]
	v_pk_fma_f32 v[140:141], v[182:183], v[52:53], v[140:141] op_sel_hi:[0,1,1]
	v_pk_fma_f32 v[140:141], v[184:185], v[48:49], v[140:141] op_sel_hi:[0,1,1]
	v_pk_fma_f32 v[140:141], v[186:187], v[44:45], v[140:141] op_sel_hi:[0,1,1]
	v_pk_fma_f32 v[140:141], v[188:189], v[40:41], v[140:141] op_sel_hi:[0,1,1]
	v_pk_fma_f32 v[140:141], v[190:191], v[36:37], v[140:141] op_sel_hi:[0,1,1]
	v_lshlrev_b32_e32 v142, 16, v33
	v_and_b32_e32 v143, 0xffff0000, v33
	v_pk_fma_f32 v[32:33], v[146:147], v[142:143], v[140:141] op_sel_hi:[0,1,1]
	v_pk_fma_f32 v[32:33], v[156:157], v[32:33], v[64:65] op_sel_hi:[0,1,1] neg_lo:[0,0,1] neg_hi:[0,0,1]
	v_cvt_pk_bf16_f32 v197, v32, v33
	v_pk_fma_f32 v[32:33], v[176:177], v[76:77], v[192:193] op_sel_hi:[0,1,1]
	v_pk_fma_f32 v[32:33], v[178:179], v[68:69], v[32:33] op_sel_hi:[0,1,1]
	v_pk_fma_f32 v[32:33], v[180:181], v[62:63], v[32:33] op_sel_hi:[0,1,1]
	v_pk_fma_f32 v[32:33], v[182:183], v[78:79], v[32:33] op_sel_hi:[0,1,1]
	v_pk_fma_f32 v[32:33], v[184:185], v[108:109], v[32:33] op_sel_hi:[0,1,1]
	v_pk_fma_f32 v[32:33], v[186:187], v[122:123], v[32:33] op_sel_hi:[0,1,1]
	v_pk_fma_f32 v[32:33], v[188:189], v[138:139], v[32:33] op_sel_hi:[0,1,1]
	v_pk_fma_f32 v[32:33], v[190:191], v[150:151], v[32:33] op_sel_hi:[0,1,1]
	v_lshlrev_b32_e32 v140, 16, v34
	v_and_b32_e32 v141, 0xffff0000, v34
	v_pk_fma_f32 v[32:33], v[146:147], v[140:141], v[32:33] op_sel_hi:[0,1,1]
	v_pk_fma_f32 v[32:33], v[156:157], v[32:33], v[68:69] op_sel_hi:[0,1,1] neg_lo:[0,0,1] neg_hi:[0,0,1]
	v_cvt_pk_bf16_f32 v198, v32, v33
	v_pk_fma_f32 v[32:33], v[176:177], v[70:71], v[174:175] op_sel_hi:[0,1,1]
	v_pk_fma_f32 v[32:33], v[178:179], v[66:67], v[32:33] op_sel_hi:[0,1,1]
	v_pk_fma_f32 v[32:33], v[180:181], v[58:59], v[32:33] op_sel_hi:[0,1,1]
	v_pk_fma_f32 v[32:33], v[182:183], v[54:55], v[32:33] op_sel_hi:[0,1,1]
	v_pk_fma_f32 v[32:33], v[184:185], v[50:51], v[32:33] op_sel_hi:[0,1,1]
	v_pk_fma_f32 v[32:33], v[186:187], v[46:47], v[32:33] op_sel_hi:[0,1,1]
	v_pk_fma_f32 v[32:33], v[188:189], v[42:43], v[32:33] op_sel_hi:[0,1,1]
	v_pk_fma_f32 v[174:175], v[190:191], v[38:39], v[32:33] op_sel_hi:[0,1,1]
	v_lshlrev_b32_e32 v32, 16, v35
	v_and_b32_e32 v33, 0xffff0000, v35
	v_pk_fma_f32 v[34:35], v[146:147], v[32:33], v[174:175] op_sel_hi:[0,1,1]
	v_pk_fma_f32 v[34:35], v[156:157], v[34:35], v[66:67] op_sel_hi:[0,1,1] neg_lo:[0,0,1] neg_hi:[0,0,1]
	v_cvt_pk_bf16_f32 v199, v34, v35
	v_lshl_add_u64 v[34:35], v[126:127], 0, s[0:1]
	global_store_dwordx4 v[34:35], v[196:199], off
	v_sub_u32_e32 v34, s11, v167
	v_add_u32_e32 v35, s11, v167
	v_max_i32_e32 v160, 0, v34
	v_min_i32_e32 v161, s9, v35
	v_cmp_ge_i32_e32 vcc, s8, v160
	v_cmp_lt_i32_e64 s[0:1], s8, v161
	s_and_b64 s[0:1], vcc, s[0:1]
	v_cmp_ge_i32_e32 vcc, s26, v160
	v_cndmask_b32_e64 v156, 0, 1.0, s[0:1]
	v_cmp_lt_i32_e64 s[0:1], s26, v161
	s_and_b64 s[0:1], vcc, s[0:1]
	v_cmp_ge_i32_e32 vcc, s23, v160
	v_cndmask_b32_e64 v174, 0, 1.0, s[0:1]
	v_cmp_lt_i32_e64 s[0:1], s23, v161
	s_and_b64 s[0:1], vcc, s[0:1]
	v_cmp_ge_i32_e32 vcc, s22, v160
	v_cndmask_b32_e64 v176, 0, 1.0, s[0:1]
	v_cmp_lt_i32_e64 s[0:1], s22, v161
	s_and_b64 s[0:1], vcc, s[0:1]
	v_cmp_ge_i32_e32 vcc, s21, v160
	v_cndmask_b32_e64 v178, 0, 1.0, s[0:1]
	v_cmp_lt_i32_e64 s[0:1], s21, v161
	s_and_b64 s[0:1], vcc, s[0:1]
	v_pk_fma_f32 v[34:35], v[156:157], v[152:153], 0 op_sel_hi:[0,1,0]
	v_cndmask_b32_e64 v180, 0, 1.0, s[0:1]
	v_cmp_ge_i32_e32 vcc, s20, v160
	v_cmp_lt_i32_e64 s[0:1], s20, v161
	v_pk_fma_f32 v[34:35], v[174:175], v[132:133], v[34:35] op_sel_hi:[0,1,1]
	s_and_b64 s[0:1], vcc, s[0:1]
	v_pk_fma_f32 v[34:35], v[176:177], v[104:105], v[34:35] op_sel_hi:[0,1,1]
	v_cndmask_b32_e64 v182, 0, 1.0, s[0:1]
	v_cmp_ge_i32_e32 vcc, s19, v160
	v_cmp_lt_i32_e64 s[0:1], s19, v161
	v_pk_fma_f32 v[34:35], v[178:179], v[112:113], v[34:35] op_sel_hi:[0,1,1]
	s_and_b64 s[0:1], vcc, s[0:1]
	v_pk_fma_f32 v[34:35], v[180:181], v[92:93], v[34:35] op_sel_hi:[0,1,1]
	v_cndmask_b32_e64 v184, 0, 1.0, s[0:1]
	v_pk_fma_f32 v[34:35], v[182:183], v[88:89], v[34:35] op_sel_hi:[0,1,1]
	v_pk_fma_f32 v[152:153], v[184:185], v[86:87], v[34:35] op_sel_hi:[0,1,1]
	v_pk_fma_f32 v[34:35], v[156:157], v[154:155], 0 op_sel_hi:[0,1,0]
	v_pk_fma_f32 v[34:35], v[174:175], v[130:131], v[34:35] op_sel_hi:[0,1,1]
	v_pk_fma_f32 v[34:35], v[176:177], v[102:103], v[34:35] op_sel_hi:[0,1,1]
	v_pk_fma_f32 v[34:35], v[178:179], v[114:115], v[34:35] op_sel_hi:[0,1,1]
	v_cmp_ge_i32_e32 vcc, s10, v160
	v_cmp_lt_i32_e64 s[0:1], s10, v161
	v_pk_fma_f32 v[34:35], v[180:181], v[94:95], v[34:35] op_sel_hi:[0,1,1]
	s_and_b64 s[0:1], vcc, s[0:1]
	v_pk_fma_f32 v[34:35], v[182:183], v[80:81], v[34:35] op_sel_hi:[0,1,1]
	v_pk_fma_f32 v[154:155], v[156:157], v[172:173], 0 op_sel_hi:[0,1,0]
	v_cndmask_b32_e64 v172, 0, 1.0, s[0:1]
	v_cmp_ge_i32_e32 vcc, s11, v160
	v_cmp_lt_i32_e64 s[0:1], s11, v161
	v_pk_fma_f32 v[146:147], v[184:185], v[72:73], v[34:35] op_sel_hi:[0,1,1]
	v_pk_fma_f32 v[34:35], v[156:157], v[170:171], 0 op_sel_hi:[0,1,0]
	s_and_b64 s[0:1], vcc, s[0:1]
	v_pk_fma_f32 v[34:35], v[174:175], v[128:129], v[34:35] op_sel_hi:[0,1,1]
; __device__ __forceinline__ unsigned cvt_pk_bf16(float lo, float hi) { const f32x2 v = (f32x2){lo, hi}; return __builtin_bit_cast(unsigned, __builtin_convertvector(v, bf16v2)); }
; __device__ __forceinline__ float bf_lo(unsigned w) { return __uint_as_float(w << 16); }
; __device__ __forceinline__ float bf_hi(unsigned w) { return __uint_as_float(w & 0xffff0000u); }
; __device__ __forceinline__ void phase_mixer(const Params& p, LAS unsigned char* lds, int l, bool with_ctx, int G, int tid, int wave, int lane, int rep_attn, int rep_pool) {
;     ...
;         for (int o = 0; o < 16; ++o) {
;             const int t = t0 + o, st = max(t - lo, 0), en = min(t + hi + 1, len);
;             float acc[8];
; #pragma unroll
;             for (int e = 0; e < 8; ++e) acc[e] = 0.f;
; #pragma unroll
;             for (int i = 0; i < 16; ++i) { const int tt = t + i - 8; const float wt = (tt >= st && tt < en) ? 1.f : 0.f; const u32x4 ww = w[o + i];
;                 acc[0] += wt * bf_lo(ww.x); acc[1] += wt * bf_hi(ww.x); acc[2] += wt * bf_lo(ww.y); acc[3] += wt * bf_hi(ww.y);
;                 acc[4] += wt * bf_lo(ww.z); acc[5] += wt * bf_hi(ww.z); acc[6] += wt * bf_lo(ww.w); acc[7] += wt * bf_hi(ww.w); }
;             const float ic = 1.f / (float)(en - st);
;             const u32x4 sw = w[o + 8];
;             u32x4 ov; ov.x = cvt_pk_bf16(acc[0] * ic - bf_lo(sw.x), acc[1] * ic - bf_hi(sw.x)); ov.y = cvt_pk_bf16(acc[2] * ic - bf_lo(sw.y), acc[3] * ic - bf_hi(sw.y));
	v_pk_fma_f32 v[154:155], v[174:175], v[118:119], v[154:155] op_sel_hi:[0,1,1]
	v_cndmask_b32_e64 v174, 0, 1.0, s[0:1]
	v_cmp_ge_i32_e32 vcc, s12, v160
	v_cmp_lt_i32_e64 s[0:1], s12, v161
	s_and_b64 s[0:1], vcc, s[0:1]
	v_pk_fma_f32 v[34:35], v[176:177], v[100:101], v[34:35] op_sel_hi:[0,1,1]
	v_pk_fma_f32 v[154:155], v[176:177], v[98:99], v[154:155] op_sel_hi:[0,1,1]
	v_cndmask_b32_e64 v176, 0, 1.0, s[0:1]
	v_cmp_ge_i32_e32 vcc, s13, v160
	v_cmp_lt_i32_e64 s[0:1], s13, v161
	s_and_b64 s[0:1], vcc, s[0:1]
	v_pk_fma_f32 v[34:35], v[178:179], v[116:117], v[34:35] op_sel_hi:[0,1,1]
	v_pk_fma_f32 v[154:155], v[178:179], v[134:135], v[154:155] op_sel_hi:[0,1,1]
	v_cndmask_b32_e64 v178, 0, 1.0, s[0:1]
	v_cmp_ge_i32_e32 vcc, s14, v160
	v_cmp_lt_i32_e64 s[0:1], s14, v161
	s_and_b64 s[0:1], vcc, s[0:1]
	v_pk_fma_f32 v[34:35], v[180:181], v[96:97], v[34:35] op_sel_hi:[0,1,1]
	v_pk_fma_f32 v[154:155], v[180:181], v[110:111], v[154:155] op_sel_hi:[0,1,1]
	v_cndmask_b32_e64 v180, 0, 1.0, s[0:1]
	v_cmp_ge_i32_e32 vcc, s15, v160
	v_cmp_lt_i32_e64 s[0:1], s15, v161
	s_and_b64 s[0:1], vcc, s[0:1]
	v_pk_fma_f32 v[34:35], v[182:183], v[90:91], v[34:35] op_sel_hi:[0,1,1]
	v_pk_fma_f32 v[154:155], v[182:183], v[82:83], v[154:155] op_sel_hi:[0,1,1]
	v_cndmask_b32_e64 v182, 0, 1.0, s[0:1]
	v_cmp_ge_i32_e32 vcc, s17, v160
	v_cmp_lt_i32_e64 s[0:1], s17, v161
	v_pk_fma_f32 v[170:171], v[184:185], v[70:71], v[154:155] op_sel_hi:[0,1,1]
	s_and_b64 s[0:1], vcc, s[0:1]
	v_sub_u32_e32 v155, v161, v160
	v_pk_fma_f32 v[34:35], v[184:185], v[76:77], v[34:35] op_sel_hi:[0,1,1]
	v_cndmask_b32_e64 v184, 0, 1.0, s[0:1]
	v_cmp_ge_i32_e32 vcc, s16, v160
	v_cmp_lt_i32_e64 s[0:1], s16, v161
	v_cvt_f32_i32_e32 v155, v155
	s_and_b64 s[0:1], vcc, s[0:1]
	v_cndmask_b32_e64 v186, 0, 1.0, s[0:1]
	v_cmp_ge_i32_e32 vcc, s18, v160
	v_cmp_lt_i32_e64 s[0:1], s18, v161
	s_and_b64 s[0:1], vcc, s[0:1]
	s_nop 0
	v_cndmask_b32_e64 v154, 0, 1.0, s[0:1]
	v_div_scale_f32 v156, s[0:1], v155, v155, 1.0
	v_rcp_f32_e32 v160, v156
	s_or_b32 s0, s4, 8
	s_ashr_i32 s1, s0, 31
	s_lshl_b64 s[0:1], s[0:1], 11
	v_fma_f32 v161, -v156, v160, 1.0
	v_fmac_f32_e32 v160, v161, v160
	v_div_scale_f32 v161, vcc, 1.0, v155, 1.0
	v_mul_f32_e32 v173, v161, v160
	v_fma_f32 v175, -v156, v173, v161
	v_fmac_f32_e32 v173, v175, v160
	v_pk_fma_f32 v[152:153], v[172:173], v[84:85], v[152:153] op_sel_hi:[0,1,1]
	v_pk_fma_f32 v[146:147], v[172:173], v[64:65], v[146:147] op_sel_hi:[0,1,1]
	v_pk_fma_f32 v[152:153], v[174:175], v[60:61], v[152:153] op_sel_hi:[0,1,1]
	v_pk_fma_f32 v[146:147], v[174:175], v[56:57], v[146:147] op_sel_hi:[0,1,1]
	v_pk_fma_f32 v[152:153], v[176:177], v[74:75], v[152:153] op_sel_hi:[0,1,1]
	v_pk_fma_f32 v[146:147], v[176:177], v[52:53], v[146:147] op_sel_hi:[0,1,1]
	v_pk_fma_f32 v[152:153], v[178:179], v[106:107], v[152:153] op_sel_hi:[0,1,1]
	v_pk_fma_f32 v[146:147], v[178:179], v[48:49], v[146:147] op_sel_hi:[0,1,1]
	v_pk_fma_f32 v[152:153], v[180:181], v[120:121], v[152:153] op_sel_hi:[0,1,1]
	v_pk_fma_f32 v[146:147], v[180:181], v[44:45], v[146:147] op_sel_hi:[0,1,1]
	v_pk_fma_f32 v[152:153], v[182:183], v[136:137], v[152:153] op_sel_hi:[0,1,1]
	v_pk_fma_f32 v[146:147], v[182:183], v[40:41], v[146:147] op_sel_hi:[0,1,1]
	v_fma_f32 v156, -v156, v173, v161
	v_pk_fma_f32 v[152:153], v[184:185], v[148:149], v[152:153] op_sel_hi:[0,1,1]
	v_pk_fma_f32 v[146:147], v[184:185], v[36:37], v[146:147] op_sel_hi:[0,1,1]
	v_div_fmas_f32 v156, v156, v160, v173
	v_pk_fma_f32 v[188:189], v[186:187], v[144:145], v[152:153] op_sel_hi:[0,1,1]
	s_waitcnt vmcnt(15)
	v_lshlrev_b32_e32 v152, 16, v28
	v_and_b32_e32 v153, 0xffff0000, v28
	v_pk_fma_f32 v[190:191], v[186:187], v[142:143], v[146:147] op_sel_hi:[0,1,1]
	v_lshlrev_b32_e32 v146, 16, v29
	v_and_b32_e32 v147, 0xffff0000, v29
	v_div_fixup_f32 v156, v156, v155, 1.0
	v_pk_fma_f32 v[188:189], v[154:155], v[152:153], v[188:189] op_sel_hi:[0,1,1]
	v_pk_fma_f32 v[28:29], v[154:155], v[146:147], v[190:191] op_sel_hi:[0,1,1]
	v_pk_fma_f32 v[188:189], v[156:157], v[188:189], v[60:61] op_sel_hi:[0,1,1] neg_lo:[0,0,1] neg_hi:[0,0,1]
	v_pk_fma_f32 v[28:29], v[156:157], v[28:29], v[56:57] op_sel_hi:[0,1,1] neg_lo:[0,0,1] neg_hi:[0,0,1]
	v_cvt_pk_bf16_f32 v188, v188, v189
	v_cvt_pk_bf16_f32 v189, v28, v29
	v_pk_fma_f32 v[28:29], v[172:173], v[68:69], v[34:35] op_sel_hi:[0,1,1]
	v_pk_fma_f32 v[28:29], v[174:175], v[62:63], v[28:29] op_sel_hi:[0,1,1]
	v_pk_fma_f32 v[28:29], v[176:177], v[78:79], v[28:29] op_sel_hi:[0,1,1]
	v_pk_fma_f32 v[28:29], v[178:179], v[108:109], v[28:29] op_sel_hi:[0,1,1]
	v_pk_fma_f32 v[28:29], v[180:181], v[122:123], v[28:29] op_sel_hi:[0,1,1]
	v_pk_fma_f32 v[28:29], v[182:183], v[138:139], v[28:29] op_sel_hi:[0,1,1]
	v_pk_fma_f32 v[28:29], v[184:185], v[150:151], v[28:29] op_sel_hi:[0,1,1]
	v_pk_fma_f32 v[28:29], v[186:187], v[140:141], v[28:29] op_sel_hi:[0,1,1]
	v_lshlrev_b32_e32 v34, 16, v30
	v_and_b32_e32 v35, 0xffff0000, v30
	v_pk_fma_f32 v[28:29], v[154:155], v[34:35], v[28:29] op_sel_hi:[0,1,1]
	v_pk_fma_f32 v[28:29], v[156:157], v[28:29], v[62:63] op_sel_hi:[0,1,1] neg_lo:[0,0,1] neg_hi:[0,0,1]
	v_cvt_pk_bf16_f32 v190, v28, v29
	v_pk_fma_f32 v[28:29], v[172:173], v[66:67], v[170:171] op_sel_hi:[0,1,1]
	v_pk_fma_f32 v[28:29], v[174:175], v[58:59], v[28:29] op_sel_hi:[0,1,1]
	v_pk_fma_f32 v[28:29], v[176:177], v[54:55], v[28:29] op_sel_hi:[0,1,1]
	v_pk_fma_f32 v[28:29], v[178:179], v[50:51], v[28:29] op_sel_hi:[0,1,1]
	v_pk_fma_f32 v[28:29], v[180:181], v[46:47], v[28:29] op_sel_hi:[0,1,1]
	v_pk_fma_f32 v[28:29], v[182:183], v[42:43], v[28:29] op_sel_hi:[0,1,1]
	v_pk_fma_f32 v[28:29], v[184:185], v[38:39], v[28:29] op_sel_hi:[0,1,1]
; __device__ __forceinline__ unsigned cvt_pk_bf16(float lo, float hi) { const f32x2 v = (f32x2){lo, hi}; return __builtin_bit_cast(unsigned, __builtin_convertvector(v, bf16v2)); }
; __device__ __forceinline__ float bf_lo(unsigned w) { return __uint_as_float(w << 16); }
; __device__ __forceinline__ float bf_hi(unsigned w) { return __uint_as_float(w & 0xffff0000u); }
; __device__ __forceinline__ void phase_mixer(const Params& p, LAS unsigned char* lds, int l, bool with_ctx, int G, int tid, int wave, int lane, int rep_attn, int rep_pool) {
;     ...
;         for (int o = 0; o < 16; ++o) {
;             const int t = t0 + o, st = max(t - lo, 0), en = min(t + hi + 1, len);
;             float acc[8];
; #pragma unroll
;             for (int e = 0; e < 8; ++e) acc[e] = 0.f;
; #pragma unroll
;             for (int i = 0; i < 16; ++i) { const int tt = t + i - 8; const float wt = (tt >= st && tt < en) ? 1.f : 0.f; const u32x4 ww = w[o + i];
;                 acc[0] += wt * bf_lo(ww.x); acc[1] += wt * bf_hi(ww.x); acc[2] += wt * bf_lo(ww.y); acc[3] += wt * bf_hi(ww.y);
;                 acc[4] += wt * bf_lo(ww.z); acc[5] += wt * bf_hi(ww.z); acc[6] += wt * bf_lo(ww.w); acc[7] += wt * bf_hi(ww.w); }
;             const float ic = 1.f / (float)(en - st);
;             const u32x4 sw = w[o + 8];
;             u32x4 ov; ov.x = cvt_pk_bf16(acc[0] * ic - bf_lo(sw.x), acc[1] * ic - bf_hi(sw.x)); ov.y = cvt_pk_bf16(acc[2] * ic - bf_lo(sw.y), acc[3] * ic - bf_hi(sw.y));
;             ov.z = cvt_pk_bf16(acc[4] * ic - bf_lo(sw.z), acc[5] * ic - bf_hi(sw.z)); ov.w = cvt_pk_bf16(acc[6] * ic - bf_lo(sw.w), acc[7] * ic - bf_hi(sw.w));
;             *(u32x4*)(MIX + (size_t)(tok0 + o) * DM + 8 * lane) = ov;
	v_pk_fma_f32 v[170:171], v[186:187], v[32:33], v[28:29] op_sel_hi:[0,1,1]
	v_lshlrev_b32_e32 v28, 16, v31
	v_and_b32_e32 v29, 0xffff0000, v31
	v_pk_fma_f32 v[30:31], v[154:155], v[28:29], v[170:171] op_sel_hi:[0,1,1]
	v_pk_fma_f32 v[30:31], v[156:157], v[30:31], v[58:59] op_sel_hi:[0,1,1] neg_lo:[0,0,1] neg_hi:[0,0,1]
	v_cvt_pk_bf16_f32 v191, v30, v31
	v_lshl_add_u64 v[30:31], v[126:127], 0, s[0:1]
	global_store_dwordx4 v[30:31], v[188:191], off
	v_sub_u32_e32 v30, s12, v167
	v_add_u32_e32 v31, s12, v167
	v_max_i32_e32 v160, 0, v30
	v_min_i32_e32 v161, s9, v31
	v_cmp_ge_i32_e32 vcc, s26, v160
	v_cmp_lt_i32_e64 s[0:1], s26, v161
	s_and_b64 s[0:1], vcc, s[0:1]
	v_cmp_ge_i32_e32 vcc, s23, v160
	v_cndmask_b32_e64 v154, 0, 1.0, s[0:1]
	v_cmp_lt_i32_e64 s[0:1], s23, v161
	s_and_b64 s[0:1], vcc, s[0:1]
	v_cmp_ge_i32_e32 vcc, s22, v160
	v_cndmask_b32_e64 v156, 0, 1.0, s[0:1]
	v_cmp_lt_i32_e64 s[0:1], s22, v161
	s_and_b64 s[0:1], vcc, s[0:1]
	v_cmp_ge_i32_e32 vcc, s21, v160
	v_cndmask_b32_e64 v170, 0, 1.0, s[0:1]
	v_cmp_lt_i32_e64 s[0:1], s21, v161
	s_and_b64 s[0:1], vcc, s[0:1]
	v_cmp_ge_i32_e32 vcc, s20, v160
	v_cndmask_b32_e64 v172, 0, 1.0, s[0:1]
	v_cmp_lt_i32_e64 s[0:1], s20, v161
	s_and_b64 s[0:1], vcc, s[0:1]
	v_pk_fma_f32 v[30:31], v[154:155], v[132:133], 0 op_sel_hi:[0,1,0]
	v_cndmask_b32_e64 v174, 0, 1.0, s[0:1]
	v_cmp_ge_i32_e32 vcc, s19, v160
	v_cmp_lt_i32_e64 s[0:1], s19, v161
	v_pk_fma_f32 v[30:31], v[156:157], v[104:105], v[30:31] op_sel_hi:[0,1,1]
	s_and_b64 s[0:1], vcc, s[0:1]
	v_pk_fma_f32 v[30:31], v[170:171], v[112:113], v[30:31] op_sel_hi:[0,1,1]
	v_cndmask_b32_e64 v176, 0, 1.0, s[0:1]
	v_cmp_ge_i32_e32 vcc, s10, v160
	v_cmp_lt_i32_e64 s[0:1], s10, v161
	v_pk_fma_f32 v[30:31], v[172:173], v[92:93], v[30:31] op_sel_hi:[0,1,1]
	s_and_b64 s[0:1], vcc, s[0:1]
	v_pk_fma_f32 v[30:31], v[174:175], v[88:89], v[30:31] op_sel_hi:[0,1,1]
	v_cndmask_b32_e64 v178, 0, 1.0, s[0:1]
	v_pk_fma_f32 v[30:31], v[176:177], v[86:87], v[30:31] op_sel_hi:[0,1,1]
	v_pk_fma_f32 v[186:187], v[178:179], v[84:85], v[30:31] op_sel_hi:[0,1,1]
	v_pk_fma_f32 v[30:31], v[154:155], v[130:131], 0 op_sel_hi:[0,1,0]
	v_pk_fma_f32 v[30:31], v[156:157], v[102:103], v[30:31] op_sel_hi:[0,1,1]
	v_pk_fma_f32 v[30:31], v[170:171], v[114:115], v[30:31] op_sel_hi:[0,1,1]
	v_pk_fma_f32 v[30:31], v[172:173], v[94:95], v[30:31] op_sel_hi:[0,1,1]
	v_pk_fma_f32 v[30:31], v[174:175], v[80:81], v[30:31] op_sel_hi:[0,1,1]
	v_pk_fma_f32 v[30:31], v[176:177], v[72:73], v[30:31] op_sel_hi:[0,1,1]
	v_cmp_ge_i32_e32 vcc, s11, v160
	v_cmp_lt_i32_e64 s[0:1], s11, v161
	v_pk_fma_f32 v[184:185], v[178:179], v[64:65], v[30:31] op_sel_hi:[0,1,1]
	v_pk_fma_f32 v[30:31], v[154:155], v[128:129], 0 op_sel_hi:[0,1,0]
	v_pk_fma_f32 v[118:119], v[154:155], v[118:119], 0 op_sel_hi:[0,1,0]
	s_and_b64 s[0:1], vcc, s[0:1]
	v_pk_fma_f32 v[30:31], v[156:157], v[100:101], v[30:31] op_sel_hi:[0,1,1]
	v_pk_fma_f32 v[118:119], v[156:157], v[98:99], v[118:119] op_sel_hi:[0,1,1]
	v_cndmask_b32_e64 v156, 0, 1.0, s[0:1]
	v_cmp_ge_i32_e32 vcc, s12, v160
	v_cmp_lt_i32_e64 s[0:1], s12, v161
	s_and_b64 s[0:1], vcc, s[0:1]
	v_pk_fma_f32 v[30:31], v[170:171], v[116:117], v[30:31] op_sel_hi:[0,1,1]
	v_pk_fma_f32 v[118:119], v[170:171], v[134:135], v[118:119] op_sel_hi:[0,1,1]
	v_cndmask_b32_e64 v170, 0, 1.0, s[0:1]
	v_cmp_ge_i32_e32 vcc, s13, v160
	v_cmp_lt_i32_e64 s[0:1], s13, v161
	s_and_b64 s[0:1], vcc, s[0:1]
	v_pk_fma_f32 v[30:31], v[172:173], v[96:97], v[30:31] op_sel_hi:[0,1,1]
	v_pk_fma_f32 v[118:119], v[172:173], v[110:111], v[118:119] op_sel_hi:[0,1,1]
	v_cndmask_b32_e64 v172, 0, 1.0, s[0:1]
	v_cmp_ge_i32_e32 vcc, s14, v160
	v_cmp_lt_i32_e64 s[0:1], s14, v161
	s_and_b64 s[0:1], vcc, s[0:1]
	v_pk_fma_f32 v[30:31], v[174:175], v[90:91], v[30:31] op_sel_hi:[0,1,1]
	v_pk_fma_f32 v[118:119], v[174:175], v[82:83], v[118:119] op_sel_hi:[0,1,1]
	v_cndmask_b32_e64 v174, 0, 1.0, s[0:1]
	v_cmp_ge_i32_e32 vcc, s15, v160
	v_cmp_lt_i32_e64 s[0:1], s15, v161
	s_and_b64 s[0:1], vcc, s[0:1]
	v_pk_fma_f32 v[30:31], v[176:177], v[76:77], v[30:31] op_sel_hi:[0,1,1]
	v_pk_fma_f32 v[118:119], v[176:177], v[70:71], v[118:119] op_sel_hi:[0,1,1]
	v_cndmask_b32_e64 v176, 0, 1.0, s[0:1]
	v_cmp_ge_i32_e32 vcc, s17, v160
	v_cmp_lt_i32_e64 s[0:1], s17, v161
	s_and_b64 s[0:1], vcc, s[0:1]
	v_pk_fma_f32 v[30:31], v[178:179], v[68:69], v[30:31] op_sel_hi:[0,1,1]
	v_pk_fma_f32 v[154:155], v[178:179], v[66:67], v[118:119] op_sel_hi:[0,1,1]
	v_cndmask_b32_e64 v178, 0, 1.0, s[0:1]
	v_cmp_ge_i32_e32 vcc, s16, v160
	v_cmp_lt_i32_e64 s[0:1], s16, v161
	s_and_b64 s[0:1], vcc, s[0:1]
	v_sub_u32_e32 v118, v161, v160
	v_cndmask_b32_e64 v180, 0, 1.0, s[0:1]
	v_cmp_ge_i32_e32 vcc, s18, v160
	v_cmp_lt_i32_e64 s[0:1], s18, v161
	v_cvt_f32_i32_e32 v118, v118
	s_and_b64 s[0:1], vcc, s[0:1]
	v_cndmask_b32_e64 v182, 0, 1.0, s[0:1]
	v_cmp_ge_i32_e32 vcc, s5, v160
	v_cmp_lt_i32_e64 s[0:1], s5, v161
	s_and_b64 s[0:1], vcc, s[0:1]
	s_nop 0
	v_cndmask_b32_e64 v130, 0, 1.0, s[0:1]
	v_div_scale_f32 v119, s[0:1], v118, v118, 1.0
	v_rcp_f32_e32 v128, v119
	s_or_b32 s0, s4, 9
	s_ashr_i32 s1, s0, 31
	s_lshl_b64 s[0:1], s[0:1], 11
	v_fma_f32 v129, -v119, v128, 1.0
	v_fmac_f32_e32 v128, v129, v128
	v_div_scale_f32 v129, vcc, 1.0, v118, 1.0
	v_mul_f32_e32 v131, v129, v128
	v_fma_f32 v132, -v119, v131, v129
	v_fmac_f32_e32 v131, v132, v128
	v_fma_f32 v119, -v119, v131, v129
	v_div_fmas_f32 v119, v119, v128, v131
	v_div_fixup_f32 v132, v119, v118, 1.0
	v_pk_fma_f32 v[118:119], v[156:157], v[60:61], v[186:187] op_sel_hi:[0,1,1]
	v_pk_fma_f32 v[118:119], v[170:171], v[74:75], v[118:119] op_sel_hi:[0,1,1]
	v_pk_fma_f32 v[118:119], v[172:173], v[106:107], v[118:119] op_sel_hi:[0,1,1]
	v_pk_fma_f32 v[118:119], v[174:175], v[120:121], v[118:119] op_sel_hi:[0,1,1]
	v_pk_fma_f32 v[118:119], v[176:177], v[136:137], v[118:119] op_sel_hi:[0,1,1]
	v_pk_fma_f32 v[118:119], v[178:179], v[148:149], v[118:119] op_sel_hi:[0,1,1]
	v_pk_fma_f32 v[118:119], v[180:181], v[144:145], v[118:119] op_sel_hi:[0,1,1]
	v_pk_fma_f32 v[118:119], v[182:183], v[152:153], v[118:119] op_sel_hi:[0,1,1]
	s_waitcnt vmcnt(15)
; __device__ __forceinline__ unsigned cvt_pk_bf16(float lo, float hi) { const f32x2 v = (f32x2){lo, hi}; return __builtin_bit_cast(unsigned, __builtin_convertvector(v, bf16v2)); }
; __device__ __forceinline__ float bf_lo(unsigned w) { return __uint_as_float(w << 16); }
; __device__ __forceinline__ float bf_hi(unsigned w) { return __uint_as_float(w & 0xffff0000u); }
; __device__ __forceinline__ void phase_mixer(const Params& p, LAS unsigned char* lds, int l, bool with_ctx, int G, int tid, int wave, int lane, int rep_attn, int rep_pool) {
;     ...
;         for (int o = 0; o < 16; ++o) {
;             const int t = t0 + o, st = max(t - lo, 0), en = min(t + hi + 1, len);
;             float acc[8];
; #pragma unroll
;             for (int e = 0; e < 8; ++e) acc[e] = 0.f;
; #pragma unroll
;             for (int i = 0; i < 16; ++i) { const int tt = t + i - 8; const float wt = (tt >= st && tt < en) ? 1.f : 0.f; const u32x4 ww = w[o + i];
;                 acc[0] += wt * bf_lo(ww.x); acc[1] += wt * bf_hi(ww.x); acc[2] += wt * bf_lo(ww.y); acc[3] += wt * bf_hi(ww.y);
;                 acc[4] += wt * bf_lo(ww.z); acc[5] += wt * bf_hi(ww.z); acc[6] += wt * bf_lo(ww.w); acc[7] += wt * bf_hi(ww.w); }
;             const float ic = 1.f / (float)(en - st);
;             const u32x4 sw = w[o + 8];
;             u32x4 ov; ov.x = cvt_pk_bf16(acc[0] * ic - bf_lo(sw.x), acc[1] * ic - bf_hi(sw.x)); ov.y = cvt_pk_bf16(acc[2] * ic - bf_lo(sw.y), acc[3] * ic - bf_hi(sw.y));
;             ov.z = cvt_pk_bf16(acc[4] * ic - bf_lo(sw.z), acc[5] * ic - bf_hi(sw.z)); ov.w = cvt_pk_bf16(acc[6] * ic - bf_lo(sw.w), acc[7] * ic - bf_hi(sw.w));
;             *(u32x4*)(MIX + (size_t)(tok0 + o) * DM + 8 * lane) = ov;
	v_lshlrev_b32_e32 v128, 16, v24
	v_and_b32_e32 v129, 0xffff0000, v24
	v_pk_fma_f32 v[118:119], v[130:131], v[128:129], v[118:119] op_sel_hi:[0,1,1]
	v_pk_fma_f32 v[118:119], v[132:133], v[118:119], v[74:75] op_sel_hi:[0,1,1] neg_lo:[0,0,1] neg_hi:[0,0,1]
	v_cvt_pk_bf16_f32 v186, v118, v119
	v_pk_fma_f32 v[118:119], v[156:157], v[56:57], v[184:185] op_sel_hi:[0,1,1]
	v_pk_fma_f32 v[118:119], v[170:171], v[52:53], v[118:119] op_sel_hi:[0,1,1]
	v_pk_fma_f32 v[118:119], v[172:173], v[48:49], v[118:119] op_sel_hi:[0,1,1]
	v_pk_fma_f32 v[118:119], v[174:175], v[44:45], v[118:119] op_sel_hi:[0,1,1]
	v_pk_fma_f32 v[118:119], v[176:177], v[40:41], v[118:119] op_sel_hi:[0,1,1]
	v_pk_fma_f32 v[118:119], v[178:179], v[36:37], v[118:119] op_sel_hi:[0,1,1]
	v_pk_fma_f32 v[118:119], v[180:181], v[142:143], v[118:119] op_sel_hi:[0,1,1]
	v_pk_fma_f32 v[184:185], v[182:183], v[146:147], v[118:119] op_sel_hi:[0,1,1]
	v_lshlrev_b32_e32 v118, 16, v25
	v_and_b32_e32 v119, 0xffff0000, v25
	v_pk_fma_f32 v[24:25], v[130:131], v[118:119], v[184:185] op_sel_hi:[0,1,1]
	v_pk_fma_f32 v[24:25], v[132:133], v[24:25], v[52:53] op_sel_hi:[0,1,1] neg_lo:[0,0,1] neg_hi:[0,0,1]
	v_cvt_pk_bf16_f32 v187, v24, v25
	v_pk_fma_f32 v[24:25], v[156:157], v[62:63], v[30:31] op_sel_hi:[0,1,1]
	v_pk_fma_f32 v[24:25], v[170:171], v[78:79], v[24:25] op_sel_hi:[0,1,1]
	v_pk_fma_f32 v[24:25], v[172:173], v[108:109], v[24:25] op_sel_hi:[0,1,1]
	v_pk_fma_f32 v[24:25], v[174:175], v[122:123], v[24:25] op_sel_hi:[0,1,1]
	v_pk_fma_f32 v[24:25], v[176:177], v[138:139], v[24:25] op_sel_hi:[0,1,1]
	v_pk_fma_f32 v[24:25], v[178:179], v[150:151], v[24:25] op_sel_hi:[0,1,1]
	v_pk_fma_f32 v[24:25], v[180:181], v[140:141], v[24:25] op_sel_hi:[0,1,1]
	v_pk_fma_f32 v[24:25], v[182:183], v[34:35], v[24:25] op_sel_hi:[0,1,1]
	v_lshlrev_b32_e32 v30, 16, v26
	v_and_b32_e32 v31, 0xffff0000, v26
	v_pk_fma_f32 v[24:25], v[130:131], v[30:31], v[24:25] op_sel_hi:[0,1,1]
	v_pk_fma_f32 v[24:25], v[132:133], v[24:25], v[78:79] op_sel_hi:[0,1,1] neg_lo:[0,0,1] neg_hi:[0,0,1]
	v_cvt_pk_bf16_f32 v188, v24, v25
	v_pk_fma_f32 v[24:25], v[156:157], v[58:59], v[154:155] op_sel_hi:[0,1,1]
	v_pk_fma_f32 v[24:25], v[170:171], v[54:55], v[24:25] op_sel_hi:[0,1,1]
	v_pk_fma_f32 v[24:25], v[172:173], v[50:51], v[24:25] op_sel_hi:[0,1,1]
	v_pk_fma_f32 v[24:25], v[174:175], v[46:47], v[24:25] op_sel_hi:[0,1,1]
	v_pk_fma_f32 v[24:25], v[176:177], v[42:43], v[24:25] op_sel_hi:[0,1,1]
	v_pk_fma_f32 v[24:25], v[178:179], v[38:39], v[24:25] op_sel_hi:[0,1,1]
	v_pk_fma_f32 v[24:25], v[180:181], v[32:33], v[24:25] op_sel_hi:[0,1,1]
	v_pk_fma_f32 v[154:155], v[182:183], v[28:29], v[24:25] op_sel_hi:[0,1,1]
	v_lshlrev_b32_e32 v24, 16, v27
	v_and_b32_e32 v25, 0xffff0000, v27
	v_pk_fma_f32 v[26:27], v[130:131], v[24:25], v[154:155] op_sel_hi:[0,1,1]
	v_pk_fma_f32 v[26:27], v[132:133], v[26:27], v[54:55] op_sel_hi:[0,1,1] neg_lo:[0,0,1] neg_hi:[0,0,1]
	v_cvt_pk_bf16_f32 v189, v26, v27
	v_lshl_add_u64 v[26:27], v[126:127], 0, s[0:1]
	global_store_dwordx4 v[26:27], v[186:189], off
	v_sub_u32_e32 v26, s13, v167
	v_add_u32_e32 v27, s13, v167
	v_max_i32_e32 v133, 0, v26
	v_min_i32_e32 v155, s9, v27
	v_cmp_ge_i32_e32 vcc, s23, v133
	v_cmp_lt_i32_e64 s[0:1], s23, v155
	s_and_b64 s[0:1], vcc, s[0:1]
	v_cmp_ge_i32_e32 vcc, s22, v133
	v_cndmask_b32_e64 v130, 0, 1.0, s[0:1]
	v_cmp_lt_i32_e64 s[0:1], s22, v155
	s_and_b64 s[0:1], vcc, s[0:1]
	v_cmp_ge_i32_e32 vcc, s21, v133
	v_cndmask_b32_e64 v132, 0, 1.0, s[0:1]
	v_cmp_lt_i32_e64 s[0:1], s21, v155
	s_and_b64 s[0:1], vcc, s[0:1]
	v_cmp_ge_i32_e32 vcc, s20, v133
	v_cndmask_b32_e64 v154, 0, 1.0, s[0:1]
	v_cmp_lt_i32_e64 s[0:1], s20, v155
	s_and_b64 s[0:1], vcc, s[0:1]
	v_cmp_ge_i32_e32 vcc, s19, v133
	v_cndmask_b32_e64 v156, 0, 1.0, s[0:1]
	v_cmp_lt_i32_e64 s[0:1], s19, v155
	s_and_b64 s[0:1], vcc, s[0:1]
	v_pk_fma_f32 v[26:27], v[130:131], v[104:105], 0 op_sel_hi:[0,1,0]
	v_cndmask_b32_e64 v170, 0, 1.0, s[0:1]
	v_cmp_ge_i32_e32 vcc, s10, v133
	v_cmp_lt_i32_e64 s[0:1], s10, v155
	v_pk_fma_f32 v[26:27], v[132:133], v[112:113], v[26:27] op_sel_hi:[0,1,1]
	s_and_b64 s[0:1], vcc, s[0:1]
	v_pk_fma_f32 v[26:27], v[154:155], v[92:93], v[26:27] op_sel_hi:[0,1,1]
	v_cndmask_b32_e64 v172, 0, 1.0, s[0:1]
	v_cmp_ge_i32_e32 vcc, s11, v133
	v_cmp_lt_i32_e64 s[0:1], s11, v155
	v_pk_fma_f32 v[26:27], v[156:157], v[88:89], v[26:27] op_sel_hi:[0,1,1]
	s_and_b64 s[0:1], vcc, s[0:1]
	v_pk_fma_f32 v[26:27], v[170:171], v[86:87], v[26:27] op_sel_hi:[0,1,1]
	v_cndmask_b32_e64 v174, 0, 1.0, s[0:1]
	v_pk_fma_f32 v[26:27], v[172:173], v[84:85], v[26:27] op_sel_hi:[0,1,1]
	v_pk_fma_f32 v[182:183], v[174:175], v[60:61], v[26:27] op_sel_hi:[0,1,1]
	v_pk_fma_f32 v[26:27], v[130:131], v[102:103], 0 op_sel_hi:[0,1,0]
	v_pk_fma_f32 v[26:27], v[132:133], v[114:115], v[26:27] op_sel_hi:[0,1,1]
	v_pk_fma_f32 v[26:27], v[154:155], v[94:95], v[26:27] op_sel_hi:[0,1,1]
	v_pk_fma_f32 v[26:27], v[156:157], v[80:81], v[26:27] op_sel_hi:[0,1,1]
	v_pk_fma_f32 v[26:27], v[170:171], v[72:73], v[26:27] op_sel_hi:[0,1,1]
	v_pk_fma_f32 v[26:27], v[172:173], v[64:65], v[26:27] op_sel_hi:[0,1,1]
	v_cmp_ge_i32_e32 vcc, s12, v133
	v_cmp_lt_i32_e64 s[0:1], s12, v155
	v_pk_fma_f32 v[180:181], v[174:175], v[56:57], v[26:27] op_sel_hi:[0,1,1]
	v_pk_fma_f32 v[26:27], v[130:131], v[100:101], 0 op_sel_hi:[0,1,0]
	v_pk_fma_f32 v[98:99], v[130:131], v[98:99], 0 op_sel_hi:[0,1,0]
	s_and_b64 s[0:1], vcc, s[0:1]
	v_pk_fma_f32 v[26:27], v[132:133], v[116:117], v[26:27] op_sel_hi:[0,1,1]
	v_pk_fma_f32 v[98:99], v[132:133], v[134:135], v[98:99] op_sel_hi:[0,1,1]
	v_cndmask_b32_e64 v132, 0, 1.0, s[0:1]
	v_cmp_ge_i32_e32 vcc, s13, v133
	v_cmp_lt_i32_e64 s[0:1], s13, v155
; __device__ __forceinline__ unsigned cvt_pk_bf16(float lo, float hi) { const f32x2 v = (f32x2){lo, hi}; return __builtin_bit_cast(unsigned, __builtin_convertvector(v, bf16v2)); }
; __device__ __forceinline__ float bf_lo(unsigned w) { return __uint_as_float(w << 16); }
; __device__ __forceinline__ float bf_hi(unsigned w) { return __uint_as_float(w & 0xffff0000u); }
; __device__ __forceinline__ void phase_mixer(const Params& p, LAS unsigned char* lds, int l, bool with_ctx, int G, int tid, int wave, int lane, int rep_attn, int rep_pool) {
;     ...
;         for (int o = 0; o < 16; ++o) {
;             const int t = t0 + o, st = max(t - lo, 0), en = min(t + hi + 1, len);
;             float acc[8];
; #pragma unroll
;             for (int e = 0; e < 8; ++e) acc[e] = 0.f;
; #pragma unroll
;             for (int i = 0; i < 16; ++i) { const int tt = t + i - 8; const float wt = (tt >= st && tt < en) ? 1.f : 0.f; const u32x4 ww = w[o + i];
;                 acc[0] += wt * bf_lo(ww.x); acc[1] += wt * bf_hi(ww.x); acc[2] += wt * bf_lo(ww.y); acc[3] += wt * bf_hi(ww.y);
;                 acc[4] += wt * bf_lo(ww.z); acc[5] += wt * bf_hi(ww.z); acc[6] += wt * bf_lo(ww.w); acc[7] += wt * bf_hi(ww.w); }
;             const float ic = 1.f / (float)(en - st);
;             const u32x4 sw = w[o + 8];
;             u32x4 ov; ov.x = cvt_pk_bf16(acc[0] * ic - bf_lo(sw.x), acc[1] * ic - bf_hi(sw.x)); ov.y = cvt_pk_bf16(acc[2] * ic - bf_lo(sw.y), acc[3] * ic - bf_hi(sw.y));
;             ov.z = cvt_pk_bf16(acc[4] * ic - bf_lo(sw.z), acc[5] * ic - bf_hi(sw.z)); ov.w = cvt_pk_bf16(acc[6] * ic - bf_lo(sw.w), acc[7] * ic - bf_hi(sw.w));
;             *(u32x4*)(MIX + (size_t)(tok0 + o) * DM + 8 * lane) = ov;
	s_and_b64 s[0:1], vcc, s[0:1]
	v_pk_fma_f32 v[26:27], v[154:155], v[96:97], v[26:27] op_sel_hi:[0,1,1]
	v_pk_fma_f32 v[98:99], v[154:155], v[110:111], v[98:99] op_sel_hi:[0,1,1]
	v_cndmask_b32_e64 v154, 0, 1.0, s[0:1]
	v_cmp_ge_i32_e32 vcc, s14, v133
	v_cmp_lt_i32_e64 s[0:1], s14, v155
	s_and_b64 s[0:1], vcc, s[0:1]
	v_pk_fma_f32 v[26:27], v[156:157], v[90:91], v[26:27] op_sel_hi:[0,1,1]
	v_pk_fma_f32 v[98:99], v[156:157], v[82:83], v[98:99] op_sel_hi:[0,1,1]
	v_cndmask_b32_e64 v156, 0, 1.0, s[0:1]
	v_cmp_ge_i32_e32 vcc, s15, v133
	v_cmp_lt_i32_e64 s[0:1], s15, v155
	s_and_b64 s[0:1], vcc, s[0:1]
	v_pk_fma_f32 v[26:27], v[170:171], v[76:77], v[26:27] op_sel_hi:[0,1,1]
	v_pk_fma_f32 v[98:99], v[170:171], v[70:71], v[98:99] op_sel_hi:[0,1,1]
	v_cndmask_b32_e64 v170, 0, 1.0, s[0:1]
	v_cmp_ge_i32_e32 vcc, s17, v133
	v_cmp_lt_i32_e64 s[0:1], s17, v155
	s_and_b64 s[0:1], vcc, s[0:1]
	v_pk_fma_f32 v[26:27], v[172:173], v[68:69], v[26:27] op_sel_hi:[0,1,1]
	v_pk_fma_f32 v[98:99], v[172:173], v[66:67], v[98:99] op_sel_hi:[0,1,1]
	v_cndmask_b32_e64 v172, 0, 1.0, s[0:1]
	v_cmp_ge_i32_e32 vcc, s16, v133
	v_cmp_lt_i32_e64 s[0:1], s16, v155
	s_and_b64 s[0:1], vcc, s[0:1]
	v_pk_fma_f32 v[26:27], v[174:175], v[62:63], v[26:27] op_sel_hi:[0,1,1]
	v_pk_fma_f32 v[130:131], v[174:175], v[58:59], v[98:99] op_sel_hi:[0,1,1]
	v_cndmask_b32_e64 v174, 0, 1.0, s[0:1]
	v_cmp_ge_i32_e32 vcc, s18, v133
	v_cmp_lt_i32_e64 s[0:1], s18, v155
	s_and_b64 s[0:1], vcc, s[0:1]
	v_sub_u32_e32 v98, v155, v133
	v_cndmask_b32_e64 v176, 0, 1.0, s[0:1]
	v_cmp_ge_i32_e32 vcc, s5, v133
	v_cmp_lt_i32_e64 s[0:1], s5, v155
	v_cvt_f32_i32_e32 v98, v98
	s_and_b64 s[0:1], vcc, s[0:1]
	s_add_i32 s23, s8, 17
	v_cndmask_b32_e64 v178, 0, 1.0, s[0:1]
	v_cmp_ge_i32_e32 vcc, s23, v133
	v_cmp_lt_i32_e64 s[0:1], s23, v155
	s_and_b64 s[0:1], vcc, s[0:1]
	s_nop 0
	v_cndmask_b32_e64 v102, 0, 1.0, s[0:1]
	v_div_scale_f32 v99, s[0:1], v98, v98, 1.0
	v_rcp_f32_e32 v100, v99
	s_or_b32 s0, s4, 10
	s_ashr_i32 s1, s0, 31
	s_lshl_b64 s[0:1], s[0:1], 11
	v_fma_f32 v101, -v99, v100, 1.0
	v_fmac_f32_e32 v100, v101, v100
	v_div_scale_f32 v101, vcc, 1.0, v98, 1.0
	v_mul_f32_e32 v103, v101, v100
	v_fma_f32 v104, -v99, v103, v101
	v_fmac_f32_e32 v103, v104, v100
	v_fma_f32 v99, -v99, v103, v101
	v_div_fmas_f32 v99, v99, v100, v103
	v_div_fixup_f32 v104, v99, v98, 1.0
	v_pk_fma_f32 v[98:99], v[132:133], v[74:75], v[182:183] op_sel_hi:[0,1,1]
	v_pk_fma_f32 v[98:99], v[154:155], v[106:107], v[98:99] op_sel_hi:[0,1,1]
	v_pk_fma_f32 v[98:99], v[156:157], v[120:121], v[98:99] op_sel_hi:[0,1,1]
	v_pk_fma_f32 v[98:99], v[170:171], v[136:137], v[98:99] op_sel_hi:[0,1,1]
	v_pk_fma_f32 v[98:99], v[172:173], v[148:149], v[98:99] op_sel_hi:[0,1,1]
	v_pk_fma_f32 v[98:99], v[174:175], v[144:145], v[98:99] op_sel_hi:[0,1,1]
	v_pk_fma_f32 v[98:99], v[176:177], v[152:153], v[98:99] op_sel_hi:[0,1,1]
	v_pk_fma_f32 v[98:99], v[178:179], v[128:129], v[98:99] op_sel_hi:[0,1,1]
	s_waitcnt vmcnt(15)
	v_lshlrev_b32_e32 v100, 16, v20
	v_and_b32_e32 v101, 0xffff0000, v20
	v_pk_fma_f32 v[98:99], v[102:103], v[100:101], v[98:99] op_sel_hi:[0,1,1]
	v_pk_fma_f32 v[98:99], v[104:105], v[98:99], v[106:107] op_sel_hi:[0,1,1] neg_lo:[0,0,1] neg_hi:[0,0,1]
	v_cvt_pk_bf16_f32 v182, v98, v99
	v_pk_fma_f32 v[98:99], v[132:133], v[52:53], v[180:181] op_sel_hi:[0,1,1]
	v_pk_fma_f32 v[98:99], v[154:155], v[48:49], v[98:99] op_sel_hi:[0,1,1]
	v_pk_fma_f32 v[98:99], v[156:157], v[44:45], v[98:99] op_sel_hi:[0,1,1]
	v_pk_fma_f32 v[98:99], v[170:171], v[40:41], v[98:99] op_sel_hi:[0,1,1]
	v_pk_fma_f32 v[98:99], v[172:173], v[36:37], v[98:99] op_sel_hi:[0,1,1]
	v_pk_fma_f32 v[98:99], v[174:175], v[142:143], v[98:99] op_sel_hi:[0,1,1]
	v_pk_fma_f32 v[98:99], v[176:177], v[146:147], v[98:99] op_sel_hi:[0,1,1]
	v_pk_fma_f32 v[180:181], v[178:179], v[118:119], v[98:99] op_sel_hi:[0,1,1]
	v_lshlrev_b32_e32 v98, 16, v21
	v_and_b32_e32 v99, 0xffff0000, v21
	v_pk_fma_f32 v[20:21], v[102:103], v[98:99], v[180:181] op_sel_hi:[0,1,1]
	v_pk_fma_f32 v[20:21], v[104:105], v[20:21], v[48:49] op_sel_hi:[0,1,1] neg_lo:[0,0,1] neg_hi:[0,0,1]
	v_cvt_pk_bf16_f32 v183, v20, v21
	v_pk_fma_f32 v[20:21], v[132:133], v[78:79], v[26:27] op_sel_hi:[0,1,1]
	v_pk_fma_f32 v[20:21], v[154:155], v[108:109], v[20:21] op_sel_hi:[0,1,1]
	v_pk_fma_f32 v[20:21], v[156:157], v[122:123], v[20:21] op_sel_hi:[0,1,1]
	v_pk_fma_f32 v[20:21], v[170:171], v[138:139], v[20:21] op_sel_hi:[0,1,1]
	v_pk_fma_f32 v[20:21], v[172:173], v[150:151], v[20:21] op_sel_hi:[0,1,1]
	v_pk_fma_f32 v[20:21], v[174:175], v[140:141], v[20:21] op_sel_hi:[0,1,1]
	v_pk_fma_f32 v[20:21], v[176:177], v[34:35], v[20:21] op_sel_hi:[0,1,1]
	v_pk_fma_f32 v[20:21], v[178:179], v[30:31], v[20:21] op_sel_hi:[0,1,1]
	v_lshlrev_b32_e32 v26, 16, v22
	v_and_b32_e32 v27, 0xffff0000, v22
	v_pk_fma_f32 v[20:21], v[102:103], v[26:27], v[20:21] op_sel_hi:[0,1,1]
	v_pk_fma_f32 v[20:21], v[104:105], v[20:21], v[108:109] op_sel_hi:[0,1,1] neg_lo:[0,0,1] neg_hi:[0,0,1]
	v_cvt_pk_bf16_f32 v184, v20, v21
	v_pk_fma_f32 v[20:21], v[132:133], v[54:55], v[130:131] op_sel_hi:[0,1,1]
	v_pk_fma_f32 v[20:21], v[154:155], v[50:51], v[20:21] op_sel_hi:[0,1,1]
	v_pk_fma_f32 v[20:21], v[156:157], v[46:47], v[20:21] op_sel_hi:[0,1,1]
	v_pk_fma_f32 v[20:21], v[170:171], v[42:43], v[20:21] op_sel_hi:[0,1,1]
	v_pk_fma_f32 v[20:21], v[172:173], v[38:39], v[20:21] op_sel_hi:[0,1,1]
	v_pk_fma_f32 v[20:21], v[174:175], v[32:33], v[20:21] op_sel_hi:[0,1,1]
	v_pk_fma_f32 v[20:21], v[176:177], v[28:29], v[20:21] op_sel_hi:[0,1,1]
	v_pk_fma_f32 v[130:131], v[178:179], v[24:25], v[20:21] op_sel_hi:[0,1,1]
	v_lshlrev_b32_e32 v20, 16, v23
	v_and_b32_e32 v21, 0xffff0000, v23
; __device__ __forceinline__ unsigned cvt_pk_bf16(float lo, float hi) { const f32x2 v = (f32x2){lo, hi}; return __builtin_bit_cast(unsigned, __builtin_convertvector(v, bf16v2)); }
; __device__ __forceinline__ float bf_lo(unsigned w) { return __uint_as_float(w << 16); }
; __device__ __forceinline__ float bf_hi(unsigned w) { return __uint_as_float(w & 0xffff0000u); }
; __device__ __forceinline__ void phase_mixer(const Params& p, LAS unsigned char* lds, int l, bool with_ctx, int G, int tid, int wave, int lane, int rep_attn, int rep_pool) {
;     ...
;         for (int o = 0; o < 16; ++o) {
;             const int t = t0 + o, st = max(t - lo, 0), en = min(t + hi + 1, len);
;             float acc[8];
; #pragma unroll
;             for (int e = 0; e < 8; ++e) acc[e] = 0.f;
; #pragma unroll
;             for (int i = 0; i < 16; ++i) { const int tt = t + i - 8; const float wt = (tt >= st && tt < en) ? 1.f : 0.f; const u32x4 ww = w[o + i];
;                 acc[0] += wt * bf_lo(ww.x); acc[1] += wt * bf_hi(ww.x); acc[2] += wt * bf_lo(ww.y); acc[3] += wt * bf_hi(ww.y);
;                 acc[4] += wt * bf_lo(ww.z); acc[5] += wt * bf_hi(ww.z); acc[6] += wt * bf_lo(ww.w); acc[7] += wt * bf_hi(ww.w); }
;             const float ic = 1.f / (float)(en - st);
;             const u32x4 sw = w[o + 8];
;             u32x4 ov; ov.x = cvt_pk_bf16(acc[0] * ic - bf_lo(sw.x), acc[1] * ic - bf_hi(sw.x)); ov.y = cvt_pk_bf16(acc[2] * ic - bf_lo(sw.y), acc[3] * ic - bf_hi(sw.y));
	v_pk_fma_f32 v[22:23], v[102:103], v[20:21], v[130:131] op_sel_hi:[0,1,1]
	v_pk_fma_f32 v[22:23], v[104:105], v[22:23], v[50:51] op_sel_hi:[0,1,1] neg_lo:[0,0,1] neg_hi:[0,0,1]
	v_cvt_pk_bf16_f32 v185, v22, v23
	v_lshl_add_u64 v[22:23], v[126:127], 0, s[0:1]
	global_store_dwordx4 v[22:23], v[182:185], off
	v_sub_u32_e32 v22, s14, v167
	v_add_u32_e32 v23, s14, v167
	v_max_i32_e32 v131, 0, v22
	v_min_i32_e32 v133, s9, v23
	v_cmp_ge_i32_e32 vcc, s22, v131
	v_cmp_lt_i32_e64 s[0:1], s22, v133
	s_and_b64 s[0:1], vcc, s[0:1]
	v_cmp_ge_i32_e32 vcc, s21, v131
	v_cndmask_b32_e64 v104, 0, 1.0, s[0:1]
	v_cmp_lt_i32_e64 s[0:1], s21, v133
	s_and_b64 s[0:1], vcc, s[0:1]
	v_cmp_ge_i32_e32 vcc, s20, v131
	v_cndmask_b32_e64 v130, 0, 1.0, s[0:1]
	v_cmp_lt_i32_e64 s[0:1], s20, v133
	s_and_b64 s[0:1], vcc, s[0:1]
	v_cmp_ge_i32_e32 vcc, s19, v131
	v_cndmask_b32_e64 v132, 0, 1.0, s[0:1]
	v_cmp_lt_i32_e64 s[0:1], s19, v133
	s_and_b64 s[0:1], vcc, s[0:1]
	v_cmp_ge_i32_e32 vcc, s10, v131
	v_cndmask_b32_e64 v154, 0, 1.0, s[0:1]
	v_cmp_lt_i32_e64 s[0:1], s10, v133
	s_and_b64 s[0:1], vcc, s[0:1]
	v_pk_fma_f32 v[22:23], v[104:105], v[112:113], 0 op_sel_hi:[0,1,0]
	v_cndmask_b32_e64 v156, 0, 1.0, s[0:1]
	v_cmp_ge_i32_e32 vcc, s11, v131
	v_cmp_lt_i32_e64 s[0:1], s11, v133
	v_pk_fma_f32 v[22:23], v[130:131], v[92:93], v[22:23] op_sel_hi:[0,1,1]
	s_and_b64 s[0:1], vcc, s[0:1]
	v_pk_fma_f32 v[22:23], v[132:133], v[88:89], v[22:23] op_sel_hi:[0,1,1]
	v_cndmask_b32_e64 v170, 0, 1.0, s[0:1]
	v_cmp_ge_i32_e32 vcc, s12, v131
	v_cmp_lt_i32_e64 s[0:1], s12, v133
	v_pk_fma_f32 v[22:23], v[154:155], v[86:87], v[22:23] op_sel_hi:[0,1,1]
	s_and_b64 s[0:1], vcc, s[0:1]
	v_pk_fma_f32 v[22:23], v[156:157], v[84:85], v[22:23] op_sel_hi:[0,1,1]
	v_cndmask_b32_e64 v172, 0, 1.0, s[0:1]
	v_pk_fma_f32 v[22:23], v[170:171], v[60:61], v[22:23] op_sel_hi:[0,1,1]
	v_pk_fma_f32 v[176:177], v[172:173], v[74:75], v[22:23] op_sel_hi:[0,1,1]
	v_pk_fma_f32 v[22:23], v[104:105], v[114:115], 0 op_sel_hi:[0,1,0]
	v_pk_fma_f32 v[22:23], v[130:131], v[94:95], v[22:23] op_sel_hi:[0,1,1]
	v_pk_fma_f32 v[22:23], v[132:133], v[80:81], v[22:23] op_sel_hi:[0,1,1]
	v_pk_fma_f32 v[22:23], v[154:155], v[72:73], v[22:23] op_sel_hi:[0,1,1]
	v_pk_fma_f32 v[22:23], v[156:157], v[64:65], v[22:23] op_sel_hi:[0,1,1]
	v_pk_fma_f32 v[22:23], v[170:171], v[56:57], v[22:23] op_sel_hi:[0,1,1]
	v_cmp_ge_i32_e32 vcc, s13, v131
	v_cmp_lt_i32_e64 s[0:1], s13, v133
	v_pk_fma_f32 v[102:103], v[172:173], v[52:53], v[22:23] op_sel_hi:[0,1,1]
	v_pk_fma_f32 v[22:23], v[104:105], v[116:117], 0 op_sel_hi:[0,1,0]
	v_pk_fma_f32 v[104:105], v[104:105], v[134:135], 0 op_sel_hi:[0,1,0]
	s_and_b64 s[0:1], vcc, s[0:1]
	v_pk_fma_f32 v[22:23], v[130:131], v[96:97], v[22:23] op_sel_hi:[0,1,1]
	v_pk_fma_f32 v[104:105], v[130:131], v[110:111], v[104:105] op_sel_hi:[0,1,1]
	v_cndmask_b32_e64 v130, 0, 1.0, s[0:1]
	v_cmp_ge_i32_e32 vcc, s14, v131
	v_cmp_lt_i32_e64 s[0:1], s14, v133
	s_and_b64 s[0:1], vcc, s[0:1]
	v_pk_fma_f32 v[22:23], v[132:133], v[90:91], v[22:23] op_sel_hi:[0,1,1]
	v_pk_fma_f32 v[104:105], v[132:133], v[82:83], v[104:105] op_sel_hi:[0,1,1]
	v_cndmask_b32_e64 v132, 0, 1.0, s[0:1]
	v_cmp_ge_i32_e32 vcc, s15, v131
	v_cmp_lt_i32_e64 s[0:1], s15, v133
	s_and_b64 s[0:1], vcc, s[0:1]
	v_cmp_ge_i32_e32 vcc, s17, v131
	v_cndmask_b32_e64 v134, 0, 1.0, s[0:1]
	v_cmp_lt_i32_e64 s[0:1], s17, v133
	s_and_b64 s[0:1], vcc, s[0:1]
	v_pk_fma_f32 v[22:23], v[154:155], v[76:77], v[22:23] op_sel_hi:[0,1,1]
	v_pk_fma_f32 v[104:105], v[154:155], v[70:71], v[104:105] op_sel_hi:[0,1,1]
	v_cndmask_b32_e64 v154, 0, 1.0, s[0:1]
	v_cmp_ge_i32_e32 vcc, s16, v131
	v_cmp_lt_i32_e64 s[0:1], s16, v133
	s_and_b64 s[0:1], vcc, s[0:1]
	v_pk_fma_f32 v[22:23], v[156:157], v[68:69], v[22:23] op_sel_hi:[0,1,1]
	v_pk_fma_f32 v[104:105], v[156:157], v[66:67], v[104:105] op_sel_hi:[0,1,1]
	v_cndmask_b32_e64 v156, 0, 1.0, s[0:1]
	v_cmp_ge_i32_e32 vcc, s18, v131
	v_cmp_lt_i32_e64 s[0:1], s18, v133
	s_and_b64 s[0:1], vcc, s[0:1]
	v_pk_fma_f32 v[22:23], v[170:171], v[62:63], v[22:23] op_sel_hi:[0,1,1]
	v_pk_fma_f32 v[104:105], v[170:171], v[58:59], v[104:105] op_sel_hi:[0,1,1]
	v_cndmask_b32_e64 v170, 0, 1.0, s[0:1]
	v_cmp_ge_i32_e32 vcc, s5, v131
	v_cmp_lt_i32_e64 s[0:1], s5, v133
	v_pk_fma_f32 v[116:117], v[172:173], v[54:55], v[104:105] op_sel_hi:[0,1,1]
	s_and_b64 s[0:1], vcc, s[0:1]
	v_sub_u32_e32 v104, v133, v131
	v_pk_fma_f32 v[22:23], v[172:173], v[78:79], v[22:23] op_sel_hi:[0,1,1]
	v_cndmask_b32_e64 v172, 0, 1.0, s[0:1]
	v_cmp_ge_i32_e32 vcc, s23, v131
	v_cmp_lt_i32_e64 s[0:1], s23, v133
	v_cvt_f32_i32_e32 v104, v104
	s_and_b64 s[0:1], vcc, s[0:1]
	s_add_i32 s22, s8, 18
	v_cndmask_b32_e64 v174, 0, 1.0, s[0:1]
	v_cmp_ge_i32_e32 vcc, s22, v131
	v_cmp_lt_i32_e64 s[0:1], s22, v133
	s_and_b64 s[0:1], vcc, s[0:1]
	s_nop 0
	v_cndmask_b32_e64 v112, 0, 1.0, s[0:1]
	v_div_scale_f32 v105, s[0:1], v104, v104, 1.0
	v_rcp_f32_e32 v113, v105
	s_or_b32 s0, s4, 11
	s_ashr_i32 s1, s0, 31
	s_lshl_b64 s[0:1], s[0:1], 11
	v_fma_f32 v114, -v105, v113, 1.0
	v_fmac_f32_e32 v113, v114, v113
	v_div_scale_f32 v114, vcc, 1.0, v104, 1.0
	v_mul_f32_e32 v115, v114, v113
	v_fma_f32 v131, -v105, v115, v114
	v_fmac_f32_e32 v115, v131, v113
	v_fma_f32 v105, -v105, v115, v114
	v_div_fmas_f32 v105, v105, v113, v115
	v_div_fixup_f32 v114, v105, v104, 1.0
	v_pk_fma_f32 v[104:105], v[130:131], v[106:107], v[176:177] op_sel_hi:[0,1,1]
	v_pk_fma_f32 v[102:103], v[130:131], v[48:49], v[102:103] op_sel_hi:[0,1,1]
	v_pk_fma_f32 v[104:105], v[132:133], v[120:121], v[104:105] op_sel_hi:[0,1,1]
	v_pk_fma_f32 v[102:103], v[132:133], v[44:45], v[102:103] op_sel_hi:[0,1,1]
	v_pk_fma_f32 v[104:105], v[134:135], v[136:137], v[104:105] op_sel_hi:[0,1,1]
	v_pk_fma_f32 v[102:103], v[134:135], v[40:41], v[102:103] op_sel_hi:[0,1,1]
	v_pk_fma_f32 v[104:105], v[154:155], v[148:149], v[104:105] op_sel_hi:[0,1,1]
	v_pk_fma_f32 v[102:103], v[154:155], v[36:37], v[102:103] op_sel_hi:[0,1,1]
	v_pk_fma_f32 v[104:105], v[156:157], v[144:145], v[104:105] op_sel_hi:[0,1,1]
	v_pk_fma_f32 v[102:103], v[156:157], v[142:143], v[102:103] op_sel_hi:[0,1,1]
	v_pk_fma_f32 v[104:105], v[170:171], v[152:153], v[104:105] op_sel_hi:[0,1,1]
	v_pk_fma_f32 v[102:103], v[170:171], v[146:147], v[102:103] op_sel_hi:[0,1,1]
	v_pk_fma_f32 v[104:105], v[172:173], v[128:129], v[104:105] op_sel_hi:[0,1,1]
	v_pk_fma_f32 v[102:103], v[172:173], v[118:119], v[102:103] op_sel_hi:[0,1,1]
	v_pk_fma_f32 v[176:177], v[174:175], v[100:101], v[104:105] op_sel_hi:[0,1,1]
	s_waitcnt vmcnt(15)
; __device__ __forceinline__ unsigned cvt_pk_bf16(float lo, float hi) { const f32x2 v = (f32x2){lo, hi}; return __builtin_bit_cast(unsigned, __builtin_convertvector(v, bf16v2)); }
; __device__ __forceinline__ float bf_lo(unsigned w) { return __uint_as_float(w << 16); }
; __device__ __forceinline__ float bf_hi(unsigned w) { return __uint_as_float(w & 0xffff0000u); }
; __device__ __forceinline__ void phase_mixer(const Params& p, LAS unsigned char* lds, int l, bool with_ctx, int G, int tid, int wave, int lane, int rep_attn, int rep_pool) {
;     ...
;         for (int o = 0; o < 16; ++o) {
;             const int t = t0 + o, st = max(t - lo, 0), en = min(t + hi + 1, len);
;             float acc[8];
; #pragma unroll
;             for (int e = 0; e < 8; ++e) acc[e] = 0.f;
; #pragma unroll
;             for (int i = 0; i < 16; ++i) { const int tt = t + i - 8; const float wt = (tt >= st && tt < en) ? 1.f : 0.f; const u32x4 ww = w[o + i];
;                 acc[0] += wt * bf_lo(ww.x); acc[1] += wt * bf_hi(ww.x); acc[2] += wt * bf_lo(ww.y); acc[3] += wt * bf_hi(ww.y);
;                 acc[4] += wt * bf_lo(ww.z); acc[5] += wt * bf_hi(ww.z); acc[6] += wt * bf_lo(ww.w); acc[7] += wt * bf_hi(ww.w); }
;             const float ic = 1.f / (float)(en - st);
;             const u32x4 sw = w[o + 8];
;             u32x4 ov; ov.x = cvt_pk_bf16(acc[0] * ic - bf_lo(sw.x), acc[1] * ic - bf_hi(sw.x)); ov.y = cvt_pk_bf16(acc[2] * ic - bf_lo(sw.y), acc[3] * ic - bf_hi(sw.y));
;             ov.z = cvt_pk_bf16(acc[4] * ic - bf_lo(sw.z), acc[5] * ic - bf_hi(sw.z)); ov.w = cvt_pk_bf16(acc[6] * ic - bf_lo(sw.w), acc[7] * ic - bf_hi(sw.w));
;             *(u32x4*)(MIX + (size_t)(tok0 + o) * DM + 8 * lane) = ov;
	v_lshlrev_b32_e32 v104, 16, v16
	v_and_b32_e32 v105, 0xffff0000, v16
	v_pk_fma_f32 v[178:179], v[174:175], v[98:99], v[102:103] op_sel_hi:[0,1,1]
	v_lshlrev_b32_e32 v102, 16, v17
	v_and_b32_e32 v103, 0xffff0000, v17
	v_pk_fma_f32 v[176:177], v[112:113], v[104:105], v[176:177] op_sel_hi:[0,1,1]
	v_pk_fma_f32 v[16:17], v[112:113], v[102:103], v[178:179] op_sel_hi:[0,1,1]
	v_pk_fma_f32 v[176:177], v[114:115], v[176:177], v[120:121] op_sel_hi:[0,1,1] neg_lo:[0,0,1] neg_hi:[0,0,1]
	v_pk_fma_f32 v[16:17], v[114:115], v[16:17], v[44:45] op_sel_hi:[0,1,1] neg_lo:[0,0,1] neg_hi:[0,0,1]
	v_cvt_pk_bf16_f32 v176, v176, v177
	v_cvt_pk_bf16_f32 v177, v16, v17
	v_pk_fma_f32 v[16:17], v[130:131], v[108:109], v[22:23] op_sel_hi:[0,1,1]
	v_pk_fma_f32 v[16:17], v[132:133], v[122:123], v[16:17] op_sel_hi:[0,1,1]
	v_pk_fma_f32 v[16:17], v[134:135], v[138:139], v[16:17] op_sel_hi:[0,1,1]
	v_pk_fma_f32 v[16:17], v[154:155], v[150:151], v[16:17] op_sel_hi:[0,1,1]
	v_pk_fma_f32 v[16:17], v[156:157], v[140:141], v[16:17] op_sel_hi:[0,1,1]
	v_pk_fma_f32 v[16:17], v[170:171], v[34:35], v[16:17] op_sel_hi:[0,1,1]
	v_pk_fma_f32 v[16:17], v[172:173], v[30:31], v[16:17] op_sel_hi:[0,1,1]
	v_pk_fma_f32 v[16:17], v[174:175], v[26:27], v[16:17] op_sel_hi:[0,1,1]
	v_lshlrev_b32_e32 v22, 16, v18
	v_and_b32_e32 v23, 0xffff0000, v18
	v_pk_fma_f32 v[16:17], v[112:113], v[22:23], v[16:17] op_sel_hi:[0,1,1]
	v_pk_fma_f32 v[16:17], v[114:115], v[16:17], v[122:123] op_sel_hi:[0,1,1] neg_lo:[0,0,1] neg_hi:[0,0,1]
	v_cvt_pk_bf16_f32 v178, v16, v17
	v_pk_fma_f32 v[16:17], v[130:131], v[50:51], v[116:117] op_sel_hi:[0,1,1]
	v_pk_fma_f32 v[16:17], v[132:133], v[46:47], v[16:17] op_sel_hi:[0,1,1]
	v_pk_fma_f32 v[16:17], v[134:135], v[42:43], v[16:17] op_sel_hi:[0,1,1]
	v_pk_fma_f32 v[16:17], v[154:155], v[38:39], v[16:17] op_sel_hi:[0,1,1]
	v_pk_fma_f32 v[16:17], v[156:157], v[32:33], v[16:17] op_sel_hi:[0,1,1]
	v_pk_fma_f32 v[16:17], v[170:171], v[28:29], v[16:17] op_sel_hi:[0,1,1]
	v_pk_fma_f32 v[16:17], v[172:173], v[24:25], v[16:17] op_sel_hi:[0,1,1]
	v_pk_fma_f32 v[116:117], v[174:175], v[20:21], v[16:17] op_sel_hi:[0,1,1]
	v_lshlrev_b32_e32 v16, 16, v19
	v_and_b32_e32 v17, 0xffff0000, v19
	v_pk_fma_f32 v[18:19], v[112:113], v[16:17], v[116:117] op_sel_hi:[0,1,1]
	v_pk_fma_f32 v[18:19], v[114:115], v[18:19], v[46:47] op_sel_hi:[0,1,1] neg_lo:[0,0,1] neg_hi:[0,0,1]
	v_cvt_pk_bf16_f32 v179, v18, v19
	v_lshl_add_u64 v[18:19], v[126:127], 0, s[0:1]
	global_store_dwordx4 v[18:19], v[176:179], off
	v_sub_u32_e32 v18, s15, v167
	v_add_u32_e32 v19, s15, v167
	v_max_i32_e32 v115, 0, v18
	v_min_i32_e32 v117, s9, v19
	v_cmp_ge_i32_e32 vcc, s21, v115
	v_cmp_lt_i32_e64 s[0:1], s21, v117
	s_and_b64 s[0:1], vcc, s[0:1]
	v_cmp_ge_i32_e32 vcc, s20, v115
	v_cndmask_b32_e64 v112, 0, 1.0, s[0:1]
	v_cmp_lt_i32_e64 s[0:1], s20, v117
	s_and_b64 s[0:1], vcc, s[0:1]
	v_cmp_ge_i32_e32 vcc, s19, v115
	v_cndmask_b32_e64 v114, 0, 1.0, s[0:1]
	v_cmp_lt_i32_e64 s[0:1], s19, v117
	s_and_b64 s[0:1], vcc, s[0:1]
	v_cmp_ge_i32_e32 vcc, s10, v115
	v_cndmask_b32_e64 v116, 0, 1.0, s[0:1]
	v_cmp_lt_i32_e64 s[0:1], s10, v117
	s_and_b64 s[0:1], vcc, s[0:1]
	v_cmp_ge_i32_e32 vcc, s11, v115
	v_cndmask_b32_e64 v130, 0, 1.0, s[0:1]
	v_cmp_lt_i32_e64 s[0:1], s11, v117
	s_and_b64 s[0:1], vcc, s[0:1]
	v_pk_fma_f32 v[18:19], v[112:113], v[92:93], 0 op_sel_hi:[0,1,0]
	v_cndmask_b32_e64 v132, 0, 1.0, s[0:1]
	v_cmp_ge_i32_e32 vcc, s12, v115
	v_cmp_lt_i32_e64 s[0:1], s12, v117
	v_pk_fma_f32 v[18:19], v[114:115], v[88:89], v[18:19] op_sel_hi:[0,1,1]
	s_and_b64 s[0:1], vcc, s[0:1]
	v_pk_fma_f32 v[18:19], v[116:117], v[86:87], v[18:19] op_sel_hi:[0,1,1]
	v_cndmask_b32_e64 v134, 0, 1.0, s[0:1]
	v_cmp_ge_i32_e32 vcc, s13, v115
	v_cmp_lt_i32_e64 s[0:1], s13, v117
	v_pk_fma_f32 v[18:19], v[130:131], v[84:85], v[18:19] op_sel_hi:[0,1,1]
	s_and_b64 s[0:1], vcc, s[0:1]
	v_pk_fma_f32 v[18:19], v[132:133], v[60:61], v[18:19] op_sel_hi:[0,1,1]
	v_cndmask_b32_e64 v154, 0, 1.0, s[0:1]
	v_pk_fma_f32 v[18:19], v[134:135], v[74:75], v[18:19] op_sel_hi:[0,1,1]
	v_pk_fma_f32 v[172:173], v[154:155], v[106:107], v[18:19] op_sel_hi:[0,1,1]
	v_pk_fma_f32 v[18:19], v[112:113], v[94:95], 0 op_sel_hi:[0,1,0]
	v_pk_fma_f32 v[18:19], v[114:115], v[80:81], v[18:19] op_sel_hi:[0,1,1]
	v_pk_fma_f32 v[18:19], v[116:117], v[72:73], v[18:19] op_sel_hi:[0,1,1]
	v_pk_fma_f32 v[18:19], v[130:131], v[64:65], v[18:19] op_sel_hi:[0,1,1]
	v_pk_fma_f32 v[18:19], v[132:133], v[56:57], v[18:19] op_sel_hi:[0,1,1]
	v_pk_fma_f32 v[18:19], v[134:135], v[52:53], v[18:19] op_sel_hi:[0,1,1]
	v_cmp_ge_i32_e32 vcc, s14, v115
	v_cmp_lt_i32_e64 s[0:1], s14, v117
	v_pk_fma_f32 v[92:93], v[154:155], v[48:49], v[18:19] op_sel_hi:[0,1,1]
	v_pk_fma_f32 v[18:19], v[112:113], v[96:97], 0 op_sel_hi:[0,1,0]
	v_pk_fma_f32 v[94:95], v[112:113], v[110:111], 0 op_sel_hi:[0,1,0]
	s_and_b64 s[0:1], vcc, s[0:1]
	v_pk_fma_f32 v[18:19], v[114:115], v[90:91], v[18:19] op_sel_hi:[0,1,1]
	v_pk_fma_f32 v[94:95], v[114:115], v[82:83], v[94:95] op_sel_hi:[0,1,1]
	v_cndmask_b32_e64 v114, 0, 1.0, s[0:1]
	v_cmp_ge_i32_e32 vcc, s15, v115
	v_cmp_lt_i32_e64 s[0:1], s15, v117
	s_and_b64 s[0:1], vcc, s[0:1]
	v_pk_fma_f32 v[18:19], v[116:117], v[76:77], v[18:19] op_sel_hi:[0,1,1]
	v_pk_fma_f32 v[94:95], v[116:117], v[70:71], v[94:95] op_sel_hi:[0,1,1]
	v_cndmask_b32_e64 v116, 0, 1.0, s[0:1]
	v_cmp_ge_i32_e32 vcc, s17, v115
	v_cmp_lt_i32_e64 s[0:1], s17, v117
	s_and_b64 s[0:1], vcc, s[0:1]
	v_pk_fma_f32 v[18:19], v[130:131], v[68:69], v[18:19] op_sel_hi:[0,1,1]
	v_pk_fma_f32 v[94:95], v[130:131], v[66:67], v[94:95] op_sel_hi:[0,1,1]
	v_cndmask_b32_e64 v130, 0, 1.0, s[0:1]
	v_cmp_ge_i32_e32 vcc, s16, v115
; __device__ __forceinline__ unsigned cvt_pk_bf16(float lo, float hi) { const f32x2 v = (f32x2){lo, hi}; return __builtin_bit_cast(unsigned, __builtin_convertvector(v, bf16v2)); }
; __device__ __forceinline__ float bf_lo(unsigned w) { return __uint_as_float(w << 16); }
; __device__ __forceinline__ float bf_hi(unsigned w) { return __uint_as_float(w & 0xffff0000u); }
; __device__ __forceinline__ void phase_mixer(const Params& p, LAS unsigned char* lds, int l, bool with_ctx, int G, int tid, int wave, int lane, int rep_attn, int rep_pool) {
;     ...
;         for (int o = 0; o < 16; ++o) {
;             const int t = t0 + o, st = max(t - lo, 0), en = min(t + hi + 1, len);
;             float acc[8];
; #pragma unroll
;             for (int e = 0; e < 8; ++e) acc[e] = 0.f;
; #pragma unroll
;             for (int i = 0; i < 16; ++i) { const int tt = t + i - 8; const float wt = (tt >= st && tt < en) ? 1.f : 0.f; const u32x4 ww = w[o + i];
;                 acc[0] += wt * bf_lo(ww.x); acc[1] += wt * bf_hi(ww.x); acc[2] += wt * bf_lo(ww.y); acc[3] += wt * bf_hi(ww.y);
;                 acc[4] += wt * bf_lo(ww.z); acc[5] += wt * bf_hi(ww.z); acc[6] += wt * bf_lo(ww.w); acc[7] += wt * bf_hi(ww.w); }
;             const float ic = 1.f / (float)(en - st);
;             const u32x4 sw = w[o + 8];
;             u32x4 ov; ov.x = cvt_pk_bf16(acc[0] * ic - bf_lo(sw.x), acc[1] * ic - bf_hi(sw.x)); ov.y = cvt_pk_bf16(acc[2] * ic - bf_lo(sw.y), acc[3] * ic - bf_hi(sw.y));
;             ov.z = cvt_pk_bf16(acc[4] * ic - bf_lo(sw.z), acc[5] * ic - bf_hi(sw.z)); ov.w = cvt_pk_bf16(acc[6] * ic - bf_lo(sw.w), acc[7] * ic - bf_hi(sw.w));
;             *(u32x4*)(MIX + (size_t)(tok0 + o) * DM + 8 * lane) = ov;
	v_cmp_lt_i32_e64 s[0:1], s16, v117
	s_and_b64 s[0:1], vcc, s[0:1]
	v_pk_fma_f32 v[18:19], v[132:133], v[62:63], v[18:19] op_sel_hi:[0,1,1]
	v_pk_fma_f32 v[94:95], v[132:133], v[58:59], v[94:95] op_sel_hi:[0,1,1]
	v_cndmask_b32_e64 v132, 0, 1.0, s[0:1]
	v_cmp_ge_i32_e32 vcc, s18, v115
	v_cmp_lt_i32_e64 s[0:1], s18, v117
	s_and_b64 s[0:1], vcc, s[0:1]
	v_pk_fma_f32 v[18:19], v[134:135], v[78:79], v[18:19] op_sel_hi:[0,1,1]
	v_pk_fma_f32 v[94:95], v[134:135], v[54:55], v[94:95] op_sel_hi:[0,1,1]
	v_cndmask_b32_e64 v134, 0, 1.0, s[0:1]
	v_cmp_ge_i32_e32 vcc, s5, v115
	v_cmp_lt_i32_e64 s[0:1], s5, v117
	s_and_b64 s[0:1], vcc, s[0:1]
	v_pk_fma_f32 v[18:19], v[154:155], v[108:109], v[18:19] op_sel_hi:[0,1,1]
	v_pk_fma_f32 v[112:113], v[154:155], v[50:51], v[94:95] op_sel_hi:[0,1,1]
	v_cndmask_b32_e64 v154, 0, 1.0, s[0:1]
	v_cmp_ge_i32_e32 vcc, s23, v115
	v_cmp_lt_i32_e64 s[0:1], s23, v117
	s_and_b64 s[0:1], vcc, s[0:1]
	v_sub_u32_e32 v94, v117, v115
	v_cndmask_b32_e64 v156, 0, 1.0, s[0:1]
	v_cmp_ge_i32_e32 vcc, s22, v115
	v_cmp_lt_i32_e64 s[0:1], s22, v117
	v_cvt_f32_i32_e32 v94, v94
	s_and_b64 s[0:1], vcc, s[0:1]
	s_add_i32 s21, s8, 19
	v_cndmask_b32_e64 v170, 0, 1.0, s[0:1]
	v_cmp_ge_i32_e32 vcc, s21, v115
	v_cmp_lt_i32_e64 s[0:1], s21, v117
	s_and_b64 s[0:1], vcc, s[0:1]
	s_nop 0
	v_cndmask_b32_e64 v96, 0, 1.0, s[0:1]
	v_div_scale_f32 v95, s[0:1], v94, v94, 1.0
	v_rcp_f32_e32 v97, v95
	s_or_b32 s0, s4, 12
	s_ashr_i32 s1, s0, 31
	s_lshl_b64 s[0:1], s[0:1], 11
	v_fma_f32 v110, -v95, v97, 1.0
	v_fmac_f32_e32 v97, v110, v97
	v_div_scale_f32 v110, vcc, 1.0, v94, 1.0
	v_mul_f32_e32 v111, v110, v97
	v_fma_f32 v115, -v95, v111, v110
	v_fmac_f32_e32 v111, v115, v97
	v_fma_f32 v95, -v95, v111, v110
	v_div_fmas_f32 v95, v95, v97, v111
	v_div_fixup_f32 v110, v95, v94, 1.0
	v_pk_fma_f32 v[94:95], v[114:115], v[120:121], v[172:173] op_sel_hi:[0,1,1]
	v_pk_fma_f32 v[92:93], v[114:115], v[44:45], v[92:93] op_sel_hi:[0,1,1]
	v_pk_fma_f32 v[94:95], v[116:117], v[136:137], v[94:95] op_sel_hi:[0,1,1]
	v_pk_fma_f32 v[92:93], v[116:117], v[40:41], v[92:93] op_sel_hi:[0,1,1]
	v_pk_fma_f32 v[94:95], v[130:131], v[148:149], v[94:95] op_sel_hi:[0,1,1]
	v_pk_fma_f32 v[92:93], v[130:131], v[36:37], v[92:93] op_sel_hi:[0,1,1]
	v_pk_fma_f32 v[94:95], v[132:133], v[144:145], v[94:95] op_sel_hi:[0,1,1]
	v_pk_fma_f32 v[92:93], v[132:133], v[142:143], v[92:93] op_sel_hi:[0,1,1]
	v_pk_fma_f32 v[94:95], v[134:135], v[152:153], v[94:95] op_sel_hi:[0,1,1]
	v_pk_fma_f32 v[92:93], v[134:135], v[146:147], v[92:93] op_sel_hi:[0,1,1]
	v_pk_fma_f32 v[94:95], v[154:155], v[128:129], v[94:95] op_sel_hi:[0,1,1]
	v_pk_fma_f32 v[92:93], v[154:155], v[118:119], v[92:93] op_sel_hi:[0,1,1]
	v_pk_fma_f32 v[94:95], v[156:157], v[100:101], v[94:95] op_sel_hi:[0,1,1]
	v_pk_fma_f32 v[92:93], v[156:157], v[98:99], v[92:93] op_sel_hi:[0,1,1]
	v_pk_fma_f32 v[172:173], v[170:171], v[104:105], v[94:95] op_sel_hi:[0,1,1]
	s_waitcnt vmcnt(15)
	v_lshlrev_b32_e32 v94, 16, v12
	v_and_b32_e32 v95, 0xffff0000, v12
	v_pk_fma_f32 v[174:175], v[170:171], v[102:103], v[92:93] op_sel_hi:[0,1,1]
	v_lshlrev_b32_e32 v92, 16, v13
	v_and_b32_e32 v93, 0xffff0000, v13
	v_pk_fma_f32 v[172:173], v[96:97], v[94:95], v[172:173] op_sel_hi:[0,1,1]
	v_pk_fma_f32 v[12:13], v[96:97], v[92:93], v[174:175] op_sel_hi:[0,1,1]
	v_pk_fma_f32 v[172:173], v[110:111], v[172:173], v[136:137] op_sel_hi:[0,1,1] neg_lo:[0,0,1] neg_hi:[0,0,1]
	v_pk_fma_f32 v[12:13], v[110:111], v[12:13], v[40:41] op_sel_hi:[0,1,1] neg_lo:[0,0,1] neg_hi:[0,0,1]
	v_cvt_pk_bf16_f32 v172, v172, v173
	v_cvt_pk_bf16_f32 v173, v12, v13
	v_pk_fma_f32 v[12:13], v[114:115], v[122:123], v[18:19] op_sel_hi:[0,1,1]
	v_pk_fma_f32 v[12:13], v[116:117], v[138:139], v[12:13] op_sel_hi:[0,1,1]
	v_pk_fma_f32 v[12:13], v[130:131], v[150:151], v[12:13] op_sel_hi:[0,1,1]
	v_pk_fma_f32 v[12:13], v[132:133], v[140:141], v[12:13] op_sel_hi:[0,1,1]
	v_pk_fma_f32 v[12:13], v[134:135], v[34:35], v[12:13] op_sel_hi:[0,1,1]
	v_pk_fma_f32 v[12:13], v[154:155], v[30:31], v[12:13] op_sel_hi:[0,1,1]
	v_pk_fma_f32 v[12:13], v[156:157], v[26:27], v[12:13] op_sel_hi:[0,1,1]
	v_pk_fma_f32 v[12:13], v[170:171], v[22:23], v[12:13] op_sel_hi:[0,1,1]
	v_lshlrev_b32_e32 v18, 16, v14
	v_and_b32_e32 v19, 0xffff0000, v14
	v_pk_fma_f32 v[12:13], v[96:97], v[18:19], v[12:13] op_sel_hi:[0,1,1]
	v_pk_fma_f32 v[12:13], v[110:111], v[12:13], v[138:139] op_sel_hi:[0,1,1] neg_lo:[0,0,1] neg_hi:[0,0,1]
	v_cvt_pk_bf16_f32 v174, v12, v13
	v_pk_fma_f32 v[12:13], v[114:115], v[46:47], v[112:113] op_sel_hi:[0,1,1]
	v_pk_fma_f32 v[12:13], v[116:117], v[42:43], v[12:13] op_sel_hi:[0,1,1]
	v_pk_fma_f32 v[12:13], v[130:131], v[38:39], v[12:13] op_sel_hi:[0,1,1]
	v_pk_fma_f32 v[12:13], v[132:133], v[32:33], v[12:13] op_sel_hi:[0,1,1]
	v_pk_fma_f32 v[12:13], v[134:135], v[28:29], v[12:13] op_sel_hi:[0,1,1]
	v_pk_fma_f32 v[12:13], v[154:155], v[24:25], v[12:13] op_sel_hi:[0,1,1]
	v_pk_fma_f32 v[12:13], v[156:157], v[20:21], v[12:13] op_sel_hi:[0,1,1]
	v_pk_fma_f32 v[112:113], v[170:171], v[16:17], v[12:13] op_sel_hi:[0,1,1]
	v_lshlrev_b32_e32 v12, 16, v15
	v_and_b32_e32 v13, 0xffff0000, v15
	v_pk_fma_f32 v[14:15], v[96:97], v[12:13], v[112:113] op_sel_hi:[0,1,1]
	v_pk_fma_f32 v[14:15], v[110:111], v[14:15], v[42:43] op_sel_hi:[0,1,1] neg_lo:[0,0,1] neg_hi:[0,0,1]
	v_cvt_pk_bf16_f32 v175, v14, v15
	v_lshl_add_u64 v[14:15], v[126:127], 0, s[0:1]
	global_store_dwordx4 v[14:15], v[172:175], off
	v_sub_u32_e32 v14, s17, v167
	v_add_u32_e32 v15, s17, v167
	v_max_i32_e32 v111, 0, v14
	v_min_i32_e32 v113, s9, v15
	v_cmp_ge_i32_e32 vcc, s20, v111
	v_cmp_lt_i32_e64 s[0:1], s20, v113
	s_and_b64 s[0:1], vcc, s[0:1]
	v_cmp_ge_i32_e32 vcc, s19, v111
; __device__ __forceinline__ unsigned cvt_pk_bf16(float lo, float hi) { const f32x2 v = (f32x2){lo, hi}; return __builtin_bit_cast(unsigned, __builtin_convertvector(v, bf16v2)); }
; __device__ __forceinline__ float bf_lo(unsigned w) { return __uint_as_float(w << 16); }
; __device__ __forceinline__ float bf_hi(unsigned w) { return __uint_as_float(w & 0xffff0000u); }
; __device__ __forceinline__ void phase_mixer(const Params& p, LAS unsigned char* lds, int l, bool with_ctx, int G, int tid, int wave, int lane, int rep_attn, int rep_pool) {
;     ...
;         for (int o = 0; o < 16; ++o) {
;             const int t = t0 + o, st = max(t - lo, 0), en = min(t + hi + 1, len);
;             float acc[8];
; #pragma unroll
;             for (int e = 0; e < 8; ++e) acc[e] = 0.f;
; #pragma unroll
;             for (int i = 0; i < 16; ++i) { const int tt = t + i - 8; const float wt = (tt >= st && tt < en) ? 1.f : 0.f; const u32x4 ww = w[o + i];
;                 acc[0] += wt * bf_lo(ww.x); acc[1] += wt * bf_hi(ww.x); acc[2] += wt * bf_lo(ww.y); acc[3] += wt * bf_hi(ww.y);
;                 acc[4] += wt * bf_lo(ww.z); acc[5] += wt * bf_hi(ww.z); acc[6] += wt * bf_lo(ww.w); acc[7] += wt * bf_hi(ww.w); }
;             const float ic = 1.f / (float)(en - st);
;             const u32x4 sw = w[o + 8];
;             u32x4 ov; ov.x = cvt_pk_bf16(acc[0] * ic - bf_lo(sw.x), acc[1] * ic - bf_hi(sw.x)); ov.y = cvt_pk_bf16(acc[2] * ic - bf_lo(sw.y), acc[3] * ic - bf_hi(sw.y));
	v_cndmask_b32_e64 v96, 0, 1.0, s[0:1]
	v_cmp_lt_i32_e64 s[0:1], s19, v113
	s_and_b64 s[0:1], vcc, s[0:1]
	v_cmp_ge_i32_e32 vcc, s10, v111
	v_cndmask_b32_e64 v110, 0, 1.0, s[0:1]
	v_cmp_lt_i32_e64 s[0:1], s10, v113
	s_and_b64 s[0:1], vcc, s[0:1]
	v_cmp_ge_i32_e32 vcc, s11, v111
	v_cndmask_b32_e64 v112, 0, 1.0, s[0:1]
	v_cmp_lt_i32_e64 s[0:1], s11, v113
	s_and_b64 s[0:1], vcc, s[0:1]
	v_cmp_ge_i32_e32 vcc, s12, v111
	v_cndmask_b32_e64 v114, 0, 1.0, s[0:1]
	v_cmp_lt_i32_e64 s[0:1], s12, v113
	s_and_b64 s[0:1], vcc, s[0:1]
	v_pk_fma_f32 v[14:15], v[96:97], v[88:89], 0 op_sel_hi:[0,1,0]
	v_cndmask_b32_e64 v116, 0, 1.0, s[0:1]
	v_cmp_ge_i32_e32 vcc, s13, v111
	v_cmp_lt_i32_e64 s[0:1], s13, v113
	v_pk_fma_f32 v[14:15], v[110:111], v[86:87], v[14:15] op_sel_hi:[0,1,1]
	s_and_b64 s[0:1], vcc, s[0:1]
	v_pk_fma_f32 v[14:15], v[112:113], v[84:85], v[14:15] op_sel_hi:[0,1,1]
	v_cndmask_b32_e64 v130, 0, 1.0, s[0:1]
	v_cmp_ge_i32_e32 vcc, s14, v111
	v_cmp_lt_i32_e64 s[0:1], s14, v113
	v_pk_fma_f32 v[14:15], v[114:115], v[60:61], v[14:15] op_sel_hi:[0,1,1]
	s_and_b64 s[0:1], vcc, s[0:1]
	v_pk_fma_f32 v[14:15], v[116:117], v[74:75], v[14:15] op_sel_hi:[0,1,1]
	v_cndmask_b32_e64 v132, 0, 1.0, s[0:1]
	v_pk_fma_f32 v[14:15], v[130:131], v[106:107], v[14:15] op_sel_hi:[0,1,1]
	v_pk_fma_f32 v[170:171], v[132:133], v[120:121], v[14:15] op_sel_hi:[0,1,1]
	v_pk_fma_f32 v[14:15], v[96:97], v[80:81], 0 op_sel_hi:[0,1,0]
	v_pk_fma_f32 v[14:15], v[110:111], v[72:73], v[14:15] op_sel_hi:[0,1,1]
	v_pk_fma_f32 v[14:15], v[112:113], v[64:65], v[14:15] op_sel_hi:[0,1,1]
	v_pk_fma_f32 v[14:15], v[114:115], v[56:57], v[14:15] op_sel_hi:[0,1,1]
	v_pk_fma_f32 v[14:15], v[116:117], v[52:53], v[14:15] op_sel_hi:[0,1,1]
	v_pk_fma_f32 v[14:15], v[130:131], v[48:49], v[14:15] op_sel_hi:[0,1,1]
	v_cmp_ge_i32_e32 vcc, s15, v111
	v_cmp_lt_i32_e64 s[0:1], s15, v113
	v_pk_fma_f32 v[80:81], v[132:133], v[44:45], v[14:15] op_sel_hi:[0,1,1]
	v_pk_fma_f32 v[14:15], v[96:97], v[90:91], 0 op_sel_hi:[0,1,0]
	v_pk_fma_f32 v[82:83], v[96:97], v[82:83], 0 op_sel_hi:[0,1,0]
	s_and_b64 s[0:1], vcc, s[0:1]
	v_pk_fma_f32 v[14:15], v[110:111], v[76:77], v[14:15] op_sel_hi:[0,1,1]
	v_pk_fma_f32 v[82:83], v[110:111], v[70:71], v[82:83] op_sel_hi:[0,1,1]
	v_cndmask_b32_e64 v110, 0, 1.0, s[0:1]
	v_cmp_ge_i32_e32 vcc, s17, v111
	v_cmp_lt_i32_e64 s[0:1], s17, v113
	s_and_b64 s[0:1], vcc, s[0:1]
	v_pk_fma_f32 v[14:15], v[112:113], v[68:69], v[14:15] op_sel_hi:[0,1,1]
	v_pk_fma_f32 v[82:83], v[112:113], v[66:67], v[82:83] op_sel_hi:[0,1,1]
	v_cndmask_b32_e64 v112, 0, 1.0, s[0:1]
	v_cmp_ge_i32_e32 vcc, s16, v111
	v_cmp_lt_i32_e64 s[0:1], s16, v113
	s_and_b64 s[0:1], vcc, s[0:1]
	v_pk_fma_f32 v[14:15], v[114:115], v[62:63], v[14:15] op_sel_hi:[0,1,1]
	v_pk_fma_f32 v[82:83], v[114:115], v[58:59], v[82:83] op_sel_hi:[0,1,1]
	v_cndmask_b32_e64 v114, 0, 1.0, s[0:1]
	v_cmp_ge_i32_e32 vcc, s18, v111
	v_cmp_lt_i32_e64 s[0:1], s18, v113
	s_and_b64 s[0:1], vcc, s[0:1]
	v_pk_fma_f32 v[14:15], v[116:117], v[78:79], v[14:15] op_sel_hi:[0,1,1]
	v_pk_fma_f32 v[82:83], v[116:117], v[54:55], v[82:83] op_sel_hi:[0,1,1]
	v_cndmask_b32_e64 v116, 0, 1.0, s[0:1]
	v_cmp_ge_i32_e32 vcc, s5, v111
	v_cmp_lt_i32_e64 s[0:1], s5, v113
	s_and_b64 s[0:1], vcc, s[0:1]
	v_pk_fma_f32 v[14:15], v[130:131], v[108:109], v[14:15] op_sel_hi:[0,1,1]
	v_pk_fma_f32 v[82:83], v[130:131], v[50:51], v[82:83] op_sel_hi:[0,1,1]
	v_cndmask_b32_e64 v130, 0, 1.0, s[0:1]
	v_cmp_ge_i32_e32 vcc, s23, v111
	v_cmp_lt_i32_e64 s[0:1], s23, v113
	s_and_b64 s[0:1], vcc, s[0:1]
	v_pk_fma_f32 v[14:15], v[132:133], v[122:123], v[14:15] op_sel_hi:[0,1,1]
	v_pk_fma_f32 v[96:97], v[132:133], v[46:47], v[82:83] op_sel_hi:[0,1,1]
	v_cndmask_b32_e64 v132, 0, 1.0, s[0:1]
	v_cmp_ge_i32_e32 vcc, s22, v111
	v_cmp_lt_i32_e64 s[0:1], s22, v113
	s_and_b64 s[0:1], vcc, s[0:1]
	v_sub_u32_e32 v82, v113, v111
	v_cndmask_b32_e64 v134, 0, 1.0, s[0:1]
	v_cmp_ge_i32_e32 vcc, s21, v111
	v_cmp_lt_i32_e64 s[0:1], s21, v113
	v_cvt_f32_i32_e32 v82, v82
	s_and_b64 s[0:1], vcc, s[0:1]
	s_add_i32 s20, s8, 20
	v_cndmask_b32_e64 v154, 0, 1.0, s[0:1]
	v_cmp_ge_i32_e32 vcc, s20, v111
	v_cmp_lt_i32_e64 s[0:1], s20, v113
	s_and_b64 s[0:1], vcc, s[0:1]
	s_nop 0
	v_cndmask_b32_e64 v88, 0, 1.0, s[0:1]
	v_div_scale_f32 v83, s[0:1], v82, v82, 1.0
	v_rcp_f32_e32 v89, v83
	s_or_b32 s0, s4, 13
	s_ashr_i32 s1, s0, 31
	s_lshl_b64 s[0:1], s[0:1], 11
	v_fma_f32 v90, -v83, v89, 1.0
	v_fmac_f32_e32 v89, v90, v89
	v_div_scale_f32 v90, vcc, 1.0, v82, 1.0
	v_mul_f32_e32 v91, v90, v89
	v_fma_f32 v111, -v83, v91, v90
	v_fmac_f32_e32 v91, v111, v89
	v_fma_f32 v83, -v83, v91, v90
	v_div_fmas_f32 v83, v83, v89, v91
	v_div_fixup_f32 v90, v83, v82, 1.0
	v_pk_fma_f32 v[82:83], v[110:111], v[136:137], v[170:171] op_sel_hi:[0,1,1]
	v_pk_fma_f32 v[80:81], v[110:111], v[40:41], v[80:81] op_sel_hi:[0,1,1]
	v_pk_fma_f32 v[82:83], v[112:113], v[148:149], v[82:83] op_sel_hi:[0,1,1]
	v_pk_fma_f32 v[80:81], v[112:113], v[36:37], v[80:81] op_sel_hi:[0,1,1]
	v_pk_fma_f32 v[82:83], v[114:115], v[144:145], v[82:83] op_sel_hi:[0,1,1]
	v_pk_fma_f32 v[80:81], v[114:115], v[142:143], v[80:81] op_sel_hi:[0,1,1]
	v_pk_fma_f32 v[82:83], v[116:117], v[152:153], v[82:83] op_sel_hi:[0,1,1]
	v_pk_fma_f32 v[80:81], v[116:117], v[146:147], v[80:81] op_sel_hi:[0,1,1]
	v_pk_fma_f32 v[82:83], v[130:131], v[128:129], v[82:83] op_sel_hi:[0,1,1]
	v_pk_fma_f32 v[80:81], v[130:131], v[118:119], v[80:81] op_sel_hi:[0,1,1]
	v_pk_fma_f32 v[82:83], v[132:133], v[100:101], v[82:83] op_sel_hi:[0,1,1]
	v_pk_fma_f32 v[80:81], v[132:133], v[98:99], v[80:81] op_sel_hi:[0,1,1]
	v_pk_fma_f32 v[82:83], v[134:135], v[104:105], v[82:83] op_sel_hi:[0,1,1]
	v_pk_fma_f32 v[80:81], v[134:135], v[102:103], v[80:81] op_sel_hi:[0,1,1]
	v_pk_fma_f32 v[170:171], v[154:155], v[94:95], v[82:83] op_sel_hi:[0,1,1]
	s_waitcnt vmcnt(15)
; __device__ __forceinline__ unsigned cvt_pk_bf16(float lo, float hi) { const f32x2 v = (f32x2){lo, hi}; return __builtin_bit_cast(unsigned, __builtin_convertvector(v, bf16v2)); }
; __device__ __forceinline__ float bf_lo(unsigned w) { return __uint_as_float(w << 16); }
; __device__ __forceinline__ float bf_hi(unsigned w) { return __uint_as_float(w & 0xffff0000u); }
; __device__ __forceinline__ void phase_mixer(const Params& p, LAS unsigned char* lds, int l, bool with_ctx, int G, int tid, int wave, int lane, int rep_attn, int rep_pool) {
;     ...
;         for (int o = 0; o < 16; ++o) {
;             const int t = t0 + o, st = max(t - lo, 0), en = min(t + hi + 1, len);
;             float acc[8];
; #pragma unroll
;             for (int e = 0; e < 8; ++e) acc[e] = 0.f;
; #pragma unroll
;             for (int i = 0; i < 16; ++i) { const int tt = t + i - 8; const float wt = (tt >= st && tt < en) ? 1.f : 0.f; const u32x4 ww = w[o + i];
;                 acc[0] += wt * bf_lo(ww.x); acc[1] += wt * bf_hi(ww.x); acc[2] += wt * bf_lo(ww.y); acc[3] += wt * bf_hi(ww.y);
;                 acc[4] += wt * bf_lo(ww.z); acc[5] += wt * bf_hi(ww.z); acc[6] += wt * bf_lo(ww.w); acc[7] += wt * bf_hi(ww.w); }
;             const float ic = 1.f / (float)(en - st);
;             const u32x4 sw = w[o + 8];
;             u32x4 ov; ov.x = cvt_pk_bf16(acc[0] * ic - bf_lo(sw.x), acc[1] * ic - bf_hi(sw.x)); ov.y = cvt_pk_bf16(acc[2] * ic - bf_lo(sw.y), acc[3] * ic - bf_hi(sw.y));
;             ov.z = cvt_pk_bf16(acc[4] * ic - bf_lo(sw.z), acc[5] * ic - bf_hi(sw.z)); ov.w = cvt_pk_bf16(acc[6] * ic - bf_lo(sw.w), acc[7] * ic - bf_hi(sw.w));
;             *(u32x4*)(MIX + (size_t)(tok0 + o) * DM + 8 * lane) = ov;
	v_lshlrev_b32_e32 v82, 16, v8
	v_and_b32_e32 v83, 0xffff0000, v8
	v_pk_fma_f32 v[172:173], v[154:155], v[92:93], v[80:81] op_sel_hi:[0,1,1]
	v_lshlrev_b32_e32 v80, 16, v9
	v_and_b32_e32 v81, 0xffff0000, v9
	v_pk_fma_f32 v[170:171], v[88:89], v[82:83], v[170:171] op_sel_hi:[0,1,1]
	v_pk_fma_f32 v[8:9], v[88:89], v[80:81], v[172:173] op_sel_hi:[0,1,1]
	v_pk_fma_f32 v[170:171], v[90:91], v[170:171], v[148:149] op_sel_hi:[0,1,1] neg_lo:[0,0,1] neg_hi:[0,0,1]
	v_pk_fma_f32 v[8:9], v[90:91], v[8:9], v[36:37] op_sel_hi:[0,1,1] neg_lo:[0,0,1] neg_hi:[0,0,1]
	v_cvt_pk_bf16_f32 v170, v170, v171
	v_cvt_pk_bf16_f32 v171, v8, v9
	v_pk_fma_f32 v[8:9], v[110:111], v[138:139], v[14:15] op_sel_hi:[0,1,1]
	v_pk_fma_f32 v[8:9], v[112:113], v[150:151], v[8:9] op_sel_hi:[0,1,1]
	v_pk_fma_f32 v[8:9], v[114:115], v[140:141], v[8:9] op_sel_hi:[0,1,1]
	v_pk_fma_f32 v[8:9], v[116:117], v[34:35], v[8:9] op_sel_hi:[0,1,1]
	v_pk_fma_f32 v[8:9], v[130:131], v[30:31], v[8:9] op_sel_hi:[0,1,1]
	v_pk_fma_f32 v[8:9], v[132:133], v[26:27], v[8:9] op_sel_hi:[0,1,1]
	v_pk_fma_f32 v[8:9], v[134:135], v[22:23], v[8:9] op_sel_hi:[0,1,1]
	v_pk_fma_f32 v[8:9], v[154:155], v[18:19], v[8:9] op_sel_hi:[0,1,1]
	v_lshlrev_b32_e32 v14, 16, v10
	v_and_b32_e32 v15, 0xffff0000, v10
	v_pk_fma_f32 v[8:9], v[88:89], v[14:15], v[8:9] op_sel_hi:[0,1,1]
	v_pk_fma_f32 v[8:9], v[90:91], v[8:9], v[150:151] op_sel_hi:[0,1,1] neg_lo:[0,0,1] neg_hi:[0,0,1]
	v_cvt_pk_bf16_f32 v172, v8, v9
	v_pk_fma_f32 v[8:9], v[110:111], v[42:43], v[96:97] op_sel_hi:[0,1,1]
	v_pk_fma_f32 v[8:9], v[112:113], v[38:39], v[8:9] op_sel_hi:[0,1,1]
	v_pk_fma_f32 v[8:9], v[114:115], v[32:33], v[8:9] op_sel_hi:[0,1,1]
	v_pk_fma_f32 v[8:9], v[116:117], v[28:29], v[8:9] op_sel_hi:[0,1,1]
	v_pk_fma_f32 v[8:9], v[130:131], v[24:25], v[8:9] op_sel_hi:[0,1,1]
	v_pk_fma_f32 v[8:9], v[132:133], v[20:21], v[8:9] op_sel_hi:[0,1,1]
	v_pk_fma_f32 v[8:9], v[134:135], v[16:17], v[8:9] op_sel_hi:[0,1,1]
	v_pk_fma_f32 v[96:97], v[154:155], v[12:13], v[8:9] op_sel_hi:[0,1,1]
	v_lshlrev_b32_e32 v8, 16, v11
	v_and_b32_e32 v9, 0xffff0000, v11
	v_pk_fma_f32 v[10:11], v[88:89], v[8:9], v[96:97] op_sel_hi:[0,1,1]
	v_pk_fma_f32 v[10:11], v[90:91], v[10:11], v[38:39] op_sel_hi:[0,1,1] neg_lo:[0,0,1] neg_hi:[0,0,1]
	v_cvt_pk_bf16_f32 v173, v10, v11
	v_lshl_add_u64 v[10:11], v[126:127], 0, s[0:1]
	global_store_dwordx4 v[10:11], v[170:173], off
	v_sub_u32_e32 v10, s16, v167
	v_add_u32_e32 v11, s16, v167
	v_max_i32_e32 v89, 0, v10
	v_min_i32_e32 v91, s9, v11
	v_cmp_ge_i32_e32 vcc, s19, v89
	v_cmp_lt_i32_e64 s[0:1], s19, v91
	s_and_b64 s[0:1], vcc, s[0:1]
	v_cmp_ge_i32_e32 vcc, s10, v89
	v_cndmask_b32_e64 v10, 0, 1.0, s[0:1]
	v_cmp_lt_i32_e64 s[0:1], s10, v91
	s_and_b64 s[0:1], vcc, s[0:1]
	v_cmp_ge_i32_e32 vcc, s11, v89
	v_cndmask_b32_e64 v88, 0, 1.0, s[0:1]
	v_cmp_lt_i32_e64 s[0:1], s11, v91
	s_and_b64 s[0:1], vcc, s[0:1]
	v_cmp_ge_i32_e32 vcc, s12, v89
	v_cndmask_b32_e64 v90, 0, 1.0, s[0:1]
	v_cmp_lt_i32_e64 s[0:1], s12, v91
	s_and_b64 s[0:1], vcc, s[0:1]
	v_cmp_ge_i32_e32 vcc, s13, v89
	v_cndmask_b32_e64 v96, 0, 1.0, s[0:1]
	v_cmp_lt_i32_e64 s[0:1], s13, v91
	s_and_b64 s[0:1], vcc, s[0:1]
	v_cmp_ge_i32_e32 vcc, s14, v89
	v_cndmask_b32_e64 v110, 0, 1.0, s[0:1]
	v_cmp_lt_i32_e64 s[0:1], s14, v91
	s_and_b64 s[0:1], vcc, s[0:1]
	v_cmp_ge_i32_e32 vcc, s15, v89
	v_cndmask_b32_e64 v112, 0, 1.0, s[0:1]
	v_cmp_lt_i32_e64 s[0:1], s15, v91
	s_and_b64 s[0:1], vcc, s[0:1]
	v_cmp_ge_i32_e32 vcc, s17, v89
	v_cndmask_b32_e64 v114, 0, 1.0, s[0:1]
	v_cmp_lt_i32_e64 s[0:1], s17, v91
	v_pk_fma_f32 v[86:87], v[10:11], v[86:87], 0 op_sel_hi:[0,1,0]
	v_pk_fma_f32 v[72:73], v[10:11], v[72:73], 0 op_sel_hi:[0,1,0]
	v_pk_fma_f32 v[76:77], v[10:11], v[76:77], 0 op_sel_hi:[0,1,0]
	v_pk_fma_f32 v[10:11], v[10:11], v[70:71], 0 op_sel_hi:[0,1,0]
	s_and_b64 s[0:1], vcc, s[0:1]
	v_pk_fma_f32 v[86:87], v[88:89], v[84:85], v[86:87] op_sel_hi:[0,1,1]
	v_pk_fma_f32 v[72:73], v[88:89], v[64:65], v[72:73] op_sel_hi:[0,1,1]
	v_pk_fma_f32 v[76:77], v[88:89], v[68:69], v[76:77] op_sel_hi:[0,1,1]
	v_pk_fma_f32 v[10:11], v[88:89], v[66:67], v[10:11] op_sel_hi:[0,1,1]
	v_cndmask_b32_e64 v88, 0, 1.0, s[0:1]
	v_cmp_ge_i32_e32 vcc, s16, v89
	v_cmp_lt_i32_e64 s[0:1], s16, v91
	s_and_b64 s[0:1], vcc, s[0:1]
	v_pk_fma_f32 v[86:87], v[90:91], v[60:61], v[86:87] op_sel_hi:[0,1,1]
	v_pk_fma_f32 v[72:73], v[90:91], v[56:57], v[72:73] op_sel_hi:[0,1,1]
	v_pk_fma_f32 v[76:77], v[90:91], v[62:63], v[76:77] op_sel_hi:[0,1,1]
	v_pk_fma_f32 v[10:11], v[90:91], v[58:59], v[10:11] op_sel_hi:[0,1,1]
	v_cndmask_b32_e64 v90, 0, 1.0, s[0:1]
	v_cmp_ge_i32_e32 vcc, s18, v89
	v_cmp_lt_i32_e64 s[0:1], s18, v91
	s_and_b64 s[0:1], vcc, s[0:1]
	v_pk_fma_f32 v[86:87], v[96:97], v[74:75], v[86:87] op_sel_hi:[0,1,1]
	v_pk_fma_f32 v[72:73], v[96:97], v[52:53], v[72:73] op_sel_hi:[0,1,1]
	v_pk_fma_f32 v[76:77], v[96:97], v[78:79], v[76:77] op_sel_hi:[0,1,1]
	v_pk_fma_f32 v[10:11], v[96:97], v[54:55], v[10:11] op_sel_hi:[0,1,1]
	v_cndmask_b32_e64 v96, 0, 1.0, s[0:1]
	v_cmp_ge_i32_e32 vcc, s5, v89
	v_cmp_lt_i32_e64 s[0:1], s5, v91
	s_and_b64 s[0:1], vcc, s[0:1]
	v_pk_fma_f32 v[86:87], v[110:111], v[106:107], v[86:87] op_sel_hi:[0,1,1]
	v_pk_fma_f32 v[72:73], v[110:111], v[48:49], v[72:73] op_sel_hi:[0,1,1]
	v_pk_fma_f32 v[76:77], v[110:111], v[108:109], v[76:77] op_sel_hi:[0,1,1]
	v_pk_fma_f32 v[10:11], v[110:111], v[50:51], v[10:11] op_sel_hi:[0,1,1]
	v_cndmask_b32_e64 v110, 0, 1.0, s[0:1]
	v_cmp_ge_i32_e32 vcc, s23, v89
	v_cmp_lt_i32_e64 s[0:1], s23, v91
	s_and_b64 s[0:1], vcc, s[0:1]
	v_pk_fma_f32 v[86:87], v[112:113], v[120:121], v[86:87] op_sel_hi:[0,1,1]
	v_pk_fma_f32 v[72:73], v[112:113], v[44:45], v[72:73] op_sel_hi:[0,1,1]
; __device__ __forceinline__ unsigned cvt_pk_bf16(float lo, float hi) { const f32x2 v = (f32x2){lo, hi}; return __builtin_bit_cast(unsigned, __builtin_convertvector(v, bf16v2)); }
; __device__ __forceinline__ float bf_lo(unsigned w) { return __uint_as_float(w << 16); }
; __device__ __forceinline__ float bf_hi(unsigned w) { return __uint_as_float(w & 0xffff0000u); }
; __device__ __forceinline__ void phase_mixer(const Params& p, LAS unsigned char* lds, int l, bool with_ctx, int G, int tid, int wave, int lane, int rep_attn, int rep_pool) {
;     ...
;         for (int o = 0; o < 16; ++o) {
;             const int t = t0 + o, st = max(t - lo, 0), en = min(t + hi + 1, len);
;             float acc[8];
; #pragma unroll
;             for (int e = 0; e < 8; ++e) acc[e] = 0.f;
; #pragma unroll
;             for (int i = 0; i < 16; ++i) { const int tt = t + i - 8; const float wt = (tt >= st && tt < en) ? 1.f : 0.f; const u32x4 ww = w[o + i];
;                 acc[0] += wt * bf_lo(ww.x); acc[1] += wt * bf_hi(ww.x); acc[2] += wt * bf_lo(ww.y); acc[3] += wt * bf_hi(ww.y);
;                 acc[4] += wt * bf_lo(ww.z); acc[5] += wt * bf_hi(ww.z); acc[6] += wt * bf_lo(ww.w); acc[7] += wt * bf_hi(ww.w); }
;             const float ic = 1.f / (float)(en - st);
;             const u32x4 sw = w[o + 8];
;             u32x4 ov; ov.x = cvt_pk_bf16(acc[0] * ic - bf_lo(sw.x), acc[1] * ic - bf_hi(sw.x)); ov.y = cvt_pk_bf16(acc[2] * ic - bf_lo(sw.y), acc[3] * ic - bf_hi(sw.y));
;             ov.z = cvt_pk_bf16(acc[4] * ic - bf_lo(sw.z), acc[5] * ic - bf_hi(sw.z)); ov.w = cvt_pk_bf16(acc[6] * ic - bf_lo(sw.w), acc[7] * ic - bf_hi(sw.w));
;             *(u32x4*)(MIX + (size_t)(tok0 + o) * DM + 8 * lane) = ov;
	v_pk_fma_f32 v[76:77], v[112:113], v[122:123], v[76:77] op_sel_hi:[0,1,1]
	v_pk_fma_f32 v[10:11], v[112:113], v[46:47], v[10:11] op_sel_hi:[0,1,1]
	v_cndmask_b32_e64 v112, 0, 1.0, s[0:1]
	v_cmp_ge_i32_e32 vcc, s22, v89
	v_cmp_lt_i32_e64 s[0:1], s22, v91
	s_and_b64 s[0:1], vcc, s[0:1]
	v_pk_fma_f32 v[134:135], v[114:115], v[136:137], v[86:87] op_sel_hi:[0,1,1]
	v_pk_fma_f32 v[72:73], v[114:115], v[40:41], v[72:73] op_sel_hi:[0,1,1]
	v_pk_fma_f32 v[132:133], v[114:115], v[138:139], v[76:77] op_sel_hi:[0,1,1]
	v_pk_fma_f32 v[10:11], v[114:115], v[42:43], v[10:11] op_sel_hi:[0,1,1]
	v_cndmask_b32_e64 v114, 0, 1.0, s[0:1]
	v_cmp_ge_i32_e32 vcc, s21, v89
	v_cmp_lt_i32_e64 s[0:1], s21, v91
	s_and_b64 s[0:1], vcc, s[0:1]
	v_sub_u32_e32 v70, v91, v89
	v_cndmask_b32_e64 v116, 0, 1.0, s[0:1]
	v_cmp_ge_i32_e32 vcc, s20, v89
	v_cmp_lt_i32_e64 s[0:1], s20, v91
	v_cvt_f32_i32_e32 v70, v70
	s_and_b64 s[0:1], vcc, s[0:1]
	s_add_i32 s19, s8, 21
	v_cndmask_b32_e64 v130, 0, 1.0, s[0:1]
	v_cmp_ge_i32_e32 vcc, s19, v89
	v_cmp_lt_i32_e64 s[0:1], s19, v91
	s_and_b64 s[0:1], vcc, s[0:1]
	s_add_i32 s8, s8, 22
	v_cndmask_b32_e64 v76, 0, 1.0, s[0:1]
	v_div_scale_f32 v71, s[0:1], v70, v70, 1.0
	v_rcp_f32_e32 v77, v71
	s_or_b32 s0, s4, 14
	s_ashr_i32 s1, s0, 31
	s_lshl_b64 s[0:1], s[0:1], 11
	v_fma_f32 v86, -v71, v77, 1.0
	v_fmac_f32_e32 v77, v86, v77
	v_div_scale_f32 v86, vcc, 1.0, v70, 1.0
	v_mul_f32_e32 v87, v86, v77
	v_fma_f32 v89, -v71, v87, v86
	v_fmac_f32_e32 v87, v89, v77
	v_fma_f32 v71, -v71, v87, v86
	v_div_fmas_f32 v71, v71, v77, v87
	v_div_fixup_f32 v86, v71, v70, 1.0
	v_pk_fma_f32 v[70:71], v[88:89], v[148:149], v[134:135] op_sel_hi:[0,1,1]
	v_pk_fma_f32 v[70:71], v[90:91], v[144:145], v[70:71] op_sel_hi:[0,1,1]
	v_pk_fma_f32 v[70:71], v[96:97], v[152:153], v[70:71] op_sel_hi:[0,1,1]
	v_pk_fma_f32 v[70:71], v[110:111], v[128:129], v[70:71] op_sel_hi:[0,1,1]
	v_pk_fma_f32 v[70:71], v[112:113], v[100:101], v[70:71] op_sel_hi:[0,1,1]
	v_pk_fma_f32 v[70:71], v[114:115], v[104:105], v[70:71] op_sel_hi:[0,1,1]
	v_pk_fma_f32 v[70:71], v[116:117], v[94:95], v[70:71] op_sel_hi:[0,1,1]
	v_pk_fma_f32 v[70:71], v[130:131], v[82:83], v[70:71] op_sel_hi:[0,1,1]
	s_waitcnt vmcnt(15)
	v_lshlrev_b32_e32 v134, 16, v4
	v_and_b32_e32 v135, 0xffff0000, v4
	v_pk_fma_f32 v[70:71], v[76:77], v[134:135], v[70:71] op_sel_hi:[0,1,1]
	v_pk_fma_f32 v[70:71], v[86:87], v[70:71], v[144:145] op_sel_hi:[0,1,1] neg_lo:[0,0,1] neg_hi:[0,0,1]
	v_cvt_pk_bf16_f32 v4, v70, v71
	v_pk_fma_f32 v[70:71], v[88:89], v[36:37], v[72:73] op_sel_hi:[0,1,1]
	v_pk_fma_f32 v[70:71], v[90:91], v[142:143], v[70:71] op_sel_hi:[0,1,1]
	v_pk_fma_f32 v[70:71], v[96:97], v[146:147], v[70:71] op_sel_hi:[0,1,1]
	v_pk_fma_f32 v[70:71], v[110:111], v[118:119], v[70:71] op_sel_hi:[0,1,1]
	v_pk_fma_f32 v[70:71], v[112:113], v[98:99], v[70:71] op_sel_hi:[0,1,1]
	v_pk_fma_f32 v[70:71], v[114:115], v[102:103], v[70:71] op_sel_hi:[0,1,1]
	v_pk_fma_f32 v[70:71], v[116:117], v[92:93], v[70:71] op_sel_hi:[0,1,1]
	v_pk_fma_f32 v[70:71], v[130:131], v[80:81], v[70:71] op_sel_hi:[0,1,1]
	v_lshlrev_b32_e32 v72, 16, v5
	v_and_b32_e32 v73, 0xffff0000, v5
	v_pk_fma_f32 v[70:71], v[76:77], v[72:73], v[70:71] op_sel_hi:[0,1,1]
	v_pk_fma_f32 v[70:71], v[86:87], v[70:71], v[142:143] op_sel_hi:[0,1,1] neg_lo:[0,0,1] neg_hi:[0,0,1]
	v_cvt_pk_bf16_f32 v5, v70, v71
	v_pk_fma_f32 v[70:71], v[88:89], v[150:151], v[132:133] op_sel_hi:[0,1,1]
	v_pk_fma_f32 v[10:11], v[88:89], v[38:39], v[10:11] op_sel_hi:[0,1,1]
	v_pk_fma_f32 v[70:71], v[90:91], v[140:141], v[70:71] op_sel_hi:[0,1,1]
	v_pk_fma_f32 v[10:11], v[90:91], v[32:33], v[10:11] op_sel_hi:[0,1,1]
	v_pk_fma_f32 v[70:71], v[96:97], v[34:35], v[70:71] op_sel_hi:[0,1,1]
	v_pk_fma_f32 v[10:11], v[96:97], v[28:29], v[10:11] op_sel_hi:[0,1,1]
	v_pk_fma_f32 v[70:71], v[110:111], v[30:31], v[70:71] op_sel_hi:[0,1,1]
	v_pk_fma_f32 v[10:11], v[110:111], v[24:25], v[10:11] op_sel_hi:[0,1,1]
	v_pk_fma_f32 v[70:71], v[112:113], v[26:27], v[70:71] op_sel_hi:[0,1,1]
	v_pk_fma_f32 v[10:11], v[112:113], v[20:21], v[10:11] op_sel_hi:[0,1,1]
	v_pk_fma_f32 v[70:71], v[114:115], v[22:23], v[70:71] op_sel_hi:[0,1,1]
	v_pk_fma_f32 v[10:11], v[114:115], v[16:17], v[10:11] op_sel_hi:[0,1,1]
	v_pk_fma_f32 v[70:71], v[116:117], v[18:19], v[70:71] op_sel_hi:[0,1,1]
	v_pk_fma_f32 v[10:11], v[116:117], v[12:13], v[10:11] op_sel_hi:[0,1,1]
	v_pk_fma_f32 v[132:133], v[130:131], v[14:15], v[70:71] op_sel_hi:[0,1,1]
	v_lshlrev_b32_e32 v70, 16, v6
	v_and_b32_e32 v71, 0xffff0000, v6
	v_pk_fma_f32 v[88:89], v[130:131], v[8:9], v[10:11] op_sel_hi:[0,1,1]
	v_lshlrev_b32_e32 v10, 16, v7
	v_and_b32_e32 v11, 0xffff0000, v7
	v_pk_fma_f32 v[132:133], v[76:77], v[70:71], v[132:133] op_sel_hi:[0,1,1]
	v_pk_fma_f32 v[76:77], v[76:77], v[10:11], v[88:89] op_sel_hi:[0,1,1]
	v_pk_fma_f32 v[132:133], v[86:87], v[132:133], v[140:141] op_sel_hi:[0,1,1] neg_lo:[0,0,1] neg_hi:[0,0,1]
	v_pk_fma_f32 v[76:77], v[86:87], v[76:77], v[32:33] op_sel_hi:[0,1,1] neg_lo:[0,0,1] neg_hi:[0,0,1]
	v_cvt_pk_bf16_f32 v6, v132, v133
	v_cvt_pk_bf16_f32 v7, v76, v77
	v_lshl_add_u64 v[76:77], v[126:127], 0, s[0:1]
	global_store_dwordx4 v[76:77], v[4:7], off
	s_nop 1
	v_sub_u32_e32 v4, s18, v167
	v_add_u32_e32 v5, s18, v167
	v_max_i32_e32 v7, 0, v4
	v_min_i32_e32 v77, s9, v5
	v_cmp_ge_i32_e32 vcc, s10, v7
	v_cmp_lt_i32_e64 s[0:1], s10, v77
	s_and_b64 s[0:1], vcc, s[0:1]
	v_cmp_ge_i32_e32 vcc, s11, v7
	v_cndmask_b32_e64 v4, 0, 1.0, s[0:1]
	v_cmp_lt_i32_e64 s[0:1], s11, v77
	s_and_b64 s[0:1], vcc, s[0:1]
	v_cmp_ge_i32_e32 vcc, s12, v7
	v_cndmask_b32_e64 v6, 0, 1.0, s[0:1]
	v_cmp_lt_i32_e64 s[0:1], s12, v77
	s_and_b64 s[0:1], vcc, s[0:1]
	v_cmp_ge_i32_e32 vcc, s13, v7
; __device__ __forceinline__ float bf_lo(unsigned w) { return __uint_as_float(w << 16); }
; __device__ __forceinline__ float bf_hi(unsigned w) { return __uint_as_float(w & 0xffff0000u); }
; __device__ __forceinline__ void phase_mixer(const Params& p, LAS unsigned char* lds, int l, bool with_ctx, int G, int tid, int wave, int lane, int rep_attn, int rep_pool) {
;     ...
;         for (int o = 0; o < 16; ++o) {
;             const int t = t0 + o, st = max(t - lo, 0), en = min(t + hi + 1, len);
;             float acc[8];
; #pragma unroll
;             for (int e = 0; e < 8; ++e) acc[e] = 0.f;
; #pragma unroll
;             for (int i = 0; i < 16; ++i) { const int tt = t + i - 8; const float wt = (tt >= st && tt < en) ? 1.f : 0.f; const u32x4 ww = w[o + i];
;                 acc[0] += wt * bf_lo(ww.x); acc[1] += wt * bf_hi(ww.x); acc[2] += wt * bf_lo(ww.y); acc[3] += wt * bf_hi(ww.y);
;                 acc[4] += wt * bf_lo(ww.z); acc[5] += wt * bf_hi(ww.z); acc[6] += wt * bf_lo(ww.w); acc[7] += wt * bf_hi(ww.w); }
;             const float ic = 1.f / (float)(en - st);
	v_cndmask_b32_e64 v76, 0, 1.0, s[0:1]
	v_cmp_lt_i32_e64 s[0:1], s13, v77
	s_and_b64 s[0:1], vcc, s[0:1]
	v_cmp_ge_i32_e32 vcc, s14, v7
	v_cndmask_b32_e64 v86, 0, 1.0, s[0:1]
	v_cmp_lt_i32_e64 s[0:1], s14, v77
	s_and_b64 s[0:1], vcc, s[0:1]
	v_pk_fma_f32 v[84:85], v[4:5], v[84:85], 0 op_sel_hi:[0,1,0]
	v_cndmask_b32_e64 v88, 0, 1.0, s[0:1]
	v_cmp_ge_i32_e32 vcc, s15, v7
	v_cmp_lt_i32_e64 s[0:1], s15, v77
	v_pk_fma_f32 v[60:61], v[6:7], v[60:61], v[84:85] op_sel_hi:[0,1,1]
	s_and_b64 s[0:1], vcc, s[0:1]
	v_pk_fma_f32 v[60:61], v[76:77], v[74:75], v[60:61] op_sel_hi:[0,1,1]
	v_cndmask_b32_e64 v90, 0, 1.0, s[0:1]
	v_cmp_ge_i32_e32 vcc, s17, v7
	v_cmp_lt_i32_e64 s[0:1], s17, v77
	v_pk_fma_f32 v[60:61], v[86:87], v[106:107], v[60:61] op_sel_hi:[0,1,1]
	s_and_b64 s[0:1], vcc, s[0:1]
	v_pk_fma_f32 v[60:61], v[88:89], v[120:121], v[60:61] op_sel_hi:[0,1,1]
	v_cndmask_b32_e64 v96, 0, 1.0, s[0:1]
	v_pk_fma_f32 v[60:61], v[90:91], v[136:137], v[60:61] op_sel_hi:[0,1,1]
	v_pk_fma_f32 v[74:75], v[96:97], v[148:149], v[60:61] op_sel_hi:[0,1,1]
	v_pk_fma_f32 v[60:61], v[4:5], v[64:65], 0 op_sel_hi:[0,1,0]
	v_pk_fma_f32 v[56:57], v[6:7], v[56:57], v[60:61] op_sel_hi:[0,1,1]
	v_pk_fma_f32 v[52:53], v[76:77], v[52:53], v[56:57] op_sel_hi:[0,1,1]
	v_pk_fma_f32 v[48:49], v[86:87], v[48:49], v[52:53] op_sel_hi:[0,1,1]
	v_pk_fma_f32 v[44:45], v[88:89], v[44:45], v[48:49] op_sel_hi:[0,1,1]
	v_pk_fma_f32 v[40:41], v[90:91], v[40:41], v[44:45] op_sel_hi:[0,1,1]
	v_pk_fma_f32 v[60:61], v[96:97], v[36:37], v[40:41] op_sel_hi:[0,1,1]
	v_pk_fma_f32 v[36:37], v[4:5], v[68:69], 0 op_sel_hi:[0,1,0]
	v_pk_fma_f32 v[4:5], v[4:5], v[66:67], 0 op_sel_hi:[0,1,0]
	v_pk_fma_f32 v[36:37], v[6:7], v[62:63], v[36:37] op_sel_hi:[0,1,1]
	v_pk_fma_f32 v[4:5], v[6:7], v[58:59], v[4:5] op_sel_hi:[0,1,1]
	v_pk_fma_f32 v[36:37], v[76:77], v[78:79], v[36:37] op_sel_hi:[0,1,1]
	v_pk_fma_f32 v[4:5], v[76:77], v[54:55], v[4:5] op_sel_hi:[0,1,1]
	v_pk_fma_f32 v[36:37], v[86:87], v[108:109], v[36:37] op_sel_hi:[0,1,1]
	v_pk_fma_f32 v[4:5], v[86:87], v[50:51], v[4:5] op_sel_hi:[0,1,1]
	v_pk_fma_f32 v[36:37], v[88:89], v[122:123], v[36:37] op_sel_hi:[0,1,1]
	v_pk_fma_f32 v[4:5], v[88:89], v[46:47], v[4:5] op_sel_hi:[0,1,1]
	v_cmp_ge_i32_e32 vcc, s16, v7
	v_cmp_lt_i32_e64 s[0:1], s16, v77
	v_pk_fma_f32 v[36:37], v[90:91], v[138:139], v[36:37] op_sel_hi:[0,1,1]
	v_pk_fma_f32 v[4:5], v[90:91], v[42:43], v[4:5] op_sel_hi:[0,1,1]
	s_and_b64 s[0:1], vcc, s[0:1]
	v_pk_fma_f32 v[56:57], v[96:97], v[150:151], v[36:37] op_sel_hi:[0,1,1]
	v_pk_fma_f32 v[36:37], v[96:97], v[38:39], v[4:5] op_sel_hi:[0,1,1]
	v_cndmask_b32_e64 v38, 0, 1.0, s[0:1]
	v_cmp_ge_i32_e32 vcc, s18, v7
	v_cmp_lt_i32_e64 s[0:1], s18, v77
	s_and_b64 s[0:1], vcc, s[0:1]
	v_cmp_ge_i32_e32 vcc, s5, v7
	v_cndmask_b32_e64 v40, 0, 1.0, s[0:1]
	v_cmp_lt_i32_e64 s[0:1], s5, v77
	s_and_b64 s[0:1], vcc, s[0:1]
	v_cmp_ge_i32_e32 vcc, s23, v7
	v_cndmask_b32_e64 v42, 0, 1.0, s[0:1]
	v_cmp_lt_i32_e64 s[0:1], s23, v77
	s_and_b64 s[0:1], vcc, s[0:1]
	v_cmp_ge_i32_e32 vcc, s22, v7
	v_cndmask_b32_e64 v44, 0, 1.0, s[0:1]
	v_cmp_lt_i32_e64 s[0:1], s22, v77
	s_and_b64 s[0:1], vcc, s[0:1]
	v_cmp_ge_i32_e32 vcc, s21, v7
	v_cndmask_b32_e64 v46, 0, 1.0, s[0:1]
	v_cmp_lt_i32_e64 s[0:1], s21, v77
	s_and_b64 s[0:1], vcc, s[0:1]
	v_cmp_ge_i32_e32 vcc, s20, v7
	v_cndmask_b32_e64 v48, 0, 1.0, s[0:1]
	v_cmp_lt_i32_e64 s[0:1], s20, v77
	s_and_b64 s[0:1], vcc, s[0:1]
	v_sub_u32_e32 v5, v77, v7
	v_cndmask_b32_e64 v50, 0, 1.0, s[0:1]
	v_cmp_ge_i32_e32 vcc, s19, v7
	v_cmp_lt_i32_e64 s[0:1], s19, v77
	v_cvt_f32_i32_e32 v5, v5
	s_and_b64 s[0:1], vcc, s[0:1]
	v_cndmask_b32_e64 v52, 0, 1.0, s[0:1]
	v_cmp_ge_i32_e32 vcc, s8, v7
	v_cmp_lt_i32_e64 s[0:1], s8, v77
	s_and_b64 s[0:1], vcc, s[0:1]
	s_waitcnt vmcnt(15)
; __device__ __forceinline__ unsigned cvt_pk_bf16(float lo, float hi) { const f32x2 v = (f32x2){lo, hi}; return __builtin_bit_cast(unsigned, __builtin_convertvector(v, bf16v2)); }
; __device__ __forceinline__ float bf_lo(unsigned w) { return __uint_as_float(w << 16); }
; __device__ __forceinline__ float bf_hi(unsigned w) { return __uint_as_float(w & 0xffff0000u); }
; __device__ __forceinline__ void phase_mixer(const Params& p, LAS unsigned char* lds, int l, bool with_ctx, int G, int tid, int wave, int lane, int rep_attn, int rep_pool) {
;     ...
;     for (int run = gw; run < nrun; run += NGW) {
;     ...
;         for (int o = 0; o < 16; ++o) {
;             const int t = t0 + o, st = max(t - lo, 0), en = min(t + hi + 1, len);
;             float acc[8];
; #pragma unroll
;             for (int e = 0; e < 8; ++e) acc[e] = 0.f;
; #pragma unroll
;             for (int i = 0; i < 16; ++i) { const int tt = t + i - 8; const float wt = (tt >= st && tt < en) ? 1.f : 0.f; const u32x4 ww = w[o + i];
;                 acc[0] += wt * bf_lo(ww.x); acc[1] += wt * bf_hi(ww.x); acc[2] += wt * bf_lo(ww.y); acc[3] += wt * bf_hi(ww.y);
;                 acc[4] += wt * bf_lo(ww.z); acc[5] += wt * bf_hi(ww.z); acc[6] += wt * bf_lo(ww.w); acc[7] += wt * bf_hi(ww.w); }
;             const float ic = 1.f / (float)(en - st);
;             const u32x4 sw = w[o + 8];
;             u32x4 ov; ov.x = cvt_pk_bf16(acc[0] * ic - bf_lo(sw.x), acc[1] * ic - bf_hi(sw.x)); ov.y = cvt_pk_bf16(acc[2] * ic - bf_lo(sw.y), acc[3] * ic - bf_hi(sw.y));
;             ov.z = cvt_pk_bf16(acc[4] * ic - bf_lo(sw.z), acc[5] * ic - bf_hi(sw.z)); ov.w = cvt_pk_bf16(acc[6] * ic - bf_lo(sw.w), acc[7] * ic - bf_hi(sw.w));
;             *(u32x4*)(MIX + (size_t)(tok0 + o) * DM + 8 * lane) = ov;
	v_lshlrev_b32_e32 v58, 16, v0
	v_cndmask_b32_e64 v4, 0, 1.0, s[0:1]
	v_div_scale_f32 v6, s[0:1], v5, v5, 1.0
	v_rcp_f32_e32 v7, v6
	v_and_b32_e32 v59, 0xffff0000, v0
	s_or_b32 s0, s4, 15
	s_ashr_i32 s1, s0, 31
	v_fma_f32 v39, -v6, v7, 1.0
	v_fmac_f32_e32 v7, v39, v7
	v_div_scale_f32 v39, vcc, 1.0, v5, 1.0
	v_mul_f32_e32 v41, v39, v7
	v_fma_f32 v43, -v6, v41, v39
	v_fmac_f32_e32 v41, v43, v7
	v_pk_fma_f32 v[54:55], v[38:39], v[144:145], v[74:75] op_sel_hi:[0,1,1]
	v_pk_fma_f32 v[54:55], v[40:41], v[152:153], v[54:55] op_sel_hi:[0,1,1]
	v_pk_fma_f32 v[54:55], v[42:43], v[128:129], v[54:55] op_sel_hi:[0,1,1]
	v_pk_fma_f32 v[54:55], v[44:45], v[100:101], v[54:55] op_sel_hi:[0,1,1]
	v_pk_fma_f32 v[54:55], v[46:47], v[104:105], v[54:55] op_sel_hi:[0,1,1]
	v_pk_fma_f32 v[54:55], v[48:49], v[94:95], v[54:55] op_sel_hi:[0,1,1]
	v_fma_f32 v6, -v6, v41, v39
	v_pk_fma_f32 v[54:55], v[50:51], v[82:83], v[54:55] op_sel_hi:[0,1,1]
	v_div_fmas_f32 v6, v6, v7, v41
	v_pk_fma_f32 v[54:55], v[52:53], v[134:135], v[54:55] op_sel_hi:[0,1,1]
	v_div_fixup_f32 v6, v6, v5, 1.0
	v_pk_fma_f32 v[54:55], v[4:5], v[58:59], v[54:55] op_sel_hi:[0,1,1]
	v_pk_fma_f32 v[54:55], v[6:7], v[54:55], v[152:153] op_sel_hi:[0,1,1] neg_lo:[0,0,1] neg_hi:[0,0,1]
	v_cvt_pk_bf16_f32 v0, v54, v55
	v_pk_fma_f32 v[54:55], v[38:39], v[142:143], v[60:61] op_sel_hi:[0,1,1]
	v_pk_fma_f32 v[54:55], v[40:41], v[146:147], v[54:55] op_sel_hi:[0,1,1]
	v_pk_fma_f32 v[54:55], v[42:43], v[118:119], v[54:55] op_sel_hi:[0,1,1]
	v_pk_fma_f32 v[54:55], v[44:45], v[98:99], v[54:55] op_sel_hi:[0,1,1]
	v_pk_fma_f32 v[54:55], v[46:47], v[102:103], v[54:55] op_sel_hi:[0,1,1]
	v_pk_fma_f32 v[54:55], v[48:49], v[92:93], v[54:55] op_sel_hi:[0,1,1]
	v_pk_fma_f32 v[54:55], v[50:51], v[80:81], v[54:55] op_sel_hi:[0,1,1]
	v_pk_fma_f32 v[54:55], v[52:53], v[72:73], v[54:55] op_sel_hi:[0,1,1]
	v_lshlrev_b32_e32 v58, 16, v1
	v_and_b32_e32 v59, 0xffff0000, v1
	v_pk_fma_f32 v[54:55], v[4:5], v[58:59], v[54:55] op_sel_hi:[0,1,1]
	v_pk_fma_f32 v[54:55], v[6:7], v[54:55], v[146:147] op_sel_hi:[0,1,1] neg_lo:[0,0,1] neg_hi:[0,0,1]
	v_cvt_pk_bf16_f32 v1, v54, v55
	v_pk_fma_f32 v[54:55], v[38:39], v[140:141], v[56:57] op_sel_hi:[0,1,1]
	v_pk_fma_f32 v[54:55], v[40:41], v[34:35], v[54:55] op_sel_hi:[0,1,1]
	v_pk_fma_f32 v[30:31], v[42:43], v[30:31], v[54:55] op_sel_hi:[0,1,1]
	v_pk_fma_f32 v[26:27], v[44:45], v[26:27], v[30:31] op_sel_hi:[0,1,1]
	v_pk_fma_f32 v[22:23], v[46:47], v[22:23], v[26:27] op_sel_hi:[0,1,1]
	v_pk_fma_f32 v[18:19], v[48:49], v[18:19], v[22:23] op_sel_hi:[0,1,1]
	v_pk_fma_f32 v[14:15], v[50:51], v[14:15], v[18:19] op_sel_hi:[0,1,1]
	v_pk_fma_f32 v[14:15], v[52:53], v[70:71], v[14:15] op_sel_hi:[0,1,1]
	v_lshlrev_b32_e32 v18, 16, v2
	v_and_b32_e32 v19, 0xffff0000, v2
	v_pk_fma_f32 v[14:15], v[4:5], v[18:19], v[14:15] op_sel_hi:[0,1,1]
	v_pk_fma_f32 v[14:15], v[6:7], v[14:15], v[34:35] op_sel_hi:[0,1,1] neg_lo:[0,0,1] neg_hi:[0,0,1]
	v_cvt_pk_bf16_f32 v2, v14, v15
	v_pk_fma_f32 v[14:15], v[38:39], v[32:33], v[36:37] op_sel_hi:[0,1,1]
	v_pk_fma_f32 v[14:15], v[40:41], v[28:29], v[14:15] op_sel_hi:[0,1,1]
	v_pk_fma_f32 v[14:15], v[42:43], v[24:25], v[14:15] op_sel_hi:[0,1,1]
	v_pk_fma_f32 v[14:15], v[44:45], v[20:21], v[14:15] op_sel_hi:[0,1,1]
	v_pk_fma_f32 v[14:15], v[46:47], v[16:17], v[14:15] op_sel_hi:[0,1,1]
	v_pk_fma_f32 v[12:13], v[48:49], v[12:13], v[14:15] op_sel_hi:[0,1,1]
	v_pk_fma_f32 v[8:9], v[50:51], v[8:9], v[12:13] op_sel_hi:[0,1,1]
	v_pk_fma_f32 v[8:9], v[52:53], v[10:11], v[8:9] op_sel_hi:[0,1,1]
	v_lshlrev_b32_e32 v10, 16, v3
	v_and_b32_e32 v11, 0xffff0000, v3
	v_pk_fma_f32 v[4:5], v[4:5], v[10:11], v[8:9] op_sel_hi:[0,1,1]
	v_pk_fma_f32 v[4:5], v[6:7], v[4:5], v[28:29] op_sel_hi:[0,1,1] neg_lo:[0,0,1] neg_hi:[0,0,1]
	s_lshl_b64 s[0:1], s[0:1], 11
	v_cvt_pk_bf16_f32 v3, v4, v5
	v_lshl_add_u64 v[4:5], v[126:127], 0, s[0:1]
	s_cmp_lt_i32 s6, s7
	global_store_dwordx4 v[4:5], v[0:3], off
	s_cbranch_scc1 .LBB0_308
